# hand-written LayerNorm phases: one wave per row with three rows of loads in flight, DPP wave reductions, 16-byte bf16 stores
# speedup vs baseline: 1.0001x; 1.0001x over previous
; __device__ __forceinline__ int otid(int wv0) { int t = (wv0 << 6) | olane(); asm volatile("" : "+v"(t)); return t; }
; __device__ __forceinline__ int obid() { int b = blockIdx.x; asm volatile("" : "+s"(b)); return b; }
; __device__ __forceinline__ int ogrid() { int g = gridDim.x; asm volatile("" : "+s"(g)); return g; }
; __device__ __forceinline__ void ln_phase(const float* in, float* outf, bf16_t* outb, const float* g, const float* b, int wv0) {
;   const int tid_ = otid(wv0); const int lane = tid_ & 63, wv = obid() * 8 + (tid_ >> 6), nwv = ogrid() * 8;
;   f32x4 gg[8], bb[8];
; #pragma unroll
;   for (int i = 0; i < 8; ++i) { gg[i] = ((const f32x4*)g)[i * 64 + lane]; bb[i] = ((const f32x4*)b)[i * 64 + lane]; }
;   f32x4 vn[8];
;   if (wv < NTOK) { const f32x4* ir = (const f32x4*)(in + (size_t)wv * DM);
; #pragma unroll
;     for (int i = 0; i < 8; ++i) vn[i] = ir[i * 64 + lane]; }
;   for (int row = wv; row < NTOK; row += nwv) {
;     f32x4 v[8]; float s = 0.f;
; #pragma unroll
;     for (int i = 0; i < 8; ++i) v[i] = vn[i];
;     if (row + nwv < NTOK) { const f32x4* ir = (const f32x4*)(in + (size_t)(row + nwv) * DM);
; #pragma unroll
;       for (int i = 0; i < 8; ++i) vn[i] = ir[i * 64 + lane]; }
.LBB0_1158:
	s_or_b64 exec, exec, s[2:3]
	s_waitcnt lgkmcnt(0)
	s_barrier
	s_mov_b32 s0, -1
	s_load_dwordx2 s[4:5], s[54:55], 0xd0
	s_lshl_b32 s1, s53, 6
	v_mbcnt_lo_u32_b32 v0, s0, 0
	v_mbcnt_hi_u32_b32 v0, s0, v0
	v_or_b32_e32 v0, s1, v0
	s_mov_b32 s2, s82
	v_ashrrev_i32_e32 v1, 6, v0
	s_mov_b32 s0, s60
	v_lshl_add_u32 v130, s2, 3, v1
	v_cmp_gt_i32_e32 vcc, s61, v130
	s_and_saveexec_b64 s[6:7], vcc
	s_cbranch_execz .LBB0_1163
	s_waitcnt lgkmcnt(0)
	s_load_dwordx4 s[16:19], s[54:55], 0x88
	s_add_u32 s8, s4, 0x8900000
	s_addc_u32 s9, s5, 0
	s_add_u32 s10, s4, 0x4900000
	s_addc_u32 s11, s5, 0
	s_add_u32 s12, s4, 0x27700000
	s_addc_u32 s13, s5, 0
	s_lshl_b32 s0, s66, 13
	s_waitcnt lgkmcnt(0)
	s_add_u32 s16, s16, s0
	s_addc_u32 s17, s17, 0
	s_add_u32 s14, s18, s0
	s_addc_u32 s15, s19, 0
	v_mbcnt_lo_u32_b32 v243, -1, 0
	v_mbcnt_hi_u32_b32 v243, -1, v243
	v_lshlrev_b32_e32 v240, 5, v243
	v_add_u32_e32 v241, 0x1000, v240
	v_lshlrev_b32_e32 v242, 4, v243
	s_lshl_b32 s20, s82, 3
	s_add_u32 s20, s20, s53
	s_lshl_b32 s21, s60, 3
	global_load_dwordx4 v[0:3], v240, s[16:17]
	global_load_dwordx4 v[4:7], v240, s[16:17] offset:16
	global_load_dwordx4 v[8:11], v240, s[16:17] offset:2048
	global_load_dwordx4 v[12:15], v240, s[16:17] offset:2064
	global_load_dwordx4 v[16:19], v241, s[16:17]
	global_load_dwordx4 v[20:23], v241, s[16:17] offset:16
	global_load_dwordx4 v[24:27], v241, s[16:17] offset:2048
	global_load_dwordx4 v[28:31], v241, s[16:17] offset:2064
	global_load_dwordx4 v[32:35], v240, s[14:15]
	global_load_dwordx4 v[36:39], v240, s[14:15] offset:16
	global_load_dwordx4 v[40:43], v240, s[14:15] offset:2048
	global_load_dwordx4 v[44:47], v240, s[14:15] offset:2064
	global_load_dwordx4 v[48:51], v241, s[14:15]
	global_load_dwordx4 v[52:55], v241, s[14:15] offset:16
	global_load_dwordx4 v[56:59], v241, s[14:15] offset:2048
	global_load_dwordx4 v[60:63], v241, s[14:15] offset:2064
	s_mov_b32 s23, s20
	s_min_u32 s23, s23, 0x3fff
	s_lshl_b32 s23, s23, 13
	s_add_u32 s24, s8, s23
	s_addc_u32 s25, s9, 0
	global_load_dwordx4 v[64:67], v240, s[24:25]
	global_load_dwordx4 v[68:71], v240, s[24:25] offset:16
	global_load_dwordx4 v[72:75], v240, s[24:25] offset:2048
	global_load_dwordx4 v[76:79], v240, s[24:25] offset:2064
	global_load_dwordx4 v[80:83], v241, s[24:25]
	global_load_dwordx4 v[84:87], v241, s[24:25] offset:16
	global_load_dwordx4 v[88:91], v241, s[24:25] offset:2048
	global_load_dwordx4 v[92:95], v241, s[24:25] offset:2064
	s_mul_i32 s23, s21, 1
	s_add_u32 s23, s20, s23
	s_min_u32 s23, s23, 0x3fff
	s_lshl_b32 s23, s23, 13
	s_add_u32 s24, s8, s23
	s_addc_u32 s25, s9, 0
	global_load_dwordx4 v[96:99], v240, s[24:25]
	global_load_dwordx4 v[100:103], v240, s[24:25] offset:16
	global_load_dwordx4 v[104:107], v240, s[24:25] offset:2048
	global_load_dwordx4 v[108:111], v240, s[24:25] offset:2064
	global_load_dwordx4 v[112:115], v241, s[24:25]
	global_load_dwordx4 v[116:119], v241, s[24:25] offset:16
	global_load_dwordx4 v[120:123], v241, s[24:25] offset:2048
	global_load_dwordx4 v[124:127], v241, s[24:25] offset:2064
	s_mul_i32 s23, s21, 2
	s_add_u32 s23, s20, s23
	s_min_u32 s23, s23, 0x3fff
	s_lshl_b32 s23, s23, 13
	s_add_u32 s24, s8, s23
	s_addc_u32 s25, s9, 0
	global_load_dwordx4 v[128:131], v240, s[24:25]
	global_load_dwordx4 v[132:135], v240, s[24:25] offset:16
	global_load_dwordx4 v[136:139], v240, s[24:25] offset:2048
	global_load_dwordx4 v[140:143], v240, s[24:25] offset:2064
	global_load_dwordx4 v[144:147], v241, s[24:25]
	global_load_dwordx4 v[148:151], v241, s[24:25] offset:16
	global_load_dwordx4 v[152:155], v241, s[24:25] offset:2048
	global_load_dwordx4 v[156:159], v241, s[24:25] offset:2064
	s_mul_i32 s23, s21, 3
	s_add_u32 s23, s20, s23
	s_min_u32 s23, s23, 0x3fff
	s_lshl_b32 s23, s23, 13
	s_add_u32 s24, s8, s23
	s_addc_u32 s25, s9, 0
	global_load_dwordx4 v[176:179], v240, s[24:25]
	global_load_dwordx4 v[180:183], v240, s[24:25] offset:16
	global_load_dwordx4 v[184:187], v240, s[24:25] offset:2048
	global_load_dwordx4 v[188:191], v240, s[24:25] offset:2064
	global_load_dwordx4 v[192:195], v241, s[24:25]
	global_load_dwordx4 v[196:199], v241, s[24:25] offset:16
	global_load_dwordx4 v[200:203], v241, s[24:25] offset:2048
	global_load_dwordx4 v[204:207], v241, s[24:25] offset:2064
	s_waitcnt vmcnt(24)
; __device__ __forceinline__ void ln_phase(const float* in, float* outf, bf16_t* outb, const float* g, const float* b, int wv0) {
;     ...
; #pragma unroll
;     for (int i = 0; i < 8; ++i) s += v[i][0] + v[i][1] + v[i][2] + v[i][3];
;     s = wave_sum(s); const float mu = s * (1.0f / 2048.0f);
;     float sq = 0.f;
; #pragma unroll
;     for (int i = 0; i < 8; ++i) { v[i] -= mu; sq += v[i][0] * v[i][0] + v[i][1] * v[i][1] + v[i][2] * v[i][2] + v[i][3] * v[i][3]; }
;     sq = wave_sum(sq); const float rstd = __builtin_amdgcn_rsqf(sq * (1.0f / 2048.0f) + EPS);
; #pragma unroll
;     for (int i = 0; i < 8; ++i) {
;       const f32x4 y = v[i] * rstd * gg[i] + bb[i];
;       ((f32x4*)(outf + (size_t)row * DM))[i * 64 + lane] = y;
;       if (outb) { u32x2 w; w.x = pk2(y[0], y[1]); w.y = pk2(y[2], y[3]); ((u32x2*)(outb + (size_t)row * DM))[i * 64 + lane] = w; } }
	v_pk_add_f32 v[236:237], v[64:65], v[66:67]
	v_pk_add_f32 v[236:237], v[236:237], v[68:69]
	v_pk_add_f32 v[236:237], v[236:237], v[70:71]
	v_pk_add_f32 v[236:237], v[236:237], v[72:73]
	v_pk_add_f32 v[236:237], v[236:237], v[74:75]
	v_pk_add_f32 v[236:237], v[236:237], v[76:77]
	v_pk_add_f32 v[236:237], v[236:237], v[78:79]
	v_pk_add_f32 v[236:237], v[236:237], v[80:81]
	v_pk_add_f32 v[236:237], v[236:237], v[82:83]
	v_pk_add_f32 v[236:237], v[236:237], v[84:85]
	v_pk_add_f32 v[236:237], v[236:237], v[86:87]
	v_pk_add_f32 v[236:237], v[236:237], v[88:89]
	v_pk_add_f32 v[236:237], v[236:237], v[90:91]
	v_pk_add_f32 v[236:237], v[236:237], v[92:93]
	v_pk_add_f32 v[236:237], v[236:237], v[94:95]
	v_add_f32_e32 v234, v236, v237
	s_nop 1
	v_add_f32_dpp v234, v234, v234 quad_perm:[1,0,3,2] row_mask:0xf bank_mask:0xf
	s_nop 1
	v_add_f32_dpp v234, v234, v234 quad_perm:[2,3,0,1] row_mask:0xf bank_mask:0xf
	s_nop 1
	v_add_f32_dpp v234, v234, v234 row_half_mirror row_mask:0xf bank_mask:0xf
	s_nop 1
	v_add_f32_dpp v234, v234, v234 row_mirror row_mask:0xf bank_mask:0xf
	s_nop 0
	v_readlane_b32 s26, v234, 0
	v_readlane_b32 s27, v234, 16
	v_readlane_b32 s28, v234, 32
	v_readlane_b32 s29, v234, 48
	v_mov_b32_e32 v234, s26
	v_add_f32_e32 v234, s27, v234
	v_add_f32_e32 v234, s28, v234
	v_add_f32_e32 v234, s29, v234
	v_mul_f32_e32 v216, 0xba000000, v234
	v_pk_add_f32 v[64:65], v[64:65], v[216:217] op_sel_hi:[1,0]
	v_pk_add_f32 v[66:67], v[66:67], v[216:217] op_sel_hi:[1,0]
	v_pk_add_f32 v[68:69], v[68:69], v[216:217] op_sel_hi:[1,0]
	v_pk_add_f32 v[70:71], v[70:71], v[216:217] op_sel_hi:[1,0]
	v_pk_add_f32 v[72:73], v[72:73], v[216:217] op_sel_hi:[1,0]
	v_pk_add_f32 v[74:75], v[74:75], v[216:217] op_sel_hi:[1,0]
	v_pk_add_f32 v[76:77], v[76:77], v[216:217] op_sel_hi:[1,0]
	v_pk_add_f32 v[78:79], v[78:79], v[216:217] op_sel_hi:[1,0]
	v_pk_add_f32 v[80:81], v[80:81], v[216:217] op_sel_hi:[1,0]
	v_pk_add_f32 v[82:83], v[82:83], v[216:217] op_sel_hi:[1,0]
	v_pk_add_f32 v[84:85], v[84:85], v[216:217] op_sel_hi:[1,0]
	v_pk_add_f32 v[86:87], v[86:87], v[216:217] op_sel_hi:[1,0]
	v_pk_add_f32 v[88:89], v[88:89], v[216:217] op_sel_hi:[1,0]
	v_pk_add_f32 v[90:91], v[90:91], v[216:217] op_sel_hi:[1,0]
	v_pk_add_f32 v[92:93], v[92:93], v[216:217] op_sel_hi:[1,0]
	v_pk_add_f32 v[94:95], v[94:95], v[216:217] op_sel_hi:[1,0]
	v_pk_mul_f32 v[236:237], v[64:65], v[64:65]
	v_pk_fma_f32 v[236:237], v[66:67], v[66:67], v[236:237]
	v_pk_fma_f32 v[236:237], v[68:69], v[68:69], v[236:237]
	v_pk_fma_f32 v[236:237], v[70:71], v[70:71], v[236:237]
	v_pk_fma_f32 v[236:237], v[72:73], v[72:73], v[236:237]
	v_pk_fma_f32 v[236:237], v[74:75], v[74:75], v[236:237]
	v_pk_fma_f32 v[236:237], v[76:77], v[76:77], v[236:237]
	v_pk_fma_f32 v[236:237], v[78:79], v[78:79], v[236:237]
	v_pk_fma_f32 v[236:237], v[80:81], v[80:81], v[236:237]
	v_pk_fma_f32 v[236:237], v[82:83], v[82:83], v[236:237]
	v_pk_fma_f32 v[236:237], v[84:85], v[84:85], v[236:237]
	v_pk_fma_f32 v[236:237], v[86:87], v[86:87], v[236:237]
	v_pk_fma_f32 v[236:237], v[88:89], v[88:89], v[236:237]
	v_pk_fma_f32 v[236:237], v[90:91], v[90:91], v[236:237]
	v_pk_fma_f32 v[236:237], v[92:93], v[92:93], v[236:237]
	v_pk_fma_f32 v[236:237], v[94:95], v[94:95], v[236:237]
	v_add_f32_e32 v235, v236, v237
	s_nop 1
	v_add_f32_dpp v235, v235, v235 quad_perm:[1,0,3,2] row_mask:0xf bank_mask:0xf
	s_nop 1
	v_add_f32_dpp v235, v235, v235 quad_perm:[2,3,0,1] row_mask:0xf bank_mask:0xf
	s_nop 1
	v_add_f32_dpp v235, v235, v235 row_half_mirror row_mask:0xf bank_mask:0xf
	s_nop 1
	v_add_f32_dpp v235, v235, v235 row_mirror row_mask:0xf bank_mask:0xf
	s_nop 0
	v_readlane_b32 s26, v235, 0
	v_readlane_b32 s27, v235, 16
	v_readlane_b32 s28, v235, 32
	v_readlane_b32 s29, v235, 48
	v_mov_b32_e32 v235, s26
	v_add_f32_e32 v235, s27, v235
	v_add_f32_e32 v235, s28, v235
	v_add_f32_e32 v235, s29, v235
	v_fmamk_f32 v235, v235, 0x3a000000, v246
	v_rsq_f32_e32 v217, v235
	s_lshl_b32 s23, s20, 13
	s_lshr_b32 s23, s23, 1
	s_add_u32 s30, s10, s23
	s_addc_u32 s31, s11, 0
	s_lshl_b32 s23, s20, 3
	s_add_u32 s2, s12, s23
	s_addc_u32 s3, s13, 0
	v_mov_b32_e32 v243, 0
	s_mov_b64 exec, 1
	global_store_dwordx2 v243, v[216:217], s[2:3]
	s_mov_b64 exec, -1
	v_pk_mul_f32 v[64:65], v[64:65], v[216:217] op_sel:[0,1] op_sel_hi:[1,1]
	v_pk_mul_f32 v[66:67], v[66:67], v[216:217] op_sel:[0,1] op_sel_hi:[1,1]
	v_pk_fma_f32 v[64:65], v[0:1], v[64:65], v[32:33]
	v_pk_fma_f32 v[66:67], v[2:3], v[66:67], v[34:35]
	v_pk_mul_f32 v[68:69], v[68:69], v[216:217] op_sel:[0,1] op_sel_hi:[1,1]
	v_pk_mul_f32 v[70:71], v[70:71], v[216:217] op_sel:[0,1] op_sel_hi:[1,1]
	v_pk_fma_f32 v[68:69], v[4:5], v[68:69], v[36:37]
	v_pk_fma_f32 v[70:71], v[6:7], v[70:71], v[38:39]
	v_cvt_pk_bf16_f32 v208, v64, v65
	v_cvt_pk_bf16_f32 v209, v66, v67
	v_cvt_pk_bf16_f32 v210, v68, v69
	v_cvt_pk_bf16_f32 v211, v70, v71
	global_store_dwordx4 v242, v[208:211], s[30:31]
	v_pk_mul_f32 v[72:73], v[72:73], v[216:217] op_sel:[0,1] op_sel_hi:[1,1]
	v_pk_mul_f32 v[74:75], v[74:75], v[216:217] op_sel:[0,1] op_sel_hi:[1,1]
	v_pk_fma_f32 v[72:73], v[8:9], v[72:73], v[40:41]
	v_pk_fma_f32 v[74:75], v[10:11], v[74:75], v[42:43]
	v_pk_mul_f32 v[76:77], v[76:77], v[216:217] op_sel:[0,1] op_sel_hi:[1,1]
	v_pk_mul_f32 v[78:79], v[78:79], v[216:217] op_sel:[0,1] op_sel_hi:[1,1]
	v_pk_fma_f32 v[76:77], v[12:13], v[76:77], v[44:45]
	v_pk_fma_f32 v[78:79], v[14:15], v[78:79], v[46:47]
	v_cvt_pk_bf16_f32 v212, v72, v73
	v_cvt_pk_bf16_f32 v213, v74, v75
	v_cvt_pk_bf16_f32 v214, v76, v77
	v_cvt_pk_bf16_f32 v215, v78, v79
	global_store_dwordx4 v242, v[212:215], s[30:31] offset:1024
	v_pk_mul_f32 v[80:81], v[80:81], v[216:217] op_sel:[0,1] op_sel_hi:[1,1]
; __device__ __forceinline__ void ln_phase(const float* in, float* outf, bf16_t* outb, const float* g, const float* b, int wv0) {
;     ...
;   for (int row = wv; row < NTOK; row += nwv) {
;     f32x4 v[8]; float s = 0.f;
; #pragma unroll
;     for (int i = 0; i < 8; ++i) v[i] = vn[i];
;     if (row + nwv < NTOK) { const f32x4* ir = (const f32x4*)(in + (size_t)(row + nwv) * DM);
; #pragma unroll
;       for (int i = 0; i < 8; ++i) vn[i] = ir[i * 64 + lane]; }
; #pragma unroll
;     for (int i = 0; i < 8; ++i) s += v[i][0] + v[i][1] + v[i][2] + v[i][3];
;     s = wave_sum(s); const float mu = s * (1.0f / 2048.0f);
;     float sq = 0.f;
; #pragma unroll
;     for (int i = 0; i < 8; ++i) { v[i] -= mu; sq += v[i][0] * v[i][0] + v[i][1] * v[i][1] + v[i][2] * v[i][2] + v[i][3] * v[i][3]; }
;     sq = wave_sum(sq); const float rstd = __builtin_amdgcn_rsqf(sq * (1.0f / 2048.0f) + EPS);
; #pragma unroll
;     for (int i = 0; i < 8; ++i) {
;       const f32x4 y = v[i] * rstd * gg[i] + bb[i];
	v_pk_mul_f32 v[82:83], v[82:83], v[216:217] op_sel:[0,1] op_sel_hi:[1,1]
	v_pk_fma_f32 v[80:81], v[16:17], v[80:81], v[48:49]
	v_pk_fma_f32 v[82:83], v[18:19], v[82:83], v[50:51]
	v_pk_mul_f32 v[84:85], v[84:85], v[216:217] op_sel:[0,1] op_sel_hi:[1,1]
	v_pk_mul_f32 v[86:87], v[86:87], v[216:217] op_sel:[0,1] op_sel_hi:[1,1]
	v_pk_fma_f32 v[84:85], v[20:21], v[84:85], v[52:53]
	v_pk_fma_f32 v[86:87], v[22:23], v[86:87], v[54:55]
	v_cvt_pk_bf16_f32 v208, v80, v81
	v_cvt_pk_bf16_f32 v209, v82, v83
	v_cvt_pk_bf16_f32 v210, v84, v85
	v_cvt_pk_bf16_f32 v211, v86, v87
	global_store_dwordx4 v242, v[208:211], s[30:31] offset:2048
	v_pk_mul_f32 v[88:89], v[88:89], v[216:217] op_sel:[0,1] op_sel_hi:[1,1]
	v_pk_mul_f32 v[90:91], v[90:91], v[216:217] op_sel:[0,1] op_sel_hi:[1,1]
	v_pk_fma_f32 v[88:89], v[24:25], v[88:89], v[56:57]
	v_pk_fma_f32 v[90:91], v[26:27], v[90:91], v[58:59]
	v_pk_mul_f32 v[92:93], v[92:93], v[216:217] op_sel:[0,1] op_sel_hi:[1,1]
	v_pk_mul_f32 v[94:95], v[94:95], v[216:217] op_sel:[0,1] op_sel_hi:[1,1]
	v_pk_fma_f32 v[92:93], v[28:29], v[92:93], v[60:61]
	v_pk_fma_f32 v[94:95], v[30:31], v[94:95], v[62:63]
	v_cvt_pk_bf16_f32 v212, v88, v89
	v_cvt_pk_bf16_f32 v213, v90, v91
	v_cvt_pk_bf16_f32 v214, v92, v93
	v_cvt_pk_bf16_f32 v215, v94, v95
	global_store_dwordx4 v242, v[212:215], s[30:31] offset:3072
	s_add_u32 s20, s20, s21
	s_cmp_ge_u32 s20, 0x4000
	s_cbranch_scc1 .Lln1_done
	s_mul_i32 s23, s21, 3
	s_add_u32 s23, s20, s23
	s_min_u32 s23, s23, 0x3fff
	s_lshl_b32 s23, s23, 13
	s_add_u32 s24, s8, s23
	s_addc_u32 s25, s9, 0
	global_load_dwordx4 v[64:67], v240, s[24:25]
	global_load_dwordx4 v[68:71], v240, s[24:25] offset:16
	global_load_dwordx4 v[72:75], v240, s[24:25] offset:2048
	global_load_dwordx4 v[76:79], v240, s[24:25] offset:2064
	global_load_dwordx4 v[80:83], v241, s[24:25]
	global_load_dwordx4 v[84:87], v241, s[24:25] offset:16
	global_load_dwordx4 v[88:91], v241, s[24:25] offset:2048
	global_load_dwordx4 v[92:95], v241, s[24:25] offset:2064
	s_waitcnt vmcnt(29)
	v_pk_add_f32 v[236:237], v[96:97], v[98:99]
	v_pk_add_f32 v[236:237], v[236:237], v[100:101]
	v_pk_add_f32 v[236:237], v[236:237], v[102:103]
	v_pk_add_f32 v[236:237], v[236:237], v[104:105]
	v_pk_add_f32 v[236:237], v[236:237], v[106:107]
	v_pk_add_f32 v[236:237], v[236:237], v[108:109]
	v_pk_add_f32 v[236:237], v[236:237], v[110:111]
	v_pk_add_f32 v[236:237], v[236:237], v[112:113]
	v_pk_add_f32 v[236:237], v[236:237], v[114:115]
	v_pk_add_f32 v[236:237], v[236:237], v[116:117]
	v_pk_add_f32 v[236:237], v[236:237], v[118:119]
	v_pk_add_f32 v[236:237], v[236:237], v[120:121]
	v_pk_add_f32 v[236:237], v[236:237], v[122:123]
	v_pk_add_f32 v[236:237], v[236:237], v[124:125]
	v_pk_add_f32 v[236:237], v[236:237], v[126:127]
	v_add_f32_e32 v234, v236, v237
	s_nop 1
	v_add_f32_dpp v234, v234, v234 quad_perm:[1,0,3,2] row_mask:0xf bank_mask:0xf
	s_nop 1
	v_add_f32_dpp v234, v234, v234 quad_perm:[2,3,0,1] row_mask:0xf bank_mask:0xf
	s_nop 1
	v_add_f32_dpp v234, v234, v234 row_half_mirror row_mask:0xf bank_mask:0xf
	s_nop 1
	v_add_f32_dpp v234, v234, v234 row_mirror row_mask:0xf bank_mask:0xf
	s_nop 0
	v_readlane_b32 s26, v234, 0
	v_readlane_b32 s27, v234, 16
	v_readlane_b32 s28, v234, 32
	v_readlane_b32 s29, v234, 48
	v_mov_b32_e32 v234, s26
	v_add_f32_e32 v234, s27, v234
	v_add_f32_e32 v234, s28, v234
	v_add_f32_e32 v234, s29, v234
	v_mul_f32_e32 v216, 0xba000000, v234
	v_pk_add_f32 v[96:97], v[96:97], v[216:217] op_sel_hi:[1,0]
	v_pk_add_f32 v[98:99], v[98:99], v[216:217] op_sel_hi:[1,0]
	v_pk_add_f32 v[100:101], v[100:101], v[216:217] op_sel_hi:[1,0]
	v_pk_add_f32 v[102:103], v[102:103], v[216:217] op_sel_hi:[1,0]
	v_pk_add_f32 v[104:105], v[104:105], v[216:217] op_sel_hi:[1,0]
	v_pk_add_f32 v[106:107], v[106:107], v[216:217] op_sel_hi:[1,0]
	v_pk_add_f32 v[108:109], v[108:109], v[216:217] op_sel_hi:[1,0]
	v_pk_add_f32 v[110:111], v[110:111], v[216:217] op_sel_hi:[1,0]
	v_pk_add_f32 v[112:113], v[112:113], v[216:217] op_sel_hi:[1,0]
	v_pk_add_f32 v[114:115], v[114:115], v[216:217] op_sel_hi:[1,0]
	v_pk_add_f32 v[116:117], v[116:117], v[216:217] op_sel_hi:[1,0]
	v_pk_add_f32 v[118:119], v[118:119], v[216:217] op_sel_hi:[1,0]
	v_pk_add_f32 v[120:121], v[120:121], v[216:217] op_sel_hi:[1,0]
	v_pk_add_f32 v[122:123], v[122:123], v[216:217] op_sel_hi:[1,0]
	v_pk_add_f32 v[124:125], v[124:125], v[216:217] op_sel_hi:[1,0]
	v_pk_add_f32 v[126:127], v[126:127], v[216:217] op_sel_hi:[1,0]
	v_pk_mul_f32 v[236:237], v[96:97], v[96:97]
	v_pk_fma_f32 v[236:237], v[98:99], v[98:99], v[236:237]
	v_pk_fma_f32 v[236:237], v[100:101], v[100:101], v[236:237]
	v_pk_fma_f32 v[236:237], v[102:103], v[102:103], v[236:237]
	v_pk_fma_f32 v[236:237], v[104:105], v[104:105], v[236:237]
	v_pk_fma_f32 v[236:237], v[106:107], v[106:107], v[236:237]
	v_pk_fma_f32 v[236:237], v[108:109], v[108:109], v[236:237]
	v_pk_fma_f32 v[236:237], v[110:111], v[110:111], v[236:237]
	v_pk_fma_f32 v[236:237], v[112:113], v[112:113], v[236:237]
	v_pk_fma_f32 v[236:237], v[114:115], v[114:115], v[236:237]
	v_pk_fma_f32 v[236:237], v[116:117], v[116:117], v[236:237]
	v_pk_fma_f32 v[236:237], v[118:119], v[118:119], v[236:237]
	v_pk_fma_f32 v[236:237], v[120:121], v[120:121], v[236:237]
	v_pk_fma_f32 v[236:237], v[122:123], v[122:123], v[236:237]
	v_pk_fma_f32 v[236:237], v[124:125], v[124:125], v[236:237]
	v_pk_fma_f32 v[236:237], v[126:127], v[126:127], v[236:237]
	v_add_f32_e32 v235, v236, v237
	s_nop 1
	v_add_f32_dpp v235, v235, v235 quad_perm:[1,0,3,2] row_mask:0xf bank_mask:0xf
	s_nop 1
	v_add_f32_dpp v235, v235, v235 quad_perm:[2,3,0,1] row_mask:0xf bank_mask:0xf
	s_nop 1
; __device__ __forceinline__ void ln_phase(const float* in, float* outf, bf16_t* outb, const float* g, const float* b, int wv0) {
;     ...
;     s = wave_sum(s); const float mu = s * (1.0f / 2048.0f);
;     float sq = 0.f;
; #pragma unroll
;     for (int i = 0; i < 8; ++i) { v[i] -= mu; sq += v[i][0] * v[i][0] + v[i][1] * v[i][1] + v[i][2] * v[i][2] + v[i][3] * v[i][3]; }
;     sq = wave_sum(sq); const float rstd = __builtin_amdgcn_rsqf(sq * (1.0f / 2048.0f) + EPS);
; #pragma unroll
;     for (int i = 0; i < 8; ++i) {
;       const f32x4 y = v[i] * rstd * gg[i] + bb[i];
;       ((f32x4*)(outf + (size_t)row * DM))[i * 64 + lane] = y;
;       if (outb) { u32x2 w; w.x = pk2(y[0], y[1]); w.y = pk2(y[2], y[3]); ((u32x2*)(outb + (size_t)row * DM))[i * 64 + lane] = w; } }
;   }
	v_add_f32_dpp v235, v235, v235 row_half_mirror row_mask:0xf bank_mask:0xf
	s_nop 1
	v_add_f32_dpp v235, v235, v235 row_mirror row_mask:0xf bank_mask:0xf
	s_nop 0
	v_readlane_b32 s26, v235, 0
	v_readlane_b32 s27, v235, 16
	v_readlane_b32 s28, v235, 32
	v_readlane_b32 s29, v235, 48
	v_mov_b32_e32 v235, s26
	v_add_f32_e32 v235, s27, v235
	v_add_f32_e32 v235, s28, v235
	v_add_f32_e32 v235, s29, v235
	v_fmamk_f32 v235, v235, 0x3a000000, v246
	v_rsq_f32_e32 v217, v235
	s_lshl_b32 s23, s20, 13
	s_lshr_b32 s23, s23, 1
	s_add_u32 s30, s10, s23
	s_addc_u32 s31, s11, 0
	s_lshl_b32 s23, s20, 3
	s_add_u32 s2, s12, s23
	s_addc_u32 s3, s13, 0
	v_mov_b32_e32 v243, 0
	s_mov_b64 exec, 1
	global_store_dwordx2 v243, v[216:217], s[2:3]
	s_mov_b64 exec, -1
	v_pk_mul_f32 v[96:97], v[96:97], v[216:217] op_sel:[0,1] op_sel_hi:[1,1]
	v_pk_mul_f32 v[98:99], v[98:99], v[216:217] op_sel:[0,1] op_sel_hi:[1,1]
	v_pk_fma_f32 v[96:97], v[0:1], v[96:97], v[32:33]
	v_pk_fma_f32 v[98:99], v[2:3], v[98:99], v[34:35]
	v_pk_mul_f32 v[100:101], v[100:101], v[216:217] op_sel:[0,1] op_sel_hi:[1,1]
	v_pk_mul_f32 v[102:103], v[102:103], v[216:217] op_sel:[0,1] op_sel_hi:[1,1]
	v_pk_fma_f32 v[100:101], v[4:5], v[100:101], v[36:37]
	v_pk_fma_f32 v[102:103], v[6:7], v[102:103], v[38:39]
	v_cvt_pk_bf16_f32 v208, v96, v97
	v_cvt_pk_bf16_f32 v209, v98, v99
	v_cvt_pk_bf16_f32 v210, v100, v101
	v_cvt_pk_bf16_f32 v211, v102, v103
	global_store_dwordx4 v242, v[208:211], s[30:31]
	v_pk_mul_f32 v[104:105], v[104:105], v[216:217] op_sel:[0,1] op_sel_hi:[1,1]
	v_pk_mul_f32 v[106:107], v[106:107], v[216:217] op_sel:[0,1] op_sel_hi:[1,1]
	v_pk_fma_f32 v[104:105], v[8:9], v[104:105], v[40:41]
	v_pk_fma_f32 v[106:107], v[10:11], v[106:107], v[42:43]
	v_pk_mul_f32 v[108:109], v[108:109], v[216:217] op_sel:[0,1] op_sel_hi:[1,1]
	v_pk_mul_f32 v[110:111], v[110:111], v[216:217] op_sel:[0,1] op_sel_hi:[1,1]
	v_pk_fma_f32 v[108:109], v[12:13], v[108:109], v[44:45]
	v_pk_fma_f32 v[110:111], v[14:15], v[110:111], v[46:47]
	v_cvt_pk_bf16_f32 v212, v104, v105
	v_cvt_pk_bf16_f32 v213, v106, v107
	v_cvt_pk_bf16_f32 v214, v108, v109
	v_cvt_pk_bf16_f32 v215, v110, v111
	global_store_dwordx4 v242, v[212:215], s[30:31] offset:1024
	v_pk_mul_f32 v[112:113], v[112:113], v[216:217] op_sel:[0,1] op_sel_hi:[1,1]
	v_pk_mul_f32 v[114:115], v[114:115], v[216:217] op_sel:[0,1] op_sel_hi:[1,1]
	v_pk_fma_f32 v[112:113], v[16:17], v[112:113], v[48:49]
	v_pk_fma_f32 v[114:115], v[18:19], v[114:115], v[50:51]
	v_pk_mul_f32 v[116:117], v[116:117], v[216:217] op_sel:[0,1] op_sel_hi:[1,1]
	v_pk_mul_f32 v[118:119], v[118:119], v[216:217] op_sel:[0,1] op_sel_hi:[1,1]
	v_pk_fma_f32 v[116:117], v[20:21], v[116:117], v[52:53]
	v_pk_fma_f32 v[118:119], v[22:23], v[118:119], v[54:55]
	v_cvt_pk_bf16_f32 v208, v112, v113
	v_cvt_pk_bf16_f32 v209, v114, v115
	v_cvt_pk_bf16_f32 v210, v116, v117
	v_cvt_pk_bf16_f32 v211, v118, v119
	global_store_dwordx4 v242, v[208:211], s[30:31] offset:2048
	v_pk_mul_f32 v[120:121], v[120:121], v[216:217] op_sel:[0,1] op_sel_hi:[1,1]
	v_pk_mul_f32 v[122:123], v[122:123], v[216:217] op_sel:[0,1] op_sel_hi:[1,1]
	v_pk_fma_f32 v[120:121], v[24:25], v[120:121], v[56:57]
	v_pk_fma_f32 v[122:123], v[26:27], v[122:123], v[58:59]
	v_pk_mul_f32 v[124:125], v[124:125], v[216:217] op_sel:[0,1] op_sel_hi:[1,1]
	v_pk_mul_f32 v[126:127], v[126:127], v[216:217] op_sel:[0,1] op_sel_hi:[1,1]
	v_pk_fma_f32 v[124:125], v[28:29], v[124:125], v[60:61]
	v_pk_fma_f32 v[126:127], v[30:31], v[126:127], v[62:63]
	v_cvt_pk_bf16_f32 v212, v120, v121
	v_cvt_pk_bf16_f32 v213, v122, v123
	v_cvt_pk_bf16_f32 v214, v124, v125
	v_cvt_pk_bf16_f32 v215, v126, v127
	global_store_dwordx4 v242, v[212:215], s[30:31] offset:3072
	s_add_u32 s20, s20, s21
	s_cmp_ge_u32 s20, 0x4000
	s_cbranch_scc1 .Lln1_done
	s_mul_i32 s23, s21, 3
	s_add_u32 s23, s20, s23
	s_min_u32 s23, s23, 0x3fff
	s_lshl_b32 s23, s23, 13
	s_add_u32 s24, s8, s23
	s_addc_u32 s25, s9, 0
	global_load_dwordx4 v[96:99], v240, s[24:25]
	global_load_dwordx4 v[100:103], v240, s[24:25] offset:16
	global_load_dwordx4 v[104:107], v240, s[24:25] offset:2048
	global_load_dwordx4 v[108:111], v240, s[24:25] offset:2064
	global_load_dwordx4 v[112:115], v241, s[24:25]
	global_load_dwordx4 v[116:119], v241, s[24:25] offset:16
	global_load_dwordx4 v[120:123], v241, s[24:25] offset:2048
	global_load_dwordx4 v[124:127], v241, s[24:25] offset:2064
	s_waitcnt vmcnt(34)
; __device__ __forceinline__ void ln_phase(const float* in, float* outf, bf16_t* outb, const float* g, const float* b, int wv0) {
;     ...
; #pragma unroll
;     for (int i = 0; i < 8; ++i) s += v[i][0] + v[i][1] + v[i][2] + v[i][3];
;     s = wave_sum(s); const float mu = s * (1.0f / 2048.0f);
;     float sq = 0.f;
; #pragma unroll
;     for (int i = 0; i < 8; ++i) { v[i] -= mu; sq += v[i][0] * v[i][0] + v[i][1] * v[i][1] + v[i][2] * v[i][2] + v[i][3] * v[i][3]; }
;     sq = wave_sum(sq); const float rstd = __builtin_amdgcn_rsqf(sq * (1.0f / 2048.0f) + EPS);
; #pragma unroll
;     for (int i = 0; i < 8; ++i) {
;       const f32x4 y = v[i] * rstd * gg[i] + bb[i];
;       ((f32x4*)(outf + (size_t)row * DM))[i * 64 + lane] = y;
;       if (outb) { u32x2 w; w.x = pk2(y[0], y[1]); w.y = pk2(y[2], y[3]); ((u32x2*)(outb + (size_t)row * DM))[i * 64 + lane] = w; } }
	v_pk_add_f32 v[236:237], v[128:129], v[130:131]
	v_pk_add_f32 v[236:237], v[236:237], v[132:133]
	v_pk_add_f32 v[236:237], v[236:237], v[134:135]
	v_pk_add_f32 v[236:237], v[236:237], v[136:137]
	v_pk_add_f32 v[236:237], v[236:237], v[138:139]
	v_pk_add_f32 v[236:237], v[236:237], v[140:141]
	v_pk_add_f32 v[236:237], v[236:237], v[142:143]
	v_pk_add_f32 v[236:237], v[236:237], v[144:145]
	v_pk_add_f32 v[236:237], v[236:237], v[146:147]
	v_pk_add_f32 v[236:237], v[236:237], v[148:149]
	v_pk_add_f32 v[236:237], v[236:237], v[150:151]
	v_pk_add_f32 v[236:237], v[236:237], v[152:153]
	v_pk_add_f32 v[236:237], v[236:237], v[154:155]
	v_pk_add_f32 v[236:237], v[236:237], v[156:157]
	v_pk_add_f32 v[236:237], v[236:237], v[158:159]
	v_add_f32_e32 v234, v236, v237
	s_nop 1
	v_add_f32_dpp v234, v234, v234 quad_perm:[1,0,3,2] row_mask:0xf bank_mask:0xf
	s_nop 1
	v_add_f32_dpp v234, v234, v234 quad_perm:[2,3,0,1] row_mask:0xf bank_mask:0xf
	s_nop 1
	v_add_f32_dpp v234, v234, v234 row_half_mirror row_mask:0xf bank_mask:0xf
	s_nop 1
	v_add_f32_dpp v234, v234, v234 row_mirror row_mask:0xf bank_mask:0xf
	s_nop 0
	v_readlane_b32 s26, v234, 0
	v_readlane_b32 s27, v234, 16
	v_readlane_b32 s28, v234, 32
	v_readlane_b32 s29, v234, 48
	v_mov_b32_e32 v234, s26
	v_add_f32_e32 v234, s27, v234
	v_add_f32_e32 v234, s28, v234
	v_add_f32_e32 v234, s29, v234
	v_mul_f32_e32 v216, 0xba000000, v234
	v_pk_add_f32 v[128:129], v[128:129], v[216:217] op_sel_hi:[1,0]
	v_pk_add_f32 v[130:131], v[130:131], v[216:217] op_sel_hi:[1,0]
	v_pk_add_f32 v[132:133], v[132:133], v[216:217] op_sel_hi:[1,0]
	v_pk_add_f32 v[134:135], v[134:135], v[216:217] op_sel_hi:[1,0]
	v_pk_add_f32 v[136:137], v[136:137], v[216:217] op_sel_hi:[1,0]
	v_pk_add_f32 v[138:139], v[138:139], v[216:217] op_sel_hi:[1,0]
	v_pk_add_f32 v[140:141], v[140:141], v[216:217] op_sel_hi:[1,0]
	v_pk_add_f32 v[142:143], v[142:143], v[216:217] op_sel_hi:[1,0]
	v_pk_add_f32 v[144:145], v[144:145], v[216:217] op_sel_hi:[1,0]
	v_pk_add_f32 v[146:147], v[146:147], v[216:217] op_sel_hi:[1,0]
	v_pk_add_f32 v[148:149], v[148:149], v[216:217] op_sel_hi:[1,0]
	v_pk_add_f32 v[150:151], v[150:151], v[216:217] op_sel_hi:[1,0]
	v_pk_add_f32 v[152:153], v[152:153], v[216:217] op_sel_hi:[1,0]
	v_pk_add_f32 v[154:155], v[154:155], v[216:217] op_sel_hi:[1,0]
	v_pk_add_f32 v[156:157], v[156:157], v[216:217] op_sel_hi:[1,0]
	v_pk_add_f32 v[158:159], v[158:159], v[216:217] op_sel_hi:[1,0]
	v_pk_mul_f32 v[236:237], v[128:129], v[128:129]
	v_pk_fma_f32 v[236:237], v[130:131], v[130:131], v[236:237]
	v_pk_fma_f32 v[236:237], v[132:133], v[132:133], v[236:237]
	v_pk_fma_f32 v[236:237], v[134:135], v[134:135], v[236:237]
	v_pk_fma_f32 v[236:237], v[136:137], v[136:137], v[236:237]
	v_pk_fma_f32 v[236:237], v[138:139], v[138:139], v[236:237]
	v_pk_fma_f32 v[236:237], v[140:141], v[140:141], v[236:237]
	v_pk_fma_f32 v[236:237], v[142:143], v[142:143], v[236:237]
	v_pk_fma_f32 v[236:237], v[144:145], v[144:145], v[236:237]
	v_pk_fma_f32 v[236:237], v[146:147], v[146:147], v[236:237]
	v_pk_fma_f32 v[236:237], v[148:149], v[148:149], v[236:237]
	v_pk_fma_f32 v[236:237], v[150:151], v[150:151], v[236:237]
	v_pk_fma_f32 v[236:237], v[152:153], v[152:153], v[236:237]
	v_pk_fma_f32 v[236:237], v[154:155], v[154:155], v[236:237]
	v_pk_fma_f32 v[236:237], v[156:157], v[156:157], v[236:237]
	v_pk_fma_f32 v[236:237], v[158:159], v[158:159], v[236:237]
	v_add_f32_e32 v235, v236, v237
	s_nop 1
	v_add_f32_dpp v235, v235, v235 quad_perm:[1,0,3,2] row_mask:0xf bank_mask:0xf
	s_nop 1
	v_add_f32_dpp v235, v235, v235 quad_perm:[2,3,0,1] row_mask:0xf bank_mask:0xf
	s_nop 1
	v_add_f32_dpp v235, v235, v235 row_half_mirror row_mask:0xf bank_mask:0xf
	s_nop 1
	v_add_f32_dpp v235, v235, v235 row_mirror row_mask:0xf bank_mask:0xf
	s_nop 0
	v_readlane_b32 s26, v235, 0
	v_readlane_b32 s27, v235, 16
	v_readlane_b32 s28, v235, 32
	v_readlane_b32 s29, v235, 48
	v_mov_b32_e32 v235, s26
	v_add_f32_e32 v235, s27, v235
	v_add_f32_e32 v235, s28, v235
	v_add_f32_e32 v235, s29, v235
	v_fmamk_f32 v235, v235, 0x3a000000, v246
	v_rsq_f32_e32 v217, v235
	s_lshl_b32 s23, s20, 13
	s_lshr_b32 s23, s23, 1
	s_add_u32 s30, s10, s23
	s_addc_u32 s31, s11, 0
	s_lshl_b32 s23, s20, 3
	s_add_u32 s2, s12, s23
	s_addc_u32 s3, s13, 0
	v_mov_b32_e32 v243, 0
	s_mov_b64 exec, 1
	global_store_dwordx2 v243, v[216:217], s[2:3]
	s_mov_b64 exec, -1
	v_pk_mul_f32 v[128:129], v[128:129], v[216:217] op_sel:[0,1] op_sel_hi:[1,1]
	v_pk_mul_f32 v[130:131], v[130:131], v[216:217] op_sel:[0,1] op_sel_hi:[1,1]
	v_pk_fma_f32 v[128:129], v[0:1], v[128:129], v[32:33]
	v_pk_fma_f32 v[130:131], v[2:3], v[130:131], v[34:35]
	v_pk_mul_f32 v[132:133], v[132:133], v[216:217] op_sel:[0,1] op_sel_hi:[1,1]
	v_pk_mul_f32 v[134:135], v[134:135], v[216:217] op_sel:[0,1] op_sel_hi:[1,1]
	v_pk_fma_f32 v[132:133], v[4:5], v[132:133], v[36:37]
	v_pk_fma_f32 v[134:135], v[6:7], v[134:135], v[38:39]
	v_cvt_pk_bf16_f32 v208, v128, v129
	v_cvt_pk_bf16_f32 v209, v130, v131
	v_cvt_pk_bf16_f32 v210, v132, v133
	v_cvt_pk_bf16_f32 v211, v134, v135
	global_store_dwordx4 v242, v[208:211], s[30:31]
	v_pk_mul_f32 v[136:137], v[136:137], v[216:217] op_sel:[0,1] op_sel_hi:[1,1]
	v_pk_mul_f32 v[138:139], v[138:139], v[216:217] op_sel:[0,1] op_sel_hi:[1,1]
	v_pk_fma_f32 v[136:137], v[8:9], v[136:137], v[40:41]
	v_pk_fma_f32 v[138:139], v[10:11], v[138:139], v[42:43]
	v_pk_mul_f32 v[140:141], v[140:141], v[216:217] op_sel:[0,1] op_sel_hi:[1,1]
	v_pk_mul_f32 v[142:143], v[142:143], v[216:217] op_sel:[0,1] op_sel_hi:[1,1]
	v_pk_fma_f32 v[140:141], v[12:13], v[140:141], v[44:45]
	v_pk_fma_f32 v[142:143], v[14:15], v[142:143], v[46:47]
	v_cvt_pk_bf16_f32 v212, v136, v137
; __device__ __forceinline__ void ln_phase(const float* in, float* outf, bf16_t* outb, const float* g, const float* b, int wv0) {
;     ...
;   for (int row = wv; row < NTOK; row += nwv) {
;     f32x4 v[8]; float s = 0.f;
; #pragma unroll
;     for (int i = 0; i < 8; ++i) v[i] = vn[i];
;     if (row + nwv < NTOK) { const f32x4* ir = (const f32x4*)(in + (size_t)(row + nwv) * DM);
; #pragma unroll
;       for (int i = 0; i < 8; ++i) vn[i] = ir[i * 64 + lane]; }
; #pragma unroll
;     for (int i = 0; i < 8; ++i) s += v[i][0] + v[i][1] + v[i][2] + v[i][3];
;     s = wave_sum(s); const float mu = s * (1.0f / 2048.0f);
;     float sq = 0.f;
; #pragma unroll
;     for (int i = 0; i < 8; ++i) { v[i] -= mu; sq += v[i][0] * v[i][0] + v[i][1] * v[i][1] + v[i][2] * v[i][2] + v[i][3] * v[i][3]; }
;     sq = wave_sum(sq); const float rstd = __builtin_amdgcn_rsqf(sq * (1.0f / 2048.0f) + EPS);
; #pragma unroll
;     for (int i = 0; i < 8; ++i) {
;       const f32x4 y = v[i] * rstd * gg[i] + bb[i];
;       ((f32x4*)(outf + (size_t)row * DM))[i * 64 + lane] = y;
;       if (outb) { u32x2 w; w.x = pk2(y[0], y[1]); w.y = pk2(y[2], y[3]); ((u32x2*)(outb + (size_t)row * DM))[i * 64 + lane] = w; } }
	v_cvt_pk_bf16_f32 v213, v138, v139
	v_cvt_pk_bf16_f32 v214, v140, v141
	v_cvt_pk_bf16_f32 v215, v142, v143
	global_store_dwordx4 v242, v[212:215], s[30:31] offset:1024
	v_pk_mul_f32 v[144:145], v[144:145], v[216:217] op_sel:[0,1] op_sel_hi:[1,1]
	v_pk_mul_f32 v[146:147], v[146:147], v[216:217] op_sel:[0,1] op_sel_hi:[1,1]
	v_pk_fma_f32 v[144:145], v[16:17], v[144:145], v[48:49]
	v_pk_fma_f32 v[146:147], v[18:19], v[146:147], v[50:51]
	v_pk_mul_f32 v[148:149], v[148:149], v[216:217] op_sel:[0,1] op_sel_hi:[1,1]
	v_pk_mul_f32 v[150:151], v[150:151], v[216:217] op_sel:[0,1] op_sel_hi:[1,1]
	v_pk_fma_f32 v[148:149], v[20:21], v[148:149], v[52:53]
	v_pk_fma_f32 v[150:151], v[22:23], v[150:151], v[54:55]
	v_cvt_pk_bf16_f32 v208, v144, v145
	v_cvt_pk_bf16_f32 v209, v146, v147
	v_cvt_pk_bf16_f32 v210, v148, v149
	v_cvt_pk_bf16_f32 v211, v150, v151
	global_store_dwordx4 v242, v[208:211], s[30:31] offset:2048
	v_pk_mul_f32 v[152:153], v[152:153], v[216:217] op_sel:[0,1] op_sel_hi:[1,1]
	v_pk_mul_f32 v[154:155], v[154:155], v[216:217] op_sel:[0,1] op_sel_hi:[1,1]
	v_pk_fma_f32 v[152:153], v[24:25], v[152:153], v[56:57]
	v_pk_fma_f32 v[154:155], v[26:27], v[154:155], v[58:59]
	v_pk_mul_f32 v[156:157], v[156:157], v[216:217] op_sel:[0,1] op_sel_hi:[1,1]
	v_pk_mul_f32 v[158:159], v[158:159], v[216:217] op_sel:[0,1] op_sel_hi:[1,1]
	v_pk_fma_f32 v[156:157], v[28:29], v[156:157], v[60:61]
	v_pk_fma_f32 v[158:159], v[30:31], v[158:159], v[62:63]
	v_cvt_pk_bf16_f32 v212, v152, v153
	v_cvt_pk_bf16_f32 v213, v154, v155
	v_cvt_pk_bf16_f32 v214, v156, v157
	v_cvt_pk_bf16_f32 v215, v158, v159
	global_store_dwordx4 v242, v[212:215], s[30:31] offset:3072
	s_add_u32 s20, s20, s21
	s_cmp_ge_u32 s20, 0x4000
	s_cbranch_scc1 .Lln1_done
.Lln1_loop:
	s_mul_i32 s23, s21, 3
	s_add_u32 s23, s20, s23
	s_min_u32 s23, s23, 0x3fff
	s_lshl_b32 s23, s23, 13
	s_add_u32 s24, s8, s23
	s_addc_u32 s25, s9, 0
	global_load_dwordx4 v[128:131], v240, s[24:25]
	global_load_dwordx4 v[132:135], v240, s[24:25] offset:16
	global_load_dwordx4 v[136:139], v240, s[24:25] offset:2048
	global_load_dwordx4 v[140:143], v240, s[24:25] offset:2064
	global_load_dwordx4 v[144:147], v241, s[24:25]
	global_load_dwordx4 v[148:151], v241, s[24:25] offset:16
	global_load_dwordx4 v[152:155], v241, s[24:25] offset:2048
	global_load_dwordx4 v[156:159], v241, s[24:25] offset:2064
	s_waitcnt vmcnt(39)
	v_pk_add_f32 v[236:237], v[176:177], v[178:179]
	v_pk_add_f32 v[236:237], v[236:237], v[180:181]
	v_pk_add_f32 v[236:237], v[236:237], v[182:183]
	v_pk_add_f32 v[236:237], v[236:237], v[184:185]
	v_pk_add_f32 v[236:237], v[236:237], v[186:187]
	v_pk_add_f32 v[236:237], v[236:237], v[188:189]
	v_pk_add_f32 v[236:237], v[236:237], v[190:191]
	v_pk_add_f32 v[236:237], v[236:237], v[192:193]
	v_pk_add_f32 v[236:237], v[236:237], v[194:195]
	v_pk_add_f32 v[236:237], v[236:237], v[196:197]
	v_pk_add_f32 v[236:237], v[236:237], v[198:199]
	v_pk_add_f32 v[236:237], v[236:237], v[200:201]
	v_pk_add_f32 v[236:237], v[236:237], v[202:203]
	v_pk_add_f32 v[236:237], v[236:237], v[204:205]
	v_pk_add_f32 v[236:237], v[236:237], v[206:207]
	v_add_f32_e32 v234, v236, v237
	s_nop 1
	v_add_f32_dpp v234, v234, v234 quad_perm:[1,0,3,2] row_mask:0xf bank_mask:0xf
	s_nop 1
	v_add_f32_dpp v234, v234, v234 quad_perm:[2,3,0,1] row_mask:0xf bank_mask:0xf
	s_nop 1
	v_add_f32_dpp v234, v234, v234 row_half_mirror row_mask:0xf bank_mask:0xf
	s_nop 1
	v_add_f32_dpp v234, v234, v234 row_mirror row_mask:0xf bank_mask:0xf
	s_nop 0
	v_readlane_b32 s26, v234, 0
	v_readlane_b32 s27, v234, 16
	v_readlane_b32 s28, v234, 32
	v_readlane_b32 s29, v234, 48
	v_mov_b32_e32 v234, s26
	v_add_f32_e32 v234, s27, v234
	v_add_f32_e32 v234, s28, v234
	v_add_f32_e32 v234, s29, v234
	v_mul_f32_e32 v216, 0xba000000, v234
	v_pk_add_f32 v[176:177], v[176:177], v[216:217] op_sel_hi:[1,0]
	v_pk_add_f32 v[178:179], v[178:179], v[216:217] op_sel_hi:[1,0]
	v_pk_add_f32 v[180:181], v[180:181], v[216:217] op_sel_hi:[1,0]
	v_pk_add_f32 v[182:183], v[182:183], v[216:217] op_sel_hi:[1,0]
	v_pk_add_f32 v[184:185], v[184:185], v[216:217] op_sel_hi:[1,0]
	v_pk_add_f32 v[186:187], v[186:187], v[216:217] op_sel_hi:[1,0]
	v_pk_add_f32 v[188:189], v[188:189], v[216:217] op_sel_hi:[1,0]
	v_pk_add_f32 v[190:191], v[190:191], v[216:217] op_sel_hi:[1,0]
	v_pk_add_f32 v[192:193], v[192:193], v[216:217] op_sel_hi:[1,0]
	v_pk_add_f32 v[194:195], v[194:195], v[216:217] op_sel_hi:[1,0]
	v_pk_add_f32 v[196:197], v[196:197], v[216:217] op_sel_hi:[1,0]
	v_pk_add_f32 v[198:199], v[198:199], v[216:217] op_sel_hi:[1,0]
	v_pk_add_f32 v[200:201], v[200:201], v[216:217] op_sel_hi:[1,0]
	v_pk_add_f32 v[202:203], v[202:203], v[216:217] op_sel_hi:[1,0]
	v_pk_add_f32 v[204:205], v[204:205], v[216:217] op_sel_hi:[1,0]
	v_pk_add_f32 v[206:207], v[206:207], v[216:217] op_sel_hi:[1,0]
	v_pk_mul_f32 v[236:237], v[176:177], v[176:177]
	v_pk_fma_f32 v[236:237], v[178:179], v[178:179], v[236:237]
	v_pk_fma_f32 v[236:237], v[180:181], v[180:181], v[236:237]
	v_pk_fma_f32 v[236:237], v[182:183], v[182:183], v[236:237]
	v_pk_fma_f32 v[236:237], v[184:185], v[184:185], v[236:237]
	v_pk_fma_f32 v[236:237], v[186:187], v[186:187], v[236:237]
	v_pk_fma_f32 v[236:237], v[188:189], v[188:189], v[236:237]
	v_pk_fma_f32 v[236:237], v[190:191], v[190:191], v[236:237]
	v_pk_fma_f32 v[236:237], v[192:193], v[192:193], v[236:237]
	v_pk_fma_f32 v[236:237], v[194:195], v[194:195], v[236:237]
	v_pk_fma_f32 v[236:237], v[196:197], v[196:197], v[236:237]
	v_pk_fma_f32 v[236:237], v[198:199], v[198:199], v[236:237]
	v_pk_fma_f32 v[236:237], v[200:201], v[200:201], v[236:237]
	v_pk_fma_f32 v[236:237], v[202:203], v[202:203], v[236:237]
; __device__ __forceinline__ void ln_phase(const float* in, float* outf, bf16_t* outb, const float* g, const float* b, int wv0) {
;     ...
;     s = wave_sum(s); const float mu = s * (1.0f / 2048.0f);
;     float sq = 0.f;
; #pragma unroll
;     for (int i = 0; i < 8; ++i) { v[i] -= mu; sq += v[i][0] * v[i][0] + v[i][1] * v[i][1] + v[i][2] * v[i][2] + v[i][3] * v[i][3]; }
;     sq = wave_sum(sq); const float rstd = __builtin_amdgcn_rsqf(sq * (1.0f / 2048.0f) + EPS);
; #pragma unroll
;     for (int i = 0; i < 8; ++i) {
;       const f32x4 y = v[i] * rstd * gg[i] + bb[i];
;       ((f32x4*)(outf + (size_t)row * DM))[i * 64 + lane] = y;
;       if (outb) { u32x2 w; w.x = pk2(y[0], y[1]); w.y = pk2(y[2], y[3]); ((u32x2*)(outb + (size_t)row * DM))[i * 64 + lane] = w; } }
;   }
	v_pk_fma_f32 v[236:237], v[204:205], v[204:205], v[236:237]
	v_pk_fma_f32 v[236:237], v[206:207], v[206:207], v[236:237]
	v_add_f32_e32 v235, v236, v237
	s_nop 1
	v_add_f32_dpp v235, v235, v235 quad_perm:[1,0,3,2] row_mask:0xf bank_mask:0xf
	s_nop 1
	v_add_f32_dpp v235, v235, v235 quad_perm:[2,3,0,1] row_mask:0xf bank_mask:0xf
	s_nop 1
	v_add_f32_dpp v235, v235, v235 row_half_mirror row_mask:0xf bank_mask:0xf
	s_nop 1
	v_add_f32_dpp v235, v235, v235 row_mirror row_mask:0xf bank_mask:0xf
	s_nop 0
	v_readlane_b32 s26, v235, 0
	v_readlane_b32 s27, v235, 16
	v_readlane_b32 s28, v235, 32
	v_readlane_b32 s29, v235, 48
	v_mov_b32_e32 v235, s26
	v_add_f32_e32 v235, s27, v235
	v_add_f32_e32 v235, s28, v235
	v_add_f32_e32 v235, s29, v235
	v_fmamk_f32 v235, v235, 0x3a000000, v246
	v_rsq_f32_e32 v217, v235
	s_lshl_b32 s23, s20, 13
	s_lshr_b32 s23, s23, 1
	s_add_u32 s30, s10, s23
	s_addc_u32 s31, s11, 0
	s_lshl_b32 s23, s20, 3
	s_add_u32 s2, s12, s23
	s_addc_u32 s3, s13, 0
	v_mov_b32_e32 v243, 0
	s_mov_b64 exec, 1
	global_store_dwordx2 v243, v[216:217], s[2:3]
	s_mov_b64 exec, -1
	v_pk_mul_f32 v[176:177], v[176:177], v[216:217] op_sel:[0,1] op_sel_hi:[1,1]
	v_pk_mul_f32 v[178:179], v[178:179], v[216:217] op_sel:[0,1] op_sel_hi:[1,1]
	v_pk_fma_f32 v[176:177], v[0:1], v[176:177], v[32:33]
	v_pk_fma_f32 v[178:179], v[2:3], v[178:179], v[34:35]
	v_pk_mul_f32 v[180:181], v[180:181], v[216:217] op_sel:[0,1] op_sel_hi:[1,1]
	v_pk_mul_f32 v[182:183], v[182:183], v[216:217] op_sel:[0,1] op_sel_hi:[1,1]
	v_pk_fma_f32 v[180:181], v[4:5], v[180:181], v[36:37]
	v_pk_fma_f32 v[182:183], v[6:7], v[182:183], v[38:39]
	v_cvt_pk_bf16_f32 v208, v176, v177
	v_cvt_pk_bf16_f32 v209, v178, v179
	v_cvt_pk_bf16_f32 v210, v180, v181
	v_cvt_pk_bf16_f32 v211, v182, v183
	global_store_dwordx4 v242, v[208:211], s[30:31]
	v_pk_mul_f32 v[184:185], v[184:185], v[216:217] op_sel:[0,1] op_sel_hi:[1,1]
	v_pk_mul_f32 v[186:187], v[186:187], v[216:217] op_sel:[0,1] op_sel_hi:[1,1]
	v_pk_fma_f32 v[184:185], v[8:9], v[184:185], v[40:41]
	v_pk_fma_f32 v[186:187], v[10:11], v[186:187], v[42:43]
	v_pk_mul_f32 v[188:189], v[188:189], v[216:217] op_sel:[0,1] op_sel_hi:[1,1]
	v_pk_mul_f32 v[190:191], v[190:191], v[216:217] op_sel:[0,1] op_sel_hi:[1,1]
	v_pk_fma_f32 v[188:189], v[12:13], v[188:189], v[44:45]
	v_pk_fma_f32 v[190:191], v[14:15], v[190:191], v[46:47]
	v_cvt_pk_bf16_f32 v212, v184, v185
	v_cvt_pk_bf16_f32 v213, v186, v187
	v_cvt_pk_bf16_f32 v214, v188, v189
	v_cvt_pk_bf16_f32 v215, v190, v191
	global_store_dwordx4 v242, v[212:215], s[30:31] offset:1024
	v_pk_mul_f32 v[192:193], v[192:193], v[216:217] op_sel:[0,1] op_sel_hi:[1,1]
	v_pk_mul_f32 v[194:195], v[194:195], v[216:217] op_sel:[0,1] op_sel_hi:[1,1]
	v_pk_fma_f32 v[192:193], v[16:17], v[192:193], v[48:49]
	v_pk_fma_f32 v[194:195], v[18:19], v[194:195], v[50:51]
	v_pk_mul_f32 v[196:197], v[196:197], v[216:217] op_sel:[0,1] op_sel_hi:[1,1]
	v_pk_mul_f32 v[198:199], v[198:199], v[216:217] op_sel:[0,1] op_sel_hi:[1,1]
	v_pk_fma_f32 v[196:197], v[20:21], v[196:197], v[52:53]
	v_pk_fma_f32 v[198:199], v[22:23], v[198:199], v[54:55]
	v_cvt_pk_bf16_f32 v208, v192, v193
	v_cvt_pk_bf16_f32 v209, v194, v195
	v_cvt_pk_bf16_f32 v210, v196, v197
	v_cvt_pk_bf16_f32 v211, v198, v199
	global_store_dwordx4 v242, v[208:211], s[30:31] offset:2048
	v_pk_mul_f32 v[200:201], v[200:201], v[216:217] op_sel:[0,1] op_sel_hi:[1,1]
	v_pk_mul_f32 v[202:203], v[202:203], v[216:217] op_sel:[0,1] op_sel_hi:[1,1]
	v_pk_fma_f32 v[200:201], v[24:25], v[200:201], v[56:57]
	v_pk_fma_f32 v[202:203], v[26:27], v[202:203], v[58:59]
	v_pk_mul_f32 v[204:205], v[204:205], v[216:217] op_sel:[0,1] op_sel_hi:[1,1]
	v_pk_mul_f32 v[206:207], v[206:207], v[216:217] op_sel:[0,1] op_sel_hi:[1,1]
	v_pk_fma_f32 v[204:205], v[28:29], v[204:205], v[60:61]
	v_pk_fma_f32 v[206:207], v[30:31], v[206:207], v[62:63]
	v_cvt_pk_bf16_f32 v212, v200, v201
	v_cvt_pk_bf16_f32 v213, v202, v203
	v_cvt_pk_bf16_f32 v214, v204, v205
	v_cvt_pk_bf16_f32 v215, v206, v207
	global_store_dwordx4 v242, v[212:215], s[30:31] offset:3072
	s_add_u32 s20, s20, s21
	s_cmp_ge_u32 s20, 0x4000
	s_cbranch_scc1 .Lln1_done
	s_mul_i32 s23, s21, 3
	s_add_u32 s23, s20, s23
	s_min_u32 s23, s23, 0x3fff
	s_lshl_b32 s23, s23, 13
	s_add_u32 s24, s8, s23
	s_addc_u32 s25, s9, 0
	global_load_dwordx4 v[176:179], v240, s[24:25]
	global_load_dwordx4 v[180:183], v240, s[24:25] offset:16
	global_load_dwordx4 v[184:187], v240, s[24:25] offset:2048
	global_load_dwordx4 v[188:191], v240, s[24:25] offset:2064
	global_load_dwordx4 v[192:195], v241, s[24:25]
	global_load_dwordx4 v[196:199], v241, s[24:25] offset:16
	global_load_dwordx4 v[200:203], v241, s[24:25] offset:2048
	global_load_dwordx4 v[204:207], v241, s[24:25] offset:2064
	s_waitcnt vmcnt(39)
; __device__ __forceinline__ void ln_phase(const float* in, float* outf, bf16_t* outb, const float* g, const float* b, int wv0) {
;     ...
; #pragma unroll
;     for (int i = 0; i < 8; ++i) s += v[i][0] + v[i][1] + v[i][2] + v[i][3];
;     s = wave_sum(s); const float mu = s * (1.0f / 2048.0f);
;     float sq = 0.f;
; #pragma unroll
;     for (int i = 0; i < 8; ++i) { v[i] -= mu; sq += v[i][0] * v[i][0] + v[i][1] * v[i][1] + v[i][2] * v[i][2] + v[i][3] * v[i][3]; }
;     sq = wave_sum(sq); const float rstd = __builtin_amdgcn_rsqf(sq * (1.0f / 2048.0f) + EPS);
; #pragma unroll
;     for (int i = 0; i < 8; ++i) {
;       const f32x4 y = v[i] * rstd * gg[i] + bb[i];
;       ((f32x4*)(outf + (size_t)row * DM))[i * 64 + lane] = y;
;       if (outb) { u32x2 w; w.x = pk2(y[0], y[1]); w.y = pk2(y[2], y[3]); ((u32x2*)(outb + (size_t)row * DM))[i * 64 + lane] = w; } }
	v_pk_add_f32 v[236:237], v[64:65], v[66:67]
	v_pk_add_f32 v[236:237], v[236:237], v[68:69]
	v_pk_add_f32 v[236:237], v[236:237], v[70:71]
	v_pk_add_f32 v[236:237], v[236:237], v[72:73]
	v_pk_add_f32 v[236:237], v[236:237], v[74:75]
	v_pk_add_f32 v[236:237], v[236:237], v[76:77]
	v_pk_add_f32 v[236:237], v[236:237], v[78:79]
	v_pk_add_f32 v[236:237], v[236:237], v[80:81]
	v_pk_add_f32 v[236:237], v[236:237], v[82:83]
	v_pk_add_f32 v[236:237], v[236:237], v[84:85]
	v_pk_add_f32 v[236:237], v[236:237], v[86:87]
	v_pk_add_f32 v[236:237], v[236:237], v[88:89]
	v_pk_add_f32 v[236:237], v[236:237], v[90:91]
	v_pk_add_f32 v[236:237], v[236:237], v[92:93]
	v_pk_add_f32 v[236:237], v[236:237], v[94:95]
	v_add_f32_e32 v234, v236, v237
	s_nop 1
	v_add_f32_dpp v234, v234, v234 quad_perm:[1,0,3,2] row_mask:0xf bank_mask:0xf
	s_nop 1
	v_add_f32_dpp v234, v234, v234 quad_perm:[2,3,0,1] row_mask:0xf bank_mask:0xf
	s_nop 1
	v_add_f32_dpp v234, v234, v234 row_half_mirror row_mask:0xf bank_mask:0xf
	s_nop 1
	v_add_f32_dpp v234, v234, v234 row_mirror row_mask:0xf bank_mask:0xf
	s_nop 0
	v_readlane_b32 s26, v234, 0
	v_readlane_b32 s27, v234, 16
	v_readlane_b32 s28, v234, 32
	v_readlane_b32 s29, v234, 48
	v_mov_b32_e32 v234, s26
	v_add_f32_e32 v234, s27, v234
	v_add_f32_e32 v234, s28, v234
	v_add_f32_e32 v234, s29, v234
	v_mul_f32_e32 v216, 0xba000000, v234
	v_pk_add_f32 v[64:65], v[64:65], v[216:217] op_sel_hi:[1,0]
	v_pk_add_f32 v[66:67], v[66:67], v[216:217] op_sel_hi:[1,0]
	v_pk_add_f32 v[68:69], v[68:69], v[216:217] op_sel_hi:[1,0]
	v_pk_add_f32 v[70:71], v[70:71], v[216:217] op_sel_hi:[1,0]
	v_pk_add_f32 v[72:73], v[72:73], v[216:217] op_sel_hi:[1,0]
	v_pk_add_f32 v[74:75], v[74:75], v[216:217] op_sel_hi:[1,0]
	v_pk_add_f32 v[76:77], v[76:77], v[216:217] op_sel_hi:[1,0]
	v_pk_add_f32 v[78:79], v[78:79], v[216:217] op_sel_hi:[1,0]
	v_pk_add_f32 v[80:81], v[80:81], v[216:217] op_sel_hi:[1,0]
	v_pk_add_f32 v[82:83], v[82:83], v[216:217] op_sel_hi:[1,0]
	v_pk_add_f32 v[84:85], v[84:85], v[216:217] op_sel_hi:[1,0]
	v_pk_add_f32 v[86:87], v[86:87], v[216:217] op_sel_hi:[1,0]
	v_pk_add_f32 v[88:89], v[88:89], v[216:217] op_sel_hi:[1,0]
	v_pk_add_f32 v[90:91], v[90:91], v[216:217] op_sel_hi:[1,0]
	v_pk_add_f32 v[92:93], v[92:93], v[216:217] op_sel_hi:[1,0]
	v_pk_add_f32 v[94:95], v[94:95], v[216:217] op_sel_hi:[1,0]
	v_pk_mul_f32 v[236:237], v[64:65], v[64:65]
	v_pk_fma_f32 v[236:237], v[66:67], v[66:67], v[236:237]
	v_pk_fma_f32 v[236:237], v[68:69], v[68:69], v[236:237]
	v_pk_fma_f32 v[236:237], v[70:71], v[70:71], v[236:237]
	v_pk_fma_f32 v[236:237], v[72:73], v[72:73], v[236:237]
	v_pk_fma_f32 v[236:237], v[74:75], v[74:75], v[236:237]
	v_pk_fma_f32 v[236:237], v[76:77], v[76:77], v[236:237]
	v_pk_fma_f32 v[236:237], v[78:79], v[78:79], v[236:237]
	v_pk_fma_f32 v[236:237], v[80:81], v[80:81], v[236:237]
	v_pk_fma_f32 v[236:237], v[82:83], v[82:83], v[236:237]
	v_pk_fma_f32 v[236:237], v[84:85], v[84:85], v[236:237]
	v_pk_fma_f32 v[236:237], v[86:87], v[86:87], v[236:237]
	v_pk_fma_f32 v[236:237], v[88:89], v[88:89], v[236:237]
	v_pk_fma_f32 v[236:237], v[90:91], v[90:91], v[236:237]
	v_pk_fma_f32 v[236:237], v[92:93], v[92:93], v[236:237]
	v_pk_fma_f32 v[236:237], v[94:95], v[94:95], v[236:237]
	v_add_f32_e32 v235, v236, v237
	s_nop 1
	v_add_f32_dpp v235, v235, v235 quad_perm:[1,0,3,2] row_mask:0xf bank_mask:0xf
	s_nop 1
	v_add_f32_dpp v235, v235, v235 quad_perm:[2,3,0,1] row_mask:0xf bank_mask:0xf
	s_nop 1
	v_add_f32_dpp v235, v235, v235 row_half_mirror row_mask:0xf bank_mask:0xf
	s_nop 1
	v_add_f32_dpp v235, v235, v235 row_mirror row_mask:0xf bank_mask:0xf
	s_nop 0
	v_readlane_b32 s26, v235, 0
	v_readlane_b32 s27, v235, 16
	v_readlane_b32 s28, v235, 32
	v_readlane_b32 s29, v235, 48
	v_mov_b32_e32 v235, s26
	v_add_f32_e32 v235, s27, v235
	v_add_f32_e32 v235, s28, v235
	v_add_f32_e32 v235, s29, v235
	v_fmamk_f32 v235, v235, 0x3a000000, v246
	v_rsq_f32_e32 v217, v235
	s_lshl_b32 s23, s20, 13
	s_lshr_b32 s23, s23, 1
	s_add_u32 s30, s10, s23
	s_addc_u32 s31, s11, 0
	s_lshl_b32 s23, s20, 3
	s_add_u32 s2, s12, s23
	s_addc_u32 s3, s13, 0
	v_mov_b32_e32 v243, 0
	s_mov_b64 exec, 1
	global_store_dwordx2 v243, v[216:217], s[2:3]
	s_mov_b64 exec, -1
	v_pk_mul_f32 v[64:65], v[64:65], v[216:217] op_sel:[0,1] op_sel_hi:[1,1]
	v_pk_mul_f32 v[66:67], v[66:67], v[216:217] op_sel:[0,1] op_sel_hi:[1,1]
	v_pk_fma_f32 v[64:65], v[0:1], v[64:65], v[32:33]
	v_pk_fma_f32 v[66:67], v[2:3], v[66:67], v[34:35]
	v_pk_mul_f32 v[68:69], v[68:69], v[216:217] op_sel:[0,1] op_sel_hi:[1,1]
	v_pk_mul_f32 v[70:71], v[70:71], v[216:217] op_sel:[0,1] op_sel_hi:[1,1]
	v_pk_fma_f32 v[68:69], v[4:5], v[68:69], v[36:37]
	v_pk_fma_f32 v[70:71], v[6:7], v[70:71], v[38:39]
	v_cvt_pk_bf16_f32 v208, v64, v65
	v_cvt_pk_bf16_f32 v209, v66, v67
	v_cvt_pk_bf16_f32 v210, v68, v69
	v_cvt_pk_bf16_f32 v211, v70, v71
	global_store_dwordx4 v242, v[208:211], s[30:31]
	v_pk_mul_f32 v[72:73], v[72:73], v[216:217] op_sel:[0,1] op_sel_hi:[1,1]
	v_pk_mul_f32 v[74:75], v[74:75], v[216:217] op_sel:[0,1] op_sel_hi:[1,1]
	v_pk_fma_f32 v[72:73], v[8:9], v[72:73], v[40:41]
	v_pk_fma_f32 v[74:75], v[10:11], v[74:75], v[42:43]
	v_pk_mul_f32 v[76:77], v[76:77], v[216:217] op_sel:[0,1] op_sel_hi:[1,1]
	v_pk_mul_f32 v[78:79], v[78:79], v[216:217] op_sel:[0,1] op_sel_hi:[1,1]
	v_pk_fma_f32 v[76:77], v[12:13], v[76:77], v[44:45]
	v_pk_fma_f32 v[78:79], v[14:15], v[78:79], v[46:47]
	v_cvt_pk_bf16_f32 v212, v72, v73
	v_cvt_pk_bf16_f32 v213, v74, v75
	v_cvt_pk_bf16_f32 v214, v76, v77
	v_cvt_pk_bf16_f32 v215, v78, v79
	global_store_dwordx4 v242, v[212:215], s[30:31] offset:1024
	v_pk_mul_f32 v[80:81], v[80:81], v[216:217] op_sel:[0,1] op_sel_hi:[1,1]
; __device__ __forceinline__ void ln_phase(const float* in, float* outf, bf16_t* outb, const float* g, const float* b, int wv0) {
;     ...
;   for (int row = wv; row < NTOK; row += nwv) {
;     f32x4 v[8]; float s = 0.f;
; #pragma unroll
;     for (int i = 0; i < 8; ++i) v[i] = vn[i];
;     if (row + nwv < NTOK) { const f32x4* ir = (const f32x4*)(in + (size_t)(row + nwv) * DM);
; #pragma unroll
;       for (int i = 0; i < 8; ++i) vn[i] = ir[i * 64 + lane]; }
; #pragma unroll
;     for (int i = 0; i < 8; ++i) s += v[i][0] + v[i][1] + v[i][2] + v[i][3];
;     s = wave_sum(s); const float mu = s * (1.0f / 2048.0f);
;     float sq = 0.f;
; #pragma unroll
;     for (int i = 0; i < 8; ++i) { v[i] -= mu; sq += v[i][0] * v[i][0] + v[i][1] * v[i][1] + v[i][2] * v[i][2] + v[i][3] * v[i][3]; }
;     sq = wave_sum(sq); const float rstd = __builtin_amdgcn_rsqf(sq * (1.0f / 2048.0f) + EPS);
; #pragma unroll
;     for (int i = 0; i < 8; ++i) {
;       const f32x4 y = v[i] * rstd * gg[i] + bb[i];
	v_pk_mul_f32 v[82:83], v[82:83], v[216:217] op_sel:[0,1] op_sel_hi:[1,1]
	v_pk_fma_f32 v[80:81], v[16:17], v[80:81], v[48:49]
	v_pk_fma_f32 v[82:83], v[18:19], v[82:83], v[50:51]
	v_pk_mul_f32 v[84:85], v[84:85], v[216:217] op_sel:[0,1] op_sel_hi:[1,1]
	v_pk_mul_f32 v[86:87], v[86:87], v[216:217] op_sel:[0,1] op_sel_hi:[1,1]
	v_pk_fma_f32 v[84:85], v[20:21], v[84:85], v[52:53]
	v_pk_fma_f32 v[86:87], v[22:23], v[86:87], v[54:55]
	v_cvt_pk_bf16_f32 v208, v80, v81
	v_cvt_pk_bf16_f32 v209, v82, v83
	v_cvt_pk_bf16_f32 v210, v84, v85
	v_cvt_pk_bf16_f32 v211, v86, v87
	global_store_dwordx4 v242, v[208:211], s[30:31] offset:2048
	v_pk_mul_f32 v[88:89], v[88:89], v[216:217] op_sel:[0,1] op_sel_hi:[1,1]
	v_pk_mul_f32 v[90:91], v[90:91], v[216:217] op_sel:[0,1] op_sel_hi:[1,1]
	v_pk_fma_f32 v[88:89], v[24:25], v[88:89], v[56:57]
	v_pk_fma_f32 v[90:91], v[26:27], v[90:91], v[58:59]
	v_pk_mul_f32 v[92:93], v[92:93], v[216:217] op_sel:[0,1] op_sel_hi:[1,1]
	v_pk_mul_f32 v[94:95], v[94:95], v[216:217] op_sel:[0,1] op_sel_hi:[1,1]
	v_pk_fma_f32 v[92:93], v[28:29], v[92:93], v[60:61]
	v_pk_fma_f32 v[94:95], v[30:31], v[94:95], v[62:63]
	v_cvt_pk_bf16_f32 v212, v88, v89
	v_cvt_pk_bf16_f32 v213, v90, v91
	v_cvt_pk_bf16_f32 v214, v92, v93
	v_cvt_pk_bf16_f32 v215, v94, v95
	global_store_dwordx4 v242, v[212:215], s[30:31] offset:3072
	s_add_u32 s20, s20, s21
	s_cmp_ge_u32 s20, 0x4000
	s_cbranch_scc1 .Lln1_done
	s_mul_i32 s23, s21, 3
	s_add_u32 s23, s20, s23
	s_min_u32 s23, s23, 0x3fff
	s_lshl_b32 s23, s23, 13
	s_add_u32 s24, s8, s23
	s_addc_u32 s25, s9, 0
	global_load_dwordx4 v[64:67], v240, s[24:25]
	global_load_dwordx4 v[68:71], v240, s[24:25] offset:16
	global_load_dwordx4 v[72:75], v240, s[24:25] offset:2048
	global_load_dwordx4 v[76:79], v240, s[24:25] offset:2064
	global_load_dwordx4 v[80:83], v241, s[24:25]
	global_load_dwordx4 v[84:87], v241, s[24:25] offset:16
	global_load_dwordx4 v[88:91], v241, s[24:25] offset:2048
	global_load_dwordx4 v[92:95], v241, s[24:25] offset:2064
	s_waitcnt vmcnt(39)
	v_pk_add_f32 v[236:237], v[96:97], v[98:99]
	v_pk_add_f32 v[236:237], v[236:237], v[100:101]
	v_pk_add_f32 v[236:237], v[236:237], v[102:103]
	v_pk_add_f32 v[236:237], v[236:237], v[104:105]
	v_pk_add_f32 v[236:237], v[236:237], v[106:107]
	v_pk_add_f32 v[236:237], v[236:237], v[108:109]
	v_pk_add_f32 v[236:237], v[236:237], v[110:111]
	v_pk_add_f32 v[236:237], v[236:237], v[112:113]
	v_pk_add_f32 v[236:237], v[236:237], v[114:115]
	v_pk_add_f32 v[236:237], v[236:237], v[116:117]
	v_pk_add_f32 v[236:237], v[236:237], v[118:119]
	v_pk_add_f32 v[236:237], v[236:237], v[120:121]
	v_pk_add_f32 v[236:237], v[236:237], v[122:123]
	v_pk_add_f32 v[236:237], v[236:237], v[124:125]
	v_pk_add_f32 v[236:237], v[236:237], v[126:127]
	v_add_f32_e32 v234, v236, v237
	s_nop 1
	v_add_f32_dpp v234, v234, v234 quad_perm:[1,0,3,2] row_mask:0xf bank_mask:0xf
	s_nop 1
	v_add_f32_dpp v234, v234, v234 quad_perm:[2,3,0,1] row_mask:0xf bank_mask:0xf
	s_nop 1
	v_add_f32_dpp v234, v234, v234 row_half_mirror row_mask:0xf bank_mask:0xf
	s_nop 1
	v_add_f32_dpp v234, v234, v234 row_mirror row_mask:0xf bank_mask:0xf
	s_nop 0
	v_readlane_b32 s26, v234, 0
	v_readlane_b32 s27, v234, 16
	v_readlane_b32 s28, v234, 32
	v_readlane_b32 s29, v234, 48
	v_mov_b32_e32 v234, s26
	v_add_f32_e32 v234, s27, v234
	v_add_f32_e32 v234, s28, v234
	v_add_f32_e32 v234, s29, v234
	v_mul_f32_e32 v216, 0xba000000, v234
	v_pk_add_f32 v[96:97], v[96:97], v[216:217] op_sel_hi:[1,0]
	v_pk_add_f32 v[98:99], v[98:99], v[216:217] op_sel_hi:[1,0]
	v_pk_add_f32 v[100:101], v[100:101], v[216:217] op_sel_hi:[1,0]
	v_pk_add_f32 v[102:103], v[102:103], v[216:217] op_sel_hi:[1,0]
	v_pk_add_f32 v[104:105], v[104:105], v[216:217] op_sel_hi:[1,0]
	v_pk_add_f32 v[106:107], v[106:107], v[216:217] op_sel_hi:[1,0]
	v_pk_add_f32 v[108:109], v[108:109], v[216:217] op_sel_hi:[1,0]
	v_pk_add_f32 v[110:111], v[110:111], v[216:217] op_sel_hi:[1,0]
	v_pk_add_f32 v[112:113], v[112:113], v[216:217] op_sel_hi:[1,0]
	v_pk_add_f32 v[114:115], v[114:115], v[216:217] op_sel_hi:[1,0]
	v_pk_add_f32 v[116:117], v[116:117], v[216:217] op_sel_hi:[1,0]
	v_pk_add_f32 v[118:119], v[118:119], v[216:217] op_sel_hi:[1,0]
	v_pk_add_f32 v[120:121], v[120:121], v[216:217] op_sel_hi:[1,0]
	v_pk_add_f32 v[122:123], v[122:123], v[216:217] op_sel_hi:[1,0]
	v_pk_add_f32 v[124:125], v[124:125], v[216:217] op_sel_hi:[1,0]
	v_pk_add_f32 v[126:127], v[126:127], v[216:217] op_sel_hi:[1,0]
	v_pk_mul_f32 v[236:237], v[96:97], v[96:97]
	v_pk_fma_f32 v[236:237], v[98:99], v[98:99], v[236:237]
	v_pk_fma_f32 v[236:237], v[100:101], v[100:101], v[236:237]
	v_pk_fma_f32 v[236:237], v[102:103], v[102:103], v[236:237]
	v_pk_fma_f32 v[236:237], v[104:105], v[104:105], v[236:237]
	v_pk_fma_f32 v[236:237], v[106:107], v[106:107], v[236:237]
	v_pk_fma_f32 v[236:237], v[108:109], v[108:109], v[236:237]
	v_pk_fma_f32 v[236:237], v[110:111], v[110:111], v[236:237]
	v_pk_fma_f32 v[236:237], v[112:113], v[112:113], v[236:237]
	v_pk_fma_f32 v[236:237], v[114:115], v[114:115], v[236:237]
	v_pk_fma_f32 v[236:237], v[116:117], v[116:117], v[236:237]
	v_pk_fma_f32 v[236:237], v[118:119], v[118:119], v[236:237]
	v_pk_fma_f32 v[236:237], v[120:121], v[120:121], v[236:237]
	v_pk_fma_f32 v[236:237], v[122:123], v[122:123], v[236:237]
	v_pk_fma_f32 v[236:237], v[124:125], v[124:125], v[236:237]
	v_pk_fma_f32 v[236:237], v[126:127], v[126:127], v[236:237]
	v_add_f32_e32 v235, v236, v237
	s_nop 1
	v_add_f32_dpp v235, v235, v235 quad_perm:[1,0,3,2] row_mask:0xf bank_mask:0xf
	s_nop 1
	v_add_f32_dpp v235, v235, v235 quad_perm:[2,3,0,1] row_mask:0xf bank_mask:0xf
	s_nop 1
; __device__ __forceinline__ void ln_phase(const float* in, float* outf, bf16_t* outb, const float* g, const float* b, int wv0) {
;     ...
;     s = wave_sum(s); const float mu = s * (1.0f / 2048.0f);
;     float sq = 0.f;
; #pragma unroll
;     for (int i = 0; i < 8; ++i) { v[i] -= mu; sq += v[i][0] * v[i][0] + v[i][1] * v[i][1] + v[i][2] * v[i][2] + v[i][3] * v[i][3]; }
;     sq = wave_sum(sq); const float rstd = __builtin_amdgcn_rsqf(sq * (1.0f / 2048.0f) + EPS);
; #pragma unroll
;     for (int i = 0; i < 8; ++i) {
;       const f32x4 y = v[i] * rstd * gg[i] + bb[i];
;       ((f32x4*)(outf + (size_t)row * DM))[i * 64 + lane] = y;
;       if (outb) { u32x2 w; w.x = pk2(y[0], y[1]); w.y = pk2(y[2], y[3]); ((u32x2*)(outb + (size_t)row * DM))[i * 64 + lane] = w; } }
;   }
	v_add_f32_dpp v235, v235, v235 row_half_mirror row_mask:0xf bank_mask:0xf
	s_nop 1
	v_add_f32_dpp v235, v235, v235 row_mirror row_mask:0xf bank_mask:0xf
	s_nop 0
	v_readlane_b32 s26, v235, 0
	v_readlane_b32 s27, v235, 16
	v_readlane_b32 s28, v235, 32
	v_readlane_b32 s29, v235, 48
	v_mov_b32_e32 v235, s26
	v_add_f32_e32 v235, s27, v235
	v_add_f32_e32 v235, s28, v235
	v_add_f32_e32 v235, s29, v235
	v_fmamk_f32 v235, v235, 0x3a000000, v246
	v_rsq_f32_e32 v217, v235
	s_lshl_b32 s23, s20, 13
	s_lshr_b32 s23, s23, 1
	s_add_u32 s30, s10, s23
	s_addc_u32 s31, s11, 0
	s_lshl_b32 s23, s20, 3
	s_add_u32 s2, s12, s23
	s_addc_u32 s3, s13, 0
	v_mov_b32_e32 v243, 0
	s_mov_b64 exec, 1
	global_store_dwordx2 v243, v[216:217], s[2:3]
	s_mov_b64 exec, -1
	v_pk_mul_f32 v[96:97], v[96:97], v[216:217] op_sel:[0,1] op_sel_hi:[1,1]
	v_pk_mul_f32 v[98:99], v[98:99], v[216:217] op_sel:[0,1] op_sel_hi:[1,1]
	v_pk_fma_f32 v[96:97], v[0:1], v[96:97], v[32:33]
	v_pk_fma_f32 v[98:99], v[2:3], v[98:99], v[34:35]
	v_pk_mul_f32 v[100:101], v[100:101], v[216:217] op_sel:[0,1] op_sel_hi:[1,1]
	v_pk_mul_f32 v[102:103], v[102:103], v[216:217] op_sel:[0,1] op_sel_hi:[1,1]
	v_pk_fma_f32 v[100:101], v[4:5], v[100:101], v[36:37]
	v_pk_fma_f32 v[102:103], v[6:7], v[102:103], v[38:39]
	v_cvt_pk_bf16_f32 v208, v96, v97
	v_cvt_pk_bf16_f32 v209, v98, v99
	v_cvt_pk_bf16_f32 v210, v100, v101
	v_cvt_pk_bf16_f32 v211, v102, v103
	global_store_dwordx4 v242, v[208:211], s[30:31]
	v_pk_mul_f32 v[104:105], v[104:105], v[216:217] op_sel:[0,1] op_sel_hi:[1,1]
	v_pk_mul_f32 v[106:107], v[106:107], v[216:217] op_sel:[0,1] op_sel_hi:[1,1]
	v_pk_fma_f32 v[104:105], v[8:9], v[104:105], v[40:41]
	v_pk_fma_f32 v[106:107], v[10:11], v[106:107], v[42:43]
	v_pk_mul_f32 v[108:109], v[108:109], v[216:217] op_sel:[0,1] op_sel_hi:[1,1]
	v_pk_mul_f32 v[110:111], v[110:111], v[216:217] op_sel:[0,1] op_sel_hi:[1,1]
	v_pk_fma_f32 v[108:109], v[12:13], v[108:109], v[44:45]
	v_pk_fma_f32 v[110:111], v[14:15], v[110:111], v[46:47]
	v_cvt_pk_bf16_f32 v212, v104, v105
	v_cvt_pk_bf16_f32 v213, v106, v107
	v_cvt_pk_bf16_f32 v214, v108, v109
	v_cvt_pk_bf16_f32 v215, v110, v111
	global_store_dwordx4 v242, v[212:215], s[30:31] offset:1024
	v_pk_mul_f32 v[112:113], v[112:113], v[216:217] op_sel:[0,1] op_sel_hi:[1,1]
	v_pk_mul_f32 v[114:115], v[114:115], v[216:217] op_sel:[0,1] op_sel_hi:[1,1]
	v_pk_fma_f32 v[112:113], v[16:17], v[112:113], v[48:49]
	v_pk_fma_f32 v[114:115], v[18:19], v[114:115], v[50:51]
	v_pk_mul_f32 v[116:117], v[116:117], v[216:217] op_sel:[0,1] op_sel_hi:[1,1]
	v_pk_mul_f32 v[118:119], v[118:119], v[216:217] op_sel:[0,1] op_sel_hi:[1,1]
	v_pk_fma_f32 v[116:117], v[20:21], v[116:117], v[52:53]
	v_pk_fma_f32 v[118:119], v[22:23], v[118:119], v[54:55]
	v_cvt_pk_bf16_f32 v208, v112, v113
	v_cvt_pk_bf16_f32 v209, v114, v115
	v_cvt_pk_bf16_f32 v210, v116, v117
	v_cvt_pk_bf16_f32 v211, v118, v119
	global_store_dwordx4 v242, v[208:211], s[30:31] offset:2048
	v_pk_mul_f32 v[120:121], v[120:121], v[216:217] op_sel:[0,1] op_sel_hi:[1,1]
	v_pk_mul_f32 v[122:123], v[122:123], v[216:217] op_sel:[0,1] op_sel_hi:[1,1]
	v_pk_fma_f32 v[120:121], v[24:25], v[120:121], v[56:57]
	v_pk_fma_f32 v[122:123], v[26:27], v[122:123], v[58:59]
	v_pk_mul_f32 v[124:125], v[124:125], v[216:217] op_sel:[0,1] op_sel_hi:[1,1]
	v_pk_mul_f32 v[126:127], v[126:127], v[216:217] op_sel:[0,1] op_sel_hi:[1,1]
	v_pk_fma_f32 v[124:125], v[28:29], v[124:125], v[60:61]
	v_pk_fma_f32 v[126:127], v[30:31], v[126:127], v[62:63]
	v_cvt_pk_bf16_f32 v212, v120, v121
	v_cvt_pk_bf16_f32 v213, v122, v123
	v_cvt_pk_bf16_f32 v214, v124, v125
	v_cvt_pk_bf16_f32 v215, v126, v127
	global_store_dwordx4 v242, v[212:215], s[30:31] offset:3072
	s_add_u32 s20, s20, s21
	s_cmp_ge_u32 s20, 0x4000
	s_cbranch_scc1 .Lln1_done
	s_mul_i32 s23, s21, 3
	s_add_u32 s23, s20, s23
	s_min_u32 s23, s23, 0x3fff
	s_lshl_b32 s23, s23, 13
	s_add_u32 s24, s8, s23
	s_addc_u32 s25, s9, 0
	global_load_dwordx4 v[96:99], v240, s[24:25]
	global_load_dwordx4 v[100:103], v240, s[24:25] offset:16
	global_load_dwordx4 v[104:107], v240, s[24:25] offset:2048
	global_load_dwordx4 v[108:111], v240, s[24:25] offset:2064
	global_load_dwordx4 v[112:115], v241, s[24:25]
	global_load_dwordx4 v[116:119], v241, s[24:25] offset:16
	global_load_dwordx4 v[120:123], v241, s[24:25] offset:2048
	global_load_dwordx4 v[124:127], v241, s[24:25] offset:2064
	s_waitcnt vmcnt(39)
; __device__ __forceinline__ void ln_phase(const float* in, float* outf, bf16_t* outb, const float* g, const float* b, int wv0) {
;     ...
; #pragma unroll
;     for (int i = 0; i < 8; ++i) s += v[i][0] + v[i][1] + v[i][2] + v[i][3];
;     s = wave_sum(s); const float mu = s * (1.0f / 2048.0f);
;     float sq = 0.f;
; #pragma unroll
;     for (int i = 0; i < 8; ++i) { v[i] -= mu; sq += v[i][0] * v[i][0] + v[i][1] * v[i][1] + v[i][2] * v[i][2] + v[i][3] * v[i][3]; }
;     sq = wave_sum(sq); const float rstd = __builtin_amdgcn_rsqf(sq * (1.0f / 2048.0f) + EPS);
	v_pk_add_f32 v[236:237], v[128:129], v[130:131]
	v_pk_add_f32 v[236:237], v[236:237], v[132:133]
	v_pk_add_f32 v[236:237], v[236:237], v[134:135]
	v_pk_add_f32 v[236:237], v[236:237], v[136:137]
	v_pk_add_f32 v[236:237], v[236:237], v[138:139]
	v_pk_add_f32 v[236:237], v[236:237], v[140:141]
	v_pk_add_f32 v[236:237], v[236:237], v[142:143]
	v_pk_add_f32 v[236:237], v[236:237], v[144:145]
	v_pk_add_f32 v[236:237], v[236:237], v[146:147]
	v_pk_add_f32 v[236:237], v[236:237], v[148:149]
	v_pk_add_f32 v[236:237], v[236:237], v[150:151]
	v_pk_add_f32 v[236:237], v[236:237], v[152:153]
	v_pk_add_f32 v[236:237], v[236:237], v[154:155]
	v_pk_add_f32 v[236:237], v[236:237], v[156:157]
	v_pk_add_f32 v[236:237], v[236:237], v[158:159]
	v_add_f32_e32 v234, v236, v237
	s_nop 1
	v_add_f32_dpp v234, v234, v234 quad_perm:[1,0,3,2] row_mask:0xf bank_mask:0xf
	s_nop 1
	v_add_f32_dpp v234, v234, v234 quad_perm:[2,3,0,1] row_mask:0xf bank_mask:0xf
	s_nop 1
	v_add_f32_dpp v234, v234, v234 row_half_mirror row_mask:0xf bank_mask:0xf
	s_nop 1
	v_add_f32_dpp v234, v234, v234 row_mirror row_mask:0xf bank_mask:0xf
	s_nop 0
	v_readlane_b32 s26, v234, 0
	v_readlane_b32 s27, v234, 16
	v_readlane_b32 s28, v234, 32
	v_readlane_b32 s29, v234, 48
	v_mov_b32_e32 v234, s26
	v_add_f32_e32 v234, s27, v234
	v_add_f32_e32 v234, s28, v234
	v_add_f32_e32 v234, s29, v234
	v_mul_f32_e32 v216, 0xba000000, v234
	v_pk_add_f32 v[128:129], v[128:129], v[216:217] op_sel_hi:[1,0]
	v_pk_add_f32 v[130:131], v[130:131], v[216:217] op_sel_hi:[1,0]
	v_pk_add_f32 v[132:133], v[132:133], v[216:217] op_sel_hi:[1,0]
	v_pk_add_f32 v[134:135], v[134:135], v[216:217] op_sel_hi:[1,0]
	v_pk_add_f32 v[136:137], v[136:137], v[216:217] op_sel_hi:[1,0]
	v_pk_add_f32 v[138:139], v[138:139], v[216:217] op_sel_hi:[1,0]
	v_pk_add_f32 v[140:141], v[140:141], v[216:217] op_sel_hi:[1,0]
	v_pk_add_f32 v[142:143], v[142:143], v[216:217] op_sel_hi:[1,0]
	v_pk_add_f32 v[144:145], v[144:145], v[216:217] op_sel_hi:[1,0]
	v_pk_add_f32 v[146:147], v[146:147], v[216:217] op_sel_hi:[1,0]
	v_pk_add_f32 v[148:149], v[148:149], v[216:217] op_sel_hi:[1,0]
	v_pk_add_f32 v[150:151], v[150:151], v[216:217] op_sel_hi:[1,0]
	v_pk_add_f32 v[152:153], v[152:153], v[216:217] op_sel_hi:[1,0]
	v_pk_add_f32 v[154:155], v[154:155], v[216:217] op_sel_hi:[1,0]
	v_pk_add_f32 v[156:157], v[156:157], v[216:217] op_sel_hi:[1,0]
	v_pk_add_f32 v[158:159], v[158:159], v[216:217] op_sel_hi:[1,0]
	v_pk_mul_f32 v[236:237], v[128:129], v[128:129]
	v_pk_fma_f32 v[236:237], v[130:131], v[130:131], v[236:237]
	v_pk_fma_f32 v[236:237], v[132:133], v[132:133], v[236:237]
	v_pk_fma_f32 v[236:237], v[134:135], v[134:135], v[236:237]
	v_pk_fma_f32 v[236:237], v[136:137], v[136:137], v[236:237]
	v_pk_fma_f32 v[236:237], v[138:139], v[138:139], v[236:237]
	v_pk_fma_f32 v[236:237], v[140:141], v[140:141], v[236:237]
	v_pk_fma_f32 v[236:237], v[142:143], v[142:143], v[236:237]
	v_pk_fma_f32 v[236:237], v[144:145], v[144:145], v[236:237]
	v_pk_fma_f32 v[236:237], v[146:147], v[146:147], v[236:237]
	v_pk_fma_f32 v[236:237], v[148:149], v[148:149], v[236:237]
	v_pk_fma_f32 v[236:237], v[150:151], v[150:151], v[236:237]
	v_pk_fma_f32 v[236:237], v[152:153], v[152:153], v[236:237]
	v_pk_fma_f32 v[236:237], v[154:155], v[154:155], v[236:237]
	v_pk_fma_f32 v[236:237], v[156:157], v[156:157], v[236:237]
	v_pk_fma_f32 v[236:237], v[158:159], v[158:159], v[236:237]
	v_add_f32_e32 v235, v236, v237
	s_nop 1
	v_add_f32_dpp v235, v235, v235 quad_perm:[1,0,3,2] row_mask:0xf bank_mask:0xf
	s_nop 1
	v_add_f32_dpp v235, v235, v235 quad_perm:[2,3,0,1] row_mask:0xf bank_mask:0xf
	s_nop 1
	v_add_f32_dpp v235, v235, v235 row_half_mirror row_mask:0xf bank_mask:0xf
	s_nop 1
	v_add_f32_dpp v235, v235, v235 row_mirror row_mask:0xf bank_mask:0xf
; __device__ __forceinline__ void ln_phase(const float* in, float* outf, bf16_t* outb, const float* g, const float* b, int wv0) {
;     ...
;   for (int row = wv; row < NTOK; row += nwv) {
;     f32x4 v[8]; float s = 0.f;
; #pragma unroll
;     for (int i = 0; i < 8; ++i) v[i] = vn[i];
;     if (row + nwv < NTOK) { const f32x4* ir = (const f32x4*)(in + (size_t)(row + nwv) * DM);
; #pragma unroll
;       for (int i = 0; i < 8; ++i) vn[i] = ir[i * 64 + lane]; }
; #pragma unroll
;     for (int i = 0; i < 8; ++i) s += v[i][0] + v[i][1] + v[i][2] + v[i][3];
;     s = wave_sum(s); const float mu = s * (1.0f / 2048.0f);
;     float sq = 0.f;
; #pragma unroll
;     for (int i = 0; i < 8; ++i) { v[i] -= mu; sq += v[i][0] * v[i][0] + v[i][1] * v[i][1] + v[i][2] * v[i][2] + v[i][3] * v[i][3]; }
;     sq = wave_sum(sq); const float rstd = __builtin_amdgcn_rsqf(sq * (1.0f / 2048.0f) + EPS);
; #pragma unroll
;     for (int i = 0; i < 8; ++i) {
;       const f32x4 y = v[i] * rstd * gg[i] + bb[i];
;       ((f32x4*)(outf + (size_t)row * DM))[i * 64 + lane] = y;
;       if (outb) { u32x2 w; w.x = pk2(y[0], y[1]); w.y = pk2(y[2], y[3]); ((u32x2*)(outb + (size_t)row * DM))[i * 64 + lane] = w; } }
;   }
	s_nop 0
	v_readlane_b32 s26, v235, 0
	v_readlane_b32 s27, v235, 16
	v_readlane_b32 s28, v235, 32
	v_readlane_b32 s29, v235, 48
	v_mov_b32_e32 v235, s26
	v_add_f32_e32 v235, s27, v235
	v_add_f32_e32 v235, s28, v235
	v_add_f32_e32 v235, s29, v235
	v_fmamk_f32 v235, v235, 0x3a000000, v246
	v_rsq_f32_e32 v217, v235
	s_lshl_b32 s23, s20, 13
	s_lshr_b32 s23, s23, 1
	s_add_u32 s30, s10, s23
	s_addc_u32 s31, s11, 0
	s_lshl_b32 s23, s20, 3
	s_add_u32 s2, s12, s23
	s_addc_u32 s3, s13, 0
	v_mov_b32_e32 v243, 0
	s_mov_b64 exec, 1
	global_store_dwordx2 v243, v[216:217], s[2:3]
	s_mov_b64 exec, -1
	v_pk_mul_f32 v[128:129], v[128:129], v[216:217] op_sel:[0,1] op_sel_hi:[1,1]
	v_pk_mul_f32 v[130:131], v[130:131], v[216:217] op_sel:[0,1] op_sel_hi:[1,1]
	v_pk_fma_f32 v[128:129], v[0:1], v[128:129], v[32:33]
	v_pk_fma_f32 v[130:131], v[2:3], v[130:131], v[34:35]
	v_pk_mul_f32 v[132:133], v[132:133], v[216:217] op_sel:[0,1] op_sel_hi:[1,1]
	v_pk_mul_f32 v[134:135], v[134:135], v[216:217] op_sel:[0,1] op_sel_hi:[1,1]
	v_pk_fma_f32 v[132:133], v[4:5], v[132:133], v[36:37]
	v_pk_fma_f32 v[134:135], v[6:7], v[134:135], v[38:39]
	v_cvt_pk_bf16_f32 v208, v128, v129
	v_cvt_pk_bf16_f32 v209, v130, v131
	v_cvt_pk_bf16_f32 v210, v132, v133
	v_cvt_pk_bf16_f32 v211, v134, v135
	global_store_dwordx4 v242, v[208:211], s[30:31]
	v_pk_mul_f32 v[136:137], v[136:137], v[216:217] op_sel:[0,1] op_sel_hi:[1,1]
	v_pk_mul_f32 v[138:139], v[138:139], v[216:217] op_sel:[0,1] op_sel_hi:[1,1]
	v_pk_fma_f32 v[136:137], v[8:9], v[136:137], v[40:41]
	v_pk_fma_f32 v[138:139], v[10:11], v[138:139], v[42:43]
	v_pk_mul_f32 v[140:141], v[140:141], v[216:217] op_sel:[0,1] op_sel_hi:[1,1]
	v_pk_mul_f32 v[142:143], v[142:143], v[216:217] op_sel:[0,1] op_sel_hi:[1,1]
	v_pk_fma_f32 v[140:141], v[12:13], v[140:141], v[44:45]
	v_pk_fma_f32 v[142:143], v[14:15], v[142:143], v[46:47]
	v_cvt_pk_bf16_f32 v212, v136, v137
	v_cvt_pk_bf16_f32 v213, v138, v139
	v_cvt_pk_bf16_f32 v214, v140, v141
	v_cvt_pk_bf16_f32 v215, v142, v143
	global_store_dwordx4 v242, v[212:215], s[30:31] offset:1024
	v_pk_mul_f32 v[144:145], v[144:145], v[216:217] op_sel:[0,1] op_sel_hi:[1,1]
	v_pk_mul_f32 v[146:147], v[146:147], v[216:217] op_sel:[0,1] op_sel_hi:[1,1]
	v_pk_fma_f32 v[144:145], v[16:17], v[144:145], v[48:49]
	v_pk_fma_f32 v[146:147], v[18:19], v[146:147], v[50:51]
	v_pk_mul_f32 v[148:149], v[148:149], v[216:217] op_sel:[0,1] op_sel_hi:[1,1]
	v_pk_mul_f32 v[150:151], v[150:151], v[216:217] op_sel:[0,1] op_sel_hi:[1,1]
	v_pk_fma_f32 v[148:149], v[20:21], v[148:149], v[52:53]
	v_pk_fma_f32 v[150:151], v[22:23], v[150:151], v[54:55]
	v_cvt_pk_bf16_f32 v208, v144, v145
	v_cvt_pk_bf16_f32 v209, v146, v147
	v_cvt_pk_bf16_f32 v210, v148, v149
	v_cvt_pk_bf16_f32 v211, v150, v151
	global_store_dwordx4 v242, v[208:211], s[30:31] offset:2048
	v_pk_mul_f32 v[152:153], v[152:153], v[216:217] op_sel:[0,1] op_sel_hi:[1,1]
	v_pk_mul_f32 v[154:155], v[154:155], v[216:217] op_sel:[0,1] op_sel_hi:[1,1]
	v_pk_fma_f32 v[152:153], v[24:25], v[152:153], v[56:57]
	v_pk_fma_f32 v[154:155], v[26:27], v[154:155], v[58:59]
	v_pk_mul_f32 v[156:157], v[156:157], v[216:217] op_sel:[0,1] op_sel_hi:[1,1]
	v_pk_mul_f32 v[158:159], v[158:159], v[216:217] op_sel:[0,1] op_sel_hi:[1,1]
	v_pk_fma_f32 v[156:157], v[28:29], v[156:157], v[60:61]
	v_pk_fma_f32 v[158:159], v[30:31], v[158:159], v[62:63]
	v_cvt_pk_bf16_f32 v212, v152, v153
	v_cvt_pk_bf16_f32 v213, v154, v155
	v_cvt_pk_bf16_f32 v214, v156, v157
	v_cvt_pk_bf16_f32 v215, v158, v159
	global_store_dwordx4 v242, v[212:215], s[30:31] offset:3072
	s_add_u32 s20, s20, s21
	s_cmp_ge_u32 s20, 0x4000
	s_cbranch_scc1 .Lln1_done
	s_branch .Lln1_loop
.Lln1_done:
	s_waitcnt vmcnt(0)
	v_mov_b32_e32 v97, 0

; __device__ __forceinline__ int otid(int wv0) { int t = (wv0 << 6) | olane(); asm volatile("" : "+v"(t)); return t; }
; __device__ __forceinline__ int obid() { int b = blockIdx.x; asm volatile("" : "+s"(b)); return b; }
; __device__ __forceinline__ int ogrid() { int g = gridDim.x; asm volatile("" : "+s"(g)); return g; }
; __device__ __forceinline__ void ln_phase(const float* in, float* outf, bf16_t* outb, const float* g, const float* b, int wv0) {
;   const int tid_ = otid(wv0); const int lane = tid_ & 63, wv = obid() * 8 + (tid_ >> 6), nwv = ogrid() * 8;
;   f32x4 gg[8], bb[8];
; #pragma unroll
;   for (int i = 0; i < 8; ++i) { gg[i] = ((const f32x4*)g)[i * 64 + lane]; bb[i] = ((const f32x4*)b)[i * 64 + lane]; }
;   f32x4 vn[8];
;   if (wv < NTOK) { const f32x4* ir = (const f32x4*)(in + (size_t)wv * DM);
; #pragma unroll
;     for (int i = 0; i < 8; ++i) vn[i] = ir[i * 64 + lane]; }
;   for (int row = wv; row < NTOK; row += nwv) {
;     f32x4 v[8]; float s = 0.f;
; #pragma unroll
;     for (int i = 0; i < 8; ++i) v[i] = vn[i];
;     if (row + nwv < NTOK) { const f32x4* ir = (const f32x4*)(in + (size_t)(row + nwv) * DM);
; #pragma unroll
;       for (int i = 0; i < 8; ++i) vn[i] = ir[i * 64 + lane]; }
; #pragma unroll
;     for (int i = 0; i < 8; ++i) s += v[i][0] + v[i][1] + v[i][2] + v[i][3];
;     s = wave_sum(s); const float mu = s * (1.0f / 2048.0f);
.LBB0_1490:
	s_mov_b32 s0, -1
	s_lshl_b32 s22, s53, 6
	v_mbcnt_lo_u32_b32 v0, s0, 0
	v_mbcnt_hi_u32_b32 v0, s0, v0
	v_or_b32_e32 v0, s22, v0
	s_mov_b32 s1, s82
	v_ashrrev_i32_e32 v1, 6, v0
	s_mov_b32 s0, s60
	v_lshl_add_u32 v130, s1, 3, v1
	v_cmp_gt_i32_e32 vcc, s61, v130
	s_and_saveexec_b64 s[10:11], vcc
	s_cbranch_execz .LBB0_1511
	s_waitcnt lgkmcnt(0)
	s_lshl_b32 s0, s66, 13
	s_add_u32 s16, s4, s0
	s_addc_u32 s17, s5, 0
	s_add_u32 s14, s6, s0
	s_addc_u32 s15, s7, 0
	s_cmp_eq_u32 s66, 1
	s_cbranch_scc1 .Lln2_last
	v_mbcnt_lo_u32_b32 v243, -1, 0
	v_mbcnt_hi_u32_b32 v243, -1, v243
	v_lshlrev_b32_e32 v240, 5, v243
	v_add_u32_e32 v241, 0x1000, v240
	v_lshlrev_b32_e32 v242, 4, v243
	s_lshl_b32 s20, s82, 3
	s_add_u32 s20, s20, s53
	s_lshl_b32 s21, s60, 3
	global_load_dwordx4 v[0:3], v240, s[16:17]
	global_load_dwordx4 v[4:7], v240, s[16:17] offset:16
	global_load_dwordx4 v[8:11], v240, s[16:17] offset:2048
	global_load_dwordx4 v[12:15], v240, s[16:17] offset:2064
	global_load_dwordx4 v[16:19], v241, s[16:17]
	global_load_dwordx4 v[20:23], v241, s[16:17] offset:16
	global_load_dwordx4 v[24:27], v241, s[16:17] offset:2048
	global_load_dwordx4 v[28:31], v241, s[16:17] offset:2064
	global_load_dwordx4 v[32:35], v240, s[14:15]
	global_load_dwordx4 v[36:39], v240, s[14:15] offset:16
	global_load_dwordx4 v[40:43], v240, s[14:15] offset:2048
	global_load_dwordx4 v[44:47], v240, s[14:15] offset:2064
	global_load_dwordx4 v[48:51], v241, s[14:15]
	global_load_dwordx4 v[52:55], v241, s[14:15] offset:16
	global_load_dwordx4 v[56:59], v241, s[14:15] offset:2048
	global_load_dwordx4 v[60:63], v241, s[14:15] offset:2064
	s_mov_b32 s23, s20
	s_min_u32 s23, s23, 0x3fff
	s_lshl_b32 s23, s23, 13
	s_add_u32 s24, s12, s23
	s_addc_u32 s25, s13, 0
	global_load_dwordx4 v[64:67], v240, s[24:25]
	global_load_dwordx4 v[68:71], v240, s[24:25] offset:16
	global_load_dwordx4 v[72:75], v240, s[24:25] offset:2048
	global_load_dwordx4 v[76:79], v240, s[24:25] offset:2064
	global_load_dwordx4 v[80:83], v241, s[24:25]
	global_load_dwordx4 v[84:87], v241, s[24:25] offset:16
	global_load_dwordx4 v[88:91], v241, s[24:25] offset:2048
	global_load_dwordx4 v[92:95], v241, s[24:25] offset:2064
	s_mul_i32 s23, s21, 1
	s_add_u32 s23, s20, s23
	s_min_u32 s23, s23, 0x3fff
	s_lshl_b32 s23, s23, 13
	s_add_u32 s24, s12, s23
	s_addc_u32 s25, s13, 0
	global_load_dwordx4 v[96:99], v240, s[24:25]
	global_load_dwordx4 v[100:103], v240, s[24:25] offset:16
	global_load_dwordx4 v[104:107], v240, s[24:25] offset:2048
	global_load_dwordx4 v[108:111], v240, s[24:25] offset:2064
	global_load_dwordx4 v[112:115], v241, s[24:25]
	global_load_dwordx4 v[116:119], v241, s[24:25] offset:16
	global_load_dwordx4 v[120:123], v241, s[24:25] offset:2048
	global_load_dwordx4 v[124:127], v241, s[24:25] offset:2064
	s_mul_i32 s23, s21, 2
	s_add_u32 s23, s20, s23
	s_min_u32 s23, s23, 0x3fff
	s_lshl_b32 s23, s23, 13
	s_add_u32 s24, s12, s23
	s_addc_u32 s25, s13, 0
	global_load_dwordx4 v[128:131], v240, s[24:25]
	global_load_dwordx4 v[132:135], v240, s[24:25] offset:16
	global_load_dwordx4 v[136:139], v240, s[24:25] offset:2048
	global_load_dwordx4 v[140:143], v240, s[24:25] offset:2064
	global_load_dwordx4 v[144:147], v241, s[24:25]
	global_load_dwordx4 v[148:151], v241, s[24:25] offset:16
	global_load_dwordx4 v[152:155], v241, s[24:25] offset:2048
	global_load_dwordx4 v[156:159], v241, s[24:25] offset:2064
	s_mul_i32 s23, s21, 3
	s_add_u32 s23, s20, s23
	s_min_u32 s23, s23, 0x3fff
	s_lshl_b32 s23, s23, 13
	s_add_u32 s24, s12, s23
	s_addc_u32 s25, s13, 0
	global_load_dwordx4 v[176:179], v240, s[24:25]
	global_load_dwordx4 v[180:183], v240, s[24:25] offset:16
	global_load_dwordx4 v[184:187], v240, s[24:25] offset:2048
	global_load_dwordx4 v[188:191], v240, s[24:25] offset:2064
	global_load_dwordx4 v[192:195], v241, s[24:25]
	global_load_dwordx4 v[196:199], v241, s[24:25] offset:16
	global_load_dwordx4 v[200:203], v241, s[24:25] offset:2048
	global_load_dwordx4 v[204:207], v241, s[24:25] offset:2064
	s_waitcnt vmcnt(24)
	v_pk_add_f32 v[236:237], v[64:65], v[66:67]
	v_pk_add_f32 v[236:237], v[236:237], v[68:69]
	v_pk_add_f32 v[236:237], v[236:237], v[70:71]
	v_pk_add_f32 v[236:237], v[236:237], v[72:73]
	v_pk_add_f32 v[236:237], v[236:237], v[74:75]
	v_pk_add_f32 v[236:237], v[236:237], v[76:77]
	v_pk_add_f32 v[236:237], v[236:237], v[78:79]
	v_pk_add_f32 v[236:237], v[236:237], v[80:81]
	v_pk_add_f32 v[236:237], v[236:237], v[82:83]
	v_pk_add_f32 v[236:237], v[236:237], v[84:85]
	v_pk_add_f32 v[236:237], v[236:237], v[86:87]
	v_pk_add_f32 v[236:237], v[236:237], v[88:89]
	v_pk_add_f32 v[236:237], v[236:237], v[90:91]
	v_pk_add_f32 v[236:237], v[236:237], v[92:93]
	v_pk_add_f32 v[236:237], v[236:237], v[94:95]
	v_add_f32_e32 v234, v236, v237
	s_nop 1
	v_add_f32_dpp v234, v234, v234 quad_perm:[1,0,3,2] row_mask:0xf bank_mask:0xf
	s_nop 1
	v_add_f32_dpp v234, v234, v234 quad_perm:[2,3,0,1] row_mask:0xf bank_mask:0xf
	s_nop 1
	v_add_f32_dpp v234, v234, v234 row_half_mirror row_mask:0xf bank_mask:0xf
	s_nop 1
	v_add_f32_dpp v234, v234, v234 row_mirror row_mask:0xf bank_mask:0xf
	s_nop 0
	v_readlane_b32 s26, v234, 0
	v_readlane_b32 s27, v234, 16
	v_readlane_b32 s28, v234, 32
	v_readlane_b32 s29, v234, 48
	v_mov_b32_e32 v234, s26
	v_add_f32_e32 v234, s27, v234
	v_add_f32_e32 v234, s28, v234
	v_add_f32_e32 v234, s29, v234
	v_mul_f32_e32 v216, 0xba000000, v234
	v_pk_add_f32 v[64:65], v[64:65], v[216:217] op_sel_hi:[1,0]
	v_pk_add_f32 v[66:67], v[66:67], v[216:217] op_sel_hi:[1,0]
	v_pk_add_f32 v[68:69], v[68:69], v[216:217] op_sel_hi:[1,0]
	v_pk_add_f32 v[70:71], v[70:71], v[216:217] op_sel_hi:[1,0]
; __device__ __forceinline__ void ln_phase(const float* in, float* outf, bf16_t* outb, const float* g, const float* b, int wv0) {
;     ...
;     s = wave_sum(s); const float mu = s * (1.0f / 2048.0f);
;     float sq = 0.f;
; #pragma unroll
;     for (int i = 0; i < 8; ++i) { v[i] -= mu; sq += v[i][0] * v[i][0] + v[i][1] * v[i][1] + v[i][2] * v[i][2] + v[i][3] * v[i][3]; }
;     sq = wave_sum(sq); const float rstd = __builtin_amdgcn_rsqf(sq * (1.0f / 2048.0f) + EPS);
; #pragma unroll
;     for (int i = 0; i < 8; ++i) {
;       const f32x4 y = v[i] * rstd * gg[i] + bb[i];
;       ((f32x4*)(outf + (size_t)row * DM))[i * 64 + lane] = y;
;       if (outb) { u32x2 w; w.x = pk2(y[0], y[1]); w.y = pk2(y[2], y[3]); ((u32x2*)(outb + (size_t)row * DM))[i * 64 + lane] = w; } }
	v_pk_add_f32 v[72:73], v[72:73], v[216:217] op_sel_hi:[1,0]
	v_pk_add_f32 v[74:75], v[74:75], v[216:217] op_sel_hi:[1,0]
	v_pk_add_f32 v[76:77], v[76:77], v[216:217] op_sel_hi:[1,0]
	v_pk_add_f32 v[78:79], v[78:79], v[216:217] op_sel_hi:[1,0]
	v_pk_add_f32 v[80:81], v[80:81], v[216:217] op_sel_hi:[1,0]
	v_pk_add_f32 v[82:83], v[82:83], v[216:217] op_sel_hi:[1,0]
	v_pk_add_f32 v[84:85], v[84:85], v[216:217] op_sel_hi:[1,0]
	v_pk_add_f32 v[86:87], v[86:87], v[216:217] op_sel_hi:[1,0]
	v_pk_add_f32 v[88:89], v[88:89], v[216:217] op_sel_hi:[1,0]
	v_pk_add_f32 v[90:91], v[90:91], v[216:217] op_sel_hi:[1,0]
	v_pk_add_f32 v[92:93], v[92:93], v[216:217] op_sel_hi:[1,0]
	v_pk_add_f32 v[94:95], v[94:95], v[216:217] op_sel_hi:[1,0]
	v_pk_mul_f32 v[236:237], v[64:65], v[64:65]
	v_pk_fma_f32 v[236:237], v[66:67], v[66:67], v[236:237]
	v_pk_fma_f32 v[236:237], v[68:69], v[68:69], v[236:237]
	v_pk_fma_f32 v[236:237], v[70:71], v[70:71], v[236:237]
	v_pk_fma_f32 v[236:237], v[72:73], v[72:73], v[236:237]
	v_pk_fma_f32 v[236:237], v[74:75], v[74:75], v[236:237]
	v_pk_fma_f32 v[236:237], v[76:77], v[76:77], v[236:237]
	v_pk_fma_f32 v[236:237], v[78:79], v[78:79], v[236:237]
	v_pk_fma_f32 v[236:237], v[80:81], v[80:81], v[236:237]
	v_pk_fma_f32 v[236:237], v[82:83], v[82:83], v[236:237]
	v_pk_fma_f32 v[236:237], v[84:85], v[84:85], v[236:237]
	v_pk_fma_f32 v[236:237], v[86:87], v[86:87], v[236:237]
	v_pk_fma_f32 v[236:237], v[88:89], v[88:89], v[236:237]
	v_pk_fma_f32 v[236:237], v[90:91], v[90:91], v[236:237]
	v_pk_fma_f32 v[236:237], v[92:93], v[92:93], v[236:237]
	v_pk_fma_f32 v[236:237], v[94:95], v[94:95], v[236:237]
	v_add_f32_e32 v235, v236, v237
	s_nop 1
	v_add_f32_dpp v235, v235, v235 quad_perm:[1,0,3,2] row_mask:0xf bank_mask:0xf
	s_nop 1
	v_add_f32_dpp v235, v235, v235 quad_perm:[2,3,0,1] row_mask:0xf bank_mask:0xf
	s_nop 1
	v_add_f32_dpp v235, v235, v235 row_half_mirror row_mask:0xf bank_mask:0xf
	s_nop 1
	v_add_f32_dpp v235, v235, v235 row_mirror row_mask:0xf bank_mask:0xf
	s_nop 0
	v_readlane_b32 s26, v235, 0
	v_readlane_b32 s27, v235, 16
	v_readlane_b32 s28, v235, 32
	v_readlane_b32 s29, v235, 48
	v_mov_b32_e32 v235, s26
	v_add_f32_e32 v235, s27, v235
	v_add_f32_e32 v235, s28, v235
	v_add_f32_e32 v235, s29, v235
	v_fmamk_f32 v235, v235, 0x3a000000, v246
	v_rsq_f32_e32 v217, v235
	s_lshl_b32 s23, s20, 13
	s_add_u32 s28, s18, s23
	s_addc_u32 s29, s19, 0
	s_lshr_b32 s23, s23, 1
	s_add_u32 s30, s2, s23
	s_addc_u32 s31, s3, 0
	v_pk_mul_f32 v[64:65], v[64:65], v[216:217] op_sel:[0,1] op_sel_hi:[1,1]
	v_pk_mul_f32 v[66:67], v[66:67], v[216:217] op_sel:[0,1] op_sel_hi:[1,1]
	v_pk_fma_f32 v[64:65], v[0:1], v[64:65], v[32:33]
	v_pk_fma_f32 v[66:67], v[2:3], v[66:67], v[34:35]
	v_pk_mul_f32 v[68:69], v[68:69], v[216:217] op_sel:[0,1] op_sel_hi:[1,1]
	v_pk_mul_f32 v[70:71], v[70:71], v[216:217] op_sel:[0,1] op_sel_hi:[1,1]
	v_pk_fma_f32 v[68:69], v[4:5], v[68:69], v[36:37]
	v_pk_fma_f32 v[70:71], v[6:7], v[70:71], v[38:39]
	v_cvt_pk_bf16_f32 v208, v64, v65
	v_cvt_pk_bf16_f32 v209, v66, v67
	v_cvt_pk_bf16_f32 v210, v68, v69
	v_cvt_pk_bf16_f32 v211, v70, v71
	global_store_dwordx4 v240, v[64:67], s[28:29]
	global_store_dwordx4 v240, v[68:71], s[28:29] offset:16
	global_store_dwordx4 v242, v[208:211], s[30:31]
	v_pk_mul_f32 v[72:73], v[72:73], v[216:217] op_sel:[0,1] op_sel_hi:[1,1]
	v_pk_mul_f32 v[74:75], v[74:75], v[216:217] op_sel:[0,1] op_sel_hi:[1,1]
	v_pk_fma_f32 v[72:73], v[8:9], v[72:73], v[40:41]
	v_pk_fma_f32 v[74:75], v[10:11], v[74:75], v[42:43]
	v_pk_mul_f32 v[76:77], v[76:77], v[216:217] op_sel:[0,1] op_sel_hi:[1,1]
	v_pk_mul_f32 v[78:79], v[78:79], v[216:217] op_sel:[0,1] op_sel_hi:[1,1]
	v_pk_fma_f32 v[76:77], v[12:13], v[76:77], v[44:45]
	v_pk_fma_f32 v[78:79], v[14:15], v[78:79], v[46:47]
	v_cvt_pk_bf16_f32 v212, v72, v73
	v_cvt_pk_bf16_f32 v213, v74, v75
	v_cvt_pk_bf16_f32 v214, v76, v77
	v_cvt_pk_bf16_f32 v215, v78, v79
	global_store_dwordx4 v240, v[72:75], s[28:29] offset:2048
	global_store_dwordx4 v240, v[76:79], s[28:29] offset:2064
	global_store_dwordx4 v242, v[212:215], s[30:31] offset:1024
	v_pk_mul_f32 v[80:81], v[80:81], v[216:217] op_sel:[0,1] op_sel_hi:[1,1]
	v_pk_mul_f32 v[82:83], v[82:83], v[216:217] op_sel:[0,1] op_sel_hi:[1,1]
	v_pk_fma_f32 v[80:81], v[16:17], v[80:81], v[48:49]
	v_pk_fma_f32 v[82:83], v[18:19], v[82:83], v[50:51]
	v_pk_mul_f32 v[84:85], v[84:85], v[216:217] op_sel:[0,1] op_sel_hi:[1,1]
	v_pk_mul_f32 v[86:87], v[86:87], v[216:217] op_sel:[0,1] op_sel_hi:[1,1]
	v_pk_fma_f32 v[84:85], v[20:21], v[84:85], v[52:53]
	v_pk_fma_f32 v[86:87], v[22:23], v[86:87], v[54:55]
	v_cvt_pk_bf16_f32 v208, v80, v81
	v_cvt_pk_bf16_f32 v209, v82, v83
	v_cvt_pk_bf16_f32 v210, v84, v85
	v_cvt_pk_bf16_f32 v211, v86, v87
	global_store_dwordx4 v241, v[80:83], s[28:29]
	global_store_dwordx4 v241, v[84:87], s[28:29] offset:16
	global_store_dwordx4 v242, v[208:211], s[30:31] offset:2048
	v_pk_mul_f32 v[88:89], v[88:89], v[216:217] op_sel:[0,1] op_sel_hi:[1,1]
	v_pk_mul_f32 v[90:91], v[90:91], v[216:217] op_sel:[0,1] op_sel_hi:[1,1]
	v_pk_fma_f32 v[88:89], v[24:25], v[88:89], v[56:57]
	v_pk_fma_f32 v[90:91], v[26:27], v[90:91], v[58:59]
	v_pk_mul_f32 v[92:93], v[92:93], v[216:217] op_sel:[0,1] op_sel_hi:[1,1]
	v_pk_mul_f32 v[94:95], v[94:95], v[216:217] op_sel:[0,1] op_sel_hi:[1,1]
	v_pk_fma_f32 v[92:93], v[28:29], v[92:93], v[60:61]
	v_pk_fma_f32 v[94:95], v[30:31], v[94:95], v[62:63]
	v_cvt_pk_bf16_f32 v212, v88, v89
	v_cvt_pk_bf16_f32 v213, v90, v91
	v_cvt_pk_bf16_f32 v214, v92, v93
	v_cvt_pk_bf16_f32 v215, v94, v95
	global_store_dwordx4 v241, v[88:91], s[28:29] offset:2048
	global_store_dwordx4 v241, v[92:95], s[28:29] offset:2064
	global_store_dwordx4 v242, v[212:215], s[30:31] offset:3072
	s_add_u32 s20, s20, s21
	s_cmp_ge_u32 s20, 0x4000
	s_cbranch_scc1 .Lln2a_done
; __device__ __forceinline__ void ln_phase(const float* in, float* outf, bf16_t* outb, const float* g, const float* b, int wv0) {
;     ...
;   for (int row = wv; row < NTOK; row += nwv) {
;     f32x4 v[8]; float s = 0.f;
; #pragma unroll
;     for (int i = 0; i < 8; ++i) v[i] = vn[i];
;     if (row + nwv < NTOK) { const f32x4* ir = (const f32x4*)(in + (size_t)(row + nwv) * DM);
; #pragma unroll
;       for (int i = 0; i < 8; ++i) vn[i] = ir[i * 64 + lane]; }
; #pragma unroll
;     for (int i = 0; i < 8; ++i) s += v[i][0] + v[i][1] + v[i][2] + v[i][3];
;     s = wave_sum(s); const float mu = s * (1.0f / 2048.0f);
;     float sq = 0.f;
; #pragma unroll
;     for (int i = 0; i < 8; ++i) { v[i] -= mu; sq += v[i][0] * v[i][0] + v[i][1] * v[i][1] + v[i][2] * v[i][2] + v[i][3] * v[i][3]; }
;     sq = wave_sum(sq); const float rstd = __builtin_amdgcn_rsqf(sq * (1.0f / 2048.0f) + EPS);
; #pragma unroll
;     for (int i = 0; i < 8; ++i) {
;       const f32x4 y = v[i] * rstd * gg[i] + bb[i];
;       ((f32x4*)(outf + (size_t)row * DM))[i * 64 + lane] = y;
;       if (outb) { u32x2 w; w.x = pk2(y[0], y[1]); w.y = pk2(y[2], y[3]); ((u32x2*)(outb + (size_t)row * DM))[i * 64 + lane] = w; } }
	s_mul_i32 s23, s21, 3
	s_add_u32 s23, s20, s23
	s_min_u32 s23, s23, 0x3fff
	s_lshl_b32 s23, s23, 13
	s_add_u32 s24, s12, s23
	s_addc_u32 s25, s13, 0
	global_load_dwordx4 v[64:67], v240, s[24:25]
	global_load_dwordx4 v[68:71], v240, s[24:25] offset:16
	global_load_dwordx4 v[72:75], v240, s[24:25] offset:2048
	global_load_dwordx4 v[76:79], v240, s[24:25] offset:2064
	global_load_dwordx4 v[80:83], v241, s[24:25]
	global_load_dwordx4 v[84:87], v241, s[24:25] offset:16
	global_load_dwordx4 v[88:91], v241, s[24:25] offset:2048
	global_load_dwordx4 v[92:95], v241, s[24:25] offset:2064
	s_waitcnt vmcnt(36)
	v_pk_add_f32 v[236:237], v[96:97], v[98:99]
	v_pk_add_f32 v[236:237], v[236:237], v[100:101]
	v_pk_add_f32 v[236:237], v[236:237], v[102:103]
	v_pk_add_f32 v[236:237], v[236:237], v[104:105]
	v_pk_add_f32 v[236:237], v[236:237], v[106:107]
	v_pk_add_f32 v[236:237], v[236:237], v[108:109]
	v_pk_add_f32 v[236:237], v[236:237], v[110:111]
	v_pk_add_f32 v[236:237], v[236:237], v[112:113]
	v_pk_add_f32 v[236:237], v[236:237], v[114:115]
	v_pk_add_f32 v[236:237], v[236:237], v[116:117]
	v_pk_add_f32 v[236:237], v[236:237], v[118:119]
	v_pk_add_f32 v[236:237], v[236:237], v[120:121]
	v_pk_add_f32 v[236:237], v[236:237], v[122:123]
	v_pk_add_f32 v[236:237], v[236:237], v[124:125]
	v_pk_add_f32 v[236:237], v[236:237], v[126:127]
	v_add_f32_e32 v234, v236, v237
	s_nop 1
	v_add_f32_dpp v234, v234, v234 quad_perm:[1,0,3,2] row_mask:0xf bank_mask:0xf
	s_nop 1
	v_add_f32_dpp v234, v234, v234 quad_perm:[2,3,0,1] row_mask:0xf bank_mask:0xf
	s_nop 1
	v_add_f32_dpp v234, v234, v234 row_half_mirror row_mask:0xf bank_mask:0xf
	s_nop 1
	v_add_f32_dpp v234, v234, v234 row_mirror row_mask:0xf bank_mask:0xf
	s_nop 0
	v_readlane_b32 s26, v234, 0
	v_readlane_b32 s27, v234, 16
	v_readlane_b32 s28, v234, 32
	v_readlane_b32 s29, v234, 48
	v_mov_b32_e32 v234, s26
	v_add_f32_e32 v234, s27, v234
	v_add_f32_e32 v234, s28, v234
	v_add_f32_e32 v234, s29, v234
	v_mul_f32_e32 v216, 0xba000000, v234
	v_pk_add_f32 v[96:97], v[96:97], v[216:217] op_sel_hi:[1,0]
	v_pk_add_f32 v[98:99], v[98:99], v[216:217] op_sel_hi:[1,0]
	v_pk_add_f32 v[100:101], v[100:101], v[216:217] op_sel_hi:[1,0]
	v_pk_add_f32 v[102:103], v[102:103], v[216:217] op_sel_hi:[1,0]
	v_pk_add_f32 v[104:105], v[104:105], v[216:217] op_sel_hi:[1,0]
	v_pk_add_f32 v[106:107], v[106:107], v[216:217] op_sel_hi:[1,0]
	v_pk_add_f32 v[108:109], v[108:109], v[216:217] op_sel_hi:[1,0]
	v_pk_add_f32 v[110:111], v[110:111], v[216:217] op_sel_hi:[1,0]
	v_pk_add_f32 v[112:113], v[112:113], v[216:217] op_sel_hi:[1,0]
	v_pk_add_f32 v[114:115], v[114:115], v[216:217] op_sel_hi:[1,0]
	v_pk_add_f32 v[116:117], v[116:117], v[216:217] op_sel_hi:[1,0]
	v_pk_add_f32 v[118:119], v[118:119], v[216:217] op_sel_hi:[1,0]
	v_pk_add_f32 v[120:121], v[120:121], v[216:217] op_sel_hi:[1,0]
	v_pk_add_f32 v[122:123], v[122:123], v[216:217] op_sel_hi:[1,0]
	v_pk_add_f32 v[124:125], v[124:125], v[216:217] op_sel_hi:[1,0]
	v_pk_add_f32 v[126:127], v[126:127], v[216:217] op_sel_hi:[1,0]
	v_pk_mul_f32 v[236:237], v[96:97], v[96:97]
	v_pk_fma_f32 v[236:237], v[98:99], v[98:99], v[236:237]
	v_pk_fma_f32 v[236:237], v[100:101], v[100:101], v[236:237]
	v_pk_fma_f32 v[236:237], v[102:103], v[102:103], v[236:237]
	v_pk_fma_f32 v[236:237], v[104:105], v[104:105], v[236:237]
	v_pk_fma_f32 v[236:237], v[106:107], v[106:107], v[236:237]
	v_pk_fma_f32 v[236:237], v[108:109], v[108:109], v[236:237]
	v_pk_fma_f32 v[236:237], v[110:111], v[110:111], v[236:237]
	v_pk_fma_f32 v[236:237], v[112:113], v[112:113], v[236:237]
	v_pk_fma_f32 v[236:237], v[114:115], v[114:115], v[236:237]
	v_pk_fma_f32 v[236:237], v[116:117], v[116:117], v[236:237]
	v_pk_fma_f32 v[236:237], v[118:119], v[118:119], v[236:237]
	v_pk_fma_f32 v[236:237], v[120:121], v[120:121], v[236:237]
	v_pk_fma_f32 v[236:237], v[122:123], v[122:123], v[236:237]
	v_pk_fma_f32 v[236:237], v[124:125], v[124:125], v[236:237]
	v_pk_fma_f32 v[236:237], v[126:127], v[126:127], v[236:237]
	v_add_f32_e32 v235, v236, v237
	s_nop 1
	v_add_f32_dpp v235, v235, v235 quad_perm:[1,0,3,2] row_mask:0xf bank_mask:0xf
	s_nop 1
	v_add_f32_dpp v235, v235, v235 quad_perm:[2,3,0,1] row_mask:0xf bank_mask:0xf
	s_nop 1
	v_add_f32_dpp v235, v235, v235 row_half_mirror row_mask:0xf bank_mask:0xf
	s_nop 1
	v_add_f32_dpp v235, v235, v235 row_mirror row_mask:0xf bank_mask:0xf
	s_nop 0
	v_readlane_b32 s26, v235, 0
	v_readlane_b32 s27, v235, 16
	v_readlane_b32 s28, v235, 32
	v_readlane_b32 s29, v235, 48
	v_mov_b32_e32 v235, s26
	v_add_f32_e32 v235, s27, v235
	v_add_f32_e32 v235, s28, v235
	v_add_f32_e32 v235, s29, v235
	v_fmamk_f32 v235, v235, 0x3a000000, v246
	v_rsq_f32_e32 v217, v235
	s_lshl_b32 s23, s20, 13
	s_add_u32 s28, s18, s23
	s_addc_u32 s29, s19, 0
	s_lshr_b32 s23, s23, 1
	s_add_u32 s30, s2, s23
	s_addc_u32 s31, s3, 0
	v_pk_mul_f32 v[96:97], v[96:97], v[216:217] op_sel:[0,1] op_sel_hi:[1,1]
	v_pk_mul_f32 v[98:99], v[98:99], v[216:217] op_sel:[0,1] op_sel_hi:[1,1]
	v_pk_fma_f32 v[96:97], v[0:1], v[96:97], v[32:33]
	v_pk_fma_f32 v[98:99], v[2:3], v[98:99], v[34:35]
	v_pk_mul_f32 v[100:101], v[100:101], v[216:217] op_sel:[0,1] op_sel_hi:[1,1]
	v_pk_mul_f32 v[102:103], v[102:103], v[216:217] op_sel:[0,1] op_sel_hi:[1,1]
	v_pk_fma_f32 v[100:101], v[4:5], v[100:101], v[36:37]
	v_pk_fma_f32 v[102:103], v[6:7], v[102:103], v[38:39]
	v_cvt_pk_bf16_f32 v208, v96, v97
	v_cvt_pk_bf16_f32 v209, v98, v99
	v_cvt_pk_bf16_f32 v210, v100, v101
	v_cvt_pk_bf16_f32 v211, v102, v103
	global_store_dwordx4 v240, v[96:99], s[28:29]
	global_store_dwordx4 v240, v[100:103], s[28:29] offset:16
	global_store_dwordx4 v242, v[208:211], s[30:31]
; __device__ __forceinline__ void ln_phase(const float* in, float* outf, bf16_t* outb, const float* g, const float* b, int wv0) {
;     ...
;   for (int row = wv; row < NTOK; row += nwv) {
;     f32x4 v[8]; float s = 0.f;
; #pragma unroll
;     for (int i = 0; i < 8; ++i) v[i] = vn[i];
;     if (row + nwv < NTOK) { const f32x4* ir = (const f32x4*)(in + (size_t)(row + nwv) * DM);
; #pragma unroll
;       for (int i = 0; i < 8; ++i) vn[i] = ir[i * 64 + lane]; }
; #pragma unroll
;     for (int i = 0; i < 8; ++i) s += v[i][0] + v[i][1] + v[i][2] + v[i][3];
;     s = wave_sum(s); const float mu = s * (1.0f / 2048.0f);
;     float sq = 0.f;
; #pragma unroll
;     for (int i = 0; i < 8; ++i) { v[i] -= mu; sq += v[i][0] * v[i][0] + v[i][1] * v[i][1] + v[i][2] * v[i][2] + v[i][3] * v[i][3]; }
	v_pk_mul_f32 v[104:105], v[104:105], v[216:217] op_sel:[0,1] op_sel_hi:[1,1]
	v_pk_mul_f32 v[106:107], v[106:107], v[216:217] op_sel:[0,1] op_sel_hi:[1,1]
	v_pk_fma_f32 v[104:105], v[8:9], v[104:105], v[40:41]
	v_pk_fma_f32 v[106:107], v[10:11], v[106:107], v[42:43]
	v_pk_mul_f32 v[108:109], v[108:109], v[216:217] op_sel:[0,1] op_sel_hi:[1,1]
	v_pk_mul_f32 v[110:111], v[110:111], v[216:217] op_sel:[0,1] op_sel_hi:[1,1]
	v_pk_fma_f32 v[108:109], v[12:13], v[108:109], v[44:45]
	v_pk_fma_f32 v[110:111], v[14:15], v[110:111], v[46:47]
	v_cvt_pk_bf16_f32 v212, v104, v105
	v_cvt_pk_bf16_f32 v213, v106, v107
	v_cvt_pk_bf16_f32 v214, v108, v109
	v_cvt_pk_bf16_f32 v215, v110, v111
	global_store_dwordx4 v240, v[104:107], s[28:29] offset:2048
	global_store_dwordx4 v240, v[108:111], s[28:29] offset:2064
	global_store_dwordx4 v242, v[212:215], s[30:31] offset:1024
	v_pk_mul_f32 v[112:113], v[112:113], v[216:217] op_sel:[0,1] op_sel_hi:[1,1]
	v_pk_mul_f32 v[114:115], v[114:115], v[216:217] op_sel:[0,1] op_sel_hi:[1,1]
	v_pk_fma_f32 v[112:113], v[16:17], v[112:113], v[48:49]
	v_pk_fma_f32 v[114:115], v[18:19], v[114:115], v[50:51]
	v_pk_mul_f32 v[116:117], v[116:117], v[216:217] op_sel:[0,1] op_sel_hi:[1,1]
	v_pk_mul_f32 v[118:119], v[118:119], v[216:217] op_sel:[0,1] op_sel_hi:[1,1]
	v_pk_fma_f32 v[116:117], v[20:21], v[116:117], v[52:53]
	v_pk_fma_f32 v[118:119], v[22:23], v[118:119], v[54:55]
	v_cvt_pk_bf16_f32 v208, v112, v113
	v_cvt_pk_bf16_f32 v209, v114, v115
	v_cvt_pk_bf16_f32 v210, v116, v117
	v_cvt_pk_bf16_f32 v211, v118, v119
	global_store_dwordx4 v241, v[112:115], s[28:29]
	global_store_dwordx4 v241, v[116:119], s[28:29] offset:16
	global_store_dwordx4 v242, v[208:211], s[30:31] offset:2048
	v_pk_mul_f32 v[120:121], v[120:121], v[216:217] op_sel:[0,1] op_sel_hi:[1,1]
	v_pk_mul_f32 v[122:123], v[122:123], v[216:217] op_sel:[0,1] op_sel_hi:[1,1]
	v_pk_fma_f32 v[120:121], v[24:25], v[120:121], v[56:57]
	v_pk_fma_f32 v[122:123], v[26:27], v[122:123], v[58:59]
	v_pk_mul_f32 v[124:125], v[124:125], v[216:217] op_sel:[0,1] op_sel_hi:[1,1]
	v_pk_mul_f32 v[126:127], v[126:127], v[216:217] op_sel:[0,1] op_sel_hi:[1,1]
	v_pk_fma_f32 v[124:125], v[28:29], v[124:125], v[60:61]
	v_pk_fma_f32 v[126:127], v[30:31], v[126:127], v[62:63]
	v_cvt_pk_bf16_f32 v212, v120, v121
	v_cvt_pk_bf16_f32 v213, v122, v123
	v_cvt_pk_bf16_f32 v214, v124, v125
	v_cvt_pk_bf16_f32 v215, v126, v127
	global_store_dwordx4 v241, v[120:123], s[28:29] offset:2048
	global_store_dwordx4 v241, v[124:127], s[28:29] offset:2064
	global_store_dwordx4 v242, v[212:215], s[30:31] offset:3072
	s_add_u32 s20, s20, s21
	s_cmp_ge_u32 s20, 0x4000
	s_cbranch_scc1 .Lln2a_done
	s_mul_i32 s23, s21, 3
	s_add_u32 s23, s20, s23
	s_min_u32 s23, s23, 0x3fff
	s_lshl_b32 s23, s23, 13
	s_add_u32 s24, s12, s23
	s_addc_u32 s25, s13, 0
	global_load_dwordx4 v[96:99], v240, s[24:25]
	global_load_dwordx4 v[100:103], v240, s[24:25] offset:16
	global_load_dwordx4 v[104:107], v240, s[24:25] offset:2048
	global_load_dwordx4 v[108:111], v240, s[24:25] offset:2064
	global_load_dwordx4 v[112:115], v241, s[24:25]
	global_load_dwordx4 v[116:119], v241, s[24:25] offset:16
	global_load_dwordx4 v[120:123], v241, s[24:25] offset:2048
	global_load_dwordx4 v[124:127], v241, s[24:25] offset:2064
	s_waitcnt vmcnt(48)
	v_pk_add_f32 v[236:237], v[128:129], v[130:131]
	v_pk_add_f32 v[236:237], v[236:237], v[132:133]
	v_pk_add_f32 v[236:237], v[236:237], v[134:135]
	v_pk_add_f32 v[236:237], v[236:237], v[136:137]
	v_pk_add_f32 v[236:237], v[236:237], v[138:139]
	v_pk_add_f32 v[236:237], v[236:237], v[140:141]
	v_pk_add_f32 v[236:237], v[236:237], v[142:143]
	v_pk_add_f32 v[236:237], v[236:237], v[144:145]
	v_pk_add_f32 v[236:237], v[236:237], v[146:147]
	v_pk_add_f32 v[236:237], v[236:237], v[148:149]
	v_pk_add_f32 v[236:237], v[236:237], v[150:151]
	v_pk_add_f32 v[236:237], v[236:237], v[152:153]
	v_pk_add_f32 v[236:237], v[236:237], v[154:155]
	v_pk_add_f32 v[236:237], v[236:237], v[156:157]
	v_pk_add_f32 v[236:237], v[236:237], v[158:159]
	v_add_f32_e32 v234, v236, v237
	s_nop 1
	v_add_f32_dpp v234, v234, v234 quad_perm:[1,0,3,2] row_mask:0xf bank_mask:0xf
	s_nop 1
	v_add_f32_dpp v234, v234, v234 quad_perm:[2,3,0,1] row_mask:0xf bank_mask:0xf
	s_nop 1
	v_add_f32_dpp v234, v234, v234 row_half_mirror row_mask:0xf bank_mask:0xf
	s_nop 1
	v_add_f32_dpp v234, v234, v234 row_mirror row_mask:0xf bank_mask:0xf
	s_nop 0
	v_readlane_b32 s26, v234, 0
	v_readlane_b32 s27, v234, 16
	v_readlane_b32 s28, v234, 32
	v_readlane_b32 s29, v234, 48
	v_mov_b32_e32 v234, s26
	v_add_f32_e32 v234, s27, v234
	v_add_f32_e32 v234, s28, v234
	v_add_f32_e32 v234, s29, v234
	v_mul_f32_e32 v216, 0xba000000, v234
	v_pk_add_f32 v[128:129], v[128:129], v[216:217] op_sel_hi:[1,0]
	v_pk_add_f32 v[130:131], v[130:131], v[216:217] op_sel_hi:[1,0]
	v_pk_add_f32 v[132:133], v[132:133], v[216:217] op_sel_hi:[1,0]
	v_pk_add_f32 v[134:135], v[134:135], v[216:217] op_sel_hi:[1,0]
	v_pk_add_f32 v[136:137], v[136:137], v[216:217] op_sel_hi:[1,0]
	v_pk_add_f32 v[138:139], v[138:139], v[216:217] op_sel_hi:[1,0]
	v_pk_add_f32 v[140:141], v[140:141], v[216:217] op_sel_hi:[1,0]
	v_pk_add_f32 v[142:143], v[142:143], v[216:217] op_sel_hi:[1,0]
	v_pk_add_f32 v[144:145], v[144:145], v[216:217] op_sel_hi:[1,0]
	v_pk_add_f32 v[146:147], v[146:147], v[216:217] op_sel_hi:[1,0]
	v_pk_add_f32 v[148:149], v[148:149], v[216:217] op_sel_hi:[1,0]
	v_pk_add_f32 v[150:151], v[150:151], v[216:217] op_sel_hi:[1,0]
	v_pk_add_f32 v[152:153], v[152:153], v[216:217] op_sel_hi:[1,0]
	v_pk_add_f32 v[154:155], v[154:155], v[216:217] op_sel_hi:[1,0]
	v_pk_add_f32 v[156:157], v[156:157], v[216:217] op_sel_hi:[1,0]
; __device__ __forceinline__ void ln_phase(const float* in, float* outf, bf16_t* outb, const float* g, const float* b, int wv0) {
;     ...
;     for (int i = 0; i < 8; ++i) { v[i] -= mu; sq += v[i][0] * v[i][0] + v[i][1] * v[i][1] + v[i][2] * v[i][2] + v[i][3] * v[i][3]; }
;     sq = wave_sum(sq); const float rstd = __builtin_amdgcn_rsqf(sq * (1.0f / 2048.0f) + EPS);
; #pragma unroll
;     for (int i = 0; i < 8; ++i) {
;       const f32x4 y = v[i] * rstd * gg[i] + bb[i];
;       ((f32x4*)(outf + (size_t)row * DM))[i * 64 + lane] = y;
;       if (outb) { u32x2 w; w.x = pk2(y[0], y[1]); w.y = pk2(y[2], y[3]); ((u32x2*)(outb + (size_t)row * DM))[i * 64 + lane] = w; } }
	v_pk_add_f32 v[158:159], v[158:159], v[216:217] op_sel_hi:[1,0]
	v_pk_mul_f32 v[236:237], v[128:129], v[128:129]
	v_pk_fma_f32 v[236:237], v[130:131], v[130:131], v[236:237]
	v_pk_fma_f32 v[236:237], v[132:133], v[132:133], v[236:237]
	v_pk_fma_f32 v[236:237], v[134:135], v[134:135], v[236:237]
	v_pk_fma_f32 v[236:237], v[136:137], v[136:137], v[236:237]
	v_pk_fma_f32 v[236:237], v[138:139], v[138:139], v[236:237]
	v_pk_fma_f32 v[236:237], v[140:141], v[140:141], v[236:237]
	v_pk_fma_f32 v[236:237], v[142:143], v[142:143], v[236:237]
	v_pk_fma_f32 v[236:237], v[144:145], v[144:145], v[236:237]
	v_pk_fma_f32 v[236:237], v[146:147], v[146:147], v[236:237]
	v_pk_fma_f32 v[236:237], v[148:149], v[148:149], v[236:237]
	v_pk_fma_f32 v[236:237], v[150:151], v[150:151], v[236:237]
	v_pk_fma_f32 v[236:237], v[152:153], v[152:153], v[236:237]
	v_pk_fma_f32 v[236:237], v[154:155], v[154:155], v[236:237]
	v_pk_fma_f32 v[236:237], v[156:157], v[156:157], v[236:237]
	v_pk_fma_f32 v[236:237], v[158:159], v[158:159], v[236:237]
	v_add_f32_e32 v235, v236, v237
	s_nop 1
	v_add_f32_dpp v235, v235, v235 quad_perm:[1,0,3,2] row_mask:0xf bank_mask:0xf
	s_nop 1
	v_add_f32_dpp v235, v235, v235 quad_perm:[2,3,0,1] row_mask:0xf bank_mask:0xf
	s_nop 1
	v_add_f32_dpp v235, v235, v235 row_half_mirror row_mask:0xf bank_mask:0xf
	s_nop 1
	v_add_f32_dpp v235, v235, v235 row_mirror row_mask:0xf bank_mask:0xf
	s_nop 0
	v_readlane_b32 s26, v235, 0
	v_readlane_b32 s27, v235, 16
	v_readlane_b32 s28, v235, 32
	v_readlane_b32 s29, v235, 48
	v_mov_b32_e32 v235, s26
	v_add_f32_e32 v235, s27, v235
	v_add_f32_e32 v235, s28, v235
	v_add_f32_e32 v235, s29, v235
	v_fmamk_f32 v235, v235, 0x3a000000, v246
	v_rsq_f32_e32 v217, v235
	s_lshl_b32 s23, s20, 13
	s_add_u32 s28, s18, s23
	s_addc_u32 s29, s19, 0
	s_lshr_b32 s23, s23, 1
	s_add_u32 s30, s2, s23
	s_addc_u32 s31, s3, 0
	v_pk_mul_f32 v[128:129], v[128:129], v[216:217] op_sel:[0,1] op_sel_hi:[1,1]
	v_pk_mul_f32 v[130:131], v[130:131], v[216:217] op_sel:[0,1] op_sel_hi:[1,1]
	v_pk_fma_f32 v[128:129], v[0:1], v[128:129], v[32:33]
	v_pk_fma_f32 v[130:131], v[2:3], v[130:131], v[34:35]
	v_pk_mul_f32 v[132:133], v[132:133], v[216:217] op_sel:[0,1] op_sel_hi:[1,1]
	v_pk_mul_f32 v[134:135], v[134:135], v[216:217] op_sel:[0,1] op_sel_hi:[1,1]
	v_pk_fma_f32 v[132:133], v[4:5], v[132:133], v[36:37]
	v_pk_fma_f32 v[134:135], v[6:7], v[134:135], v[38:39]
	v_cvt_pk_bf16_f32 v208, v128, v129
	v_cvt_pk_bf16_f32 v209, v130, v131
	v_cvt_pk_bf16_f32 v210, v132, v133
	v_cvt_pk_bf16_f32 v211, v134, v135
	global_store_dwordx4 v240, v[128:131], s[28:29]
	global_store_dwordx4 v240, v[132:135], s[28:29] offset:16
	global_store_dwordx4 v242, v[208:211], s[30:31]
	v_pk_mul_f32 v[136:137], v[136:137], v[216:217] op_sel:[0,1] op_sel_hi:[1,1]
	v_pk_mul_f32 v[138:139], v[138:139], v[216:217] op_sel:[0,1] op_sel_hi:[1,1]
	v_pk_fma_f32 v[136:137], v[8:9], v[136:137], v[40:41]
	v_pk_fma_f32 v[138:139], v[10:11], v[138:139], v[42:43]
	v_pk_mul_f32 v[140:141], v[140:141], v[216:217] op_sel:[0,1] op_sel_hi:[1,1]
	v_pk_mul_f32 v[142:143], v[142:143], v[216:217] op_sel:[0,1] op_sel_hi:[1,1]
	v_pk_fma_f32 v[140:141], v[12:13], v[140:141], v[44:45]
	v_pk_fma_f32 v[142:143], v[14:15], v[142:143], v[46:47]
	v_cvt_pk_bf16_f32 v212, v136, v137
	v_cvt_pk_bf16_f32 v213, v138, v139
	v_cvt_pk_bf16_f32 v214, v140, v141
	v_cvt_pk_bf16_f32 v215, v142, v143
	global_store_dwordx4 v240, v[136:139], s[28:29] offset:2048
	global_store_dwordx4 v240, v[140:143], s[28:29] offset:2064
	global_store_dwordx4 v242, v[212:215], s[30:31] offset:1024
	v_pk_mul_f32 v[144:145], v[144:145], v[216:217] op_sel:[0,1] op_sel_hi:[1,1]
	v_pk_mul_f32 v[146:147], v[146:147], v[216:217] op_sel:[0,1] op_sel_hi:[1,1]
	v_pk_fma_f32 v[144:145], v[16:17], v[144:145], v[48:49]
	v_pk_fma_f32 v[146:147], v[18:19], v[146:147], v[50:51]
	v_pk_mul_f32 v[148:149], v[148:149], v[216:217] op_sel:[0,1] op_sel_hi:[1,1]
	v_pk_mul_f32 v[150:151], v[150:151], v[216:217] op_sel:[0,1] op_sel_hi:[1,1]
	v_pk_fma_f32 v[148:149], v[20:21], v[148:149], v[52:53]
	v_pk_fma_f32 v[150:151], v[22:23], v[150:151], v[54:55]
	v_cvt_pk_bf16_f32 v208, v144, v145
	v_cvt_pk_bf16_f32 v209, v146, v147
	v_cvt_pk_bf16_f32 v210, v148, v149
	v_cvt_pk_bf16_f32 v211, v150, v151
	global_store_dwordx4 v241, v[144:147], s[28:29]
	global_store_dwordx4 v241, v[148:151], s[28:29] offset:16
	global_store_dwordx4 v242, v[208:211], s[30:31] offset:2048
	v_pk_mul_f32 v[152:153], v[152:153], v[216:217] op_sel:[0,1] op_sel_hi:[1,1]
	v_pk_mul_f32 v[154:155], v[154:155], v[216:217] op_sel:[0,1] op_sel_hi:[1,1]
	v_pk_fma_f32 v[152:153], v[24:25], v[152:153], v[56:57]
	v_pk_fma_f32 v[154:155], v[26:27], v[154:155], v[58:59]
	v_pk_mul_f32 v[156:157], v[156:157], v[216:217] op_sel:[0,1] op_sel_hi:[1,1]
	v_pk_mul_f32 v[158:159], v[158:159], v[216:217] op_sel:[0,1] op_sel_hi:[1,1]
	v_pk_fma_f32 v[156:157], v[28:29], v[156:157], v[60:61]
	v_pk_fma_f32 v[158:159], v[30:31], v[158:159], v[62:63]
	v_cvt_pk_bf16_f32 v212, v152, v153
	v_cvt_pk_bf16_f32 v213, v154, v155
	v_cvt_pk_bf16_f32 v214, v156, v157
	v_cvt_pk_bf16_f32 v215, v158, v159
	global_store_dwordx4 v241, v[152:155], s[28:29] offset:2048
	global_store_dwordx4 v241, v[156:159], s[28:29] offset:2064
	global_store_dwordx4 v242, v[212:215], s[30:31] offset:3072
	s_add_u32 s20, s20, s21
	s_cmp_ge_u32 s20, 0x4000
	s_cbranch_scc1 .Lln2a_done
; __device__ __forceinline__ void ln_phase(const float* in, float* outf, bf16_t* outb, const float* g, const float* b, int wv0) {
;     ...
;   for (int row = wv; row < NTOK; row += nwv) {
;     f32x4 v[8]; float s = 0.f;
; #pragma unroll
;     for (int i = 0; i < 8; ++i) v[i] = vn[i];
;     if (row + nwv < NTOK) { const f32x4* ir = (const f32x4*)(in + (size_t)(row + nwv) * DM);
; #pragma unroll
;       for (int i = 0; i < 8; ++i) vn[i] = ir[i * 64 + lane]; }
; #pragma unroll
;     for (int i = 0; i < 8; ++i) s += v[i][0] + v[i][1] + v[i][2] + v[i][3];
;     s = wave_sum(s); const float mu = s * (1.0f / 2048.0f);
;     float sq = 0.f;
; #pragma unroll
;     for (int i = 0; i < 8; ++i) { v[i] -= mu; sq += v[i][0] * v[i][0] + v[i][1] * v[i][1] + v[i][2] * v[i][2] + v[i][3] * v[i][3]; }
;     sq = wave_sum(sq); const float rstd = __builtin_amdgcn_rsqf(sq * (1.0f / 2048.0f) + EPS);
; #pragma unroll
;     for (int i = 0; i < 8; ++i) {
;       const f32x4 y = v[i] * rstd * gg[i] + bb[i];
;       ((f32x4*)(outf + (size_t)row * DM))[i * 64 + lane] = y;
;       if (outb) { u32x2 w; w.x = pk2(y[0], y[1]); w.y = pk2(y[2], y[3]); ((u32x2*)(outb + (size_t)row * DM))[i * 64 + lane] = w; } }
.Lln2a_loop:
	s_mul_i32 s23, s21, 3
	s_add_u32 s23, s20, s23
	s_min_u32 s23, s23, 0x3fff
	s_lshl_b32 s23, s23, 13
	s_add_u32 s24, s12, s23
	s_addc_u32 s25, s13, 0
	global_load_dwordx4 v[128:131], v240, s[24:25]
	global_load_dwordx4 v[132:135], v240, s[24:25] offset:16
	global_load_dwordx4 v[136:139], v240, s[24:25] offset:2048
	global_load_dwordx4 v[140:143], v240, s[24:25] offset:2064
	global_load_dwordx4 v[144:147], v241, s[24:25]
	global_load_dwordx4 v[148:151], v241, s[24:25] offset:16
	global_load_dwordx4 v[152:155], v241, s[24:25] offset:2048
	global_load_dwordx4 v[156:159], v241, s[24:25] offset:2064
	s_waitcnt vmcnt(60)
	v_pk_add_f32 v[236:237], v[176:177], v[178:179]
	v_pk_add_f32 v[236:237], v[236:237], v[180:181]
	v_pk_add_f32 v[236:237], v[236:237], v[182:183]
	v_pk_add_f32 v[236:237], v[236:237], v[184:185]
	v_pk_add_f32 v[236:237], v[236:237], v[186:187]
	v_pk_add_f32 v[236:237], v[236:237], v[188:189]
	v_pk_add_f32 v[236:237], v[236:237], v[190:191]
	v_pk_add_f32 v[236:237], v[236:237], v[192:193]
	v_pk_add_f32 v[236:237], v[236:237], v[194:195]
	v_pk_add_f32 v[236:237], v[236:237], v[196:197]
	v_pk_add_f32 v[236:237], v[236:237], v[198:199]
	v_pk_add_f32 v[236:237], v[236:237], v[200:201]
	v_pk_add_f32 v[236:237], v[236:237], v[202:203]
	v_pk_add_f32 v[236:237], v[236:237], v[204:205]
	v_pk_add_f32 v[236:237], v[236:237], v[206:207]
	v_add_f32_e32 v234, v236, v237
	s_nop 1
	v_add_f32_dpp v234, v234, v234 quad_perm:[1,0,3,2] row_mask:0xf bank_mask:0xf
	s_nop 1
	v_add_f32_dpp v234, v234, v234 quad_perm:[2,3,0,1] row_mask:0xf bank_mask:0xf
	s_nop 1
	v_add_f32_dpp v234, v234, v234 row_half_mirror row_mask:0xf bank_mask:0xf
	s_nop 1
	v_add_f32_dpp v234, v234, v234 row_mirror row_mask:0xf bank_mask:0xf
	s_nop 0
	v_readlane_b32 s26, v234, 0
	v_readlane_b32 s27, v234, 16
	v_readlane_b32 s28, v234, 32
	v_readlane_b32 s29, v234, 48
	v_mov_b32_e32 v234, s26
	v_add_f32_e32 v234, s27, v234
	v_add_f32_e32 v234, s28, v234
	v_add_f32_e32 v234, s29, v234
	v_mul_f32_e32 v216, 0xba000000, v234
	v_pk_add_f32 v[176:177], v[176:177], v[216:217] op_sel_hi:[1,0]
	v_pk_add_f32 v[178:179], v[178:179], v[216:217] op_sel_hi:[1,0]
	v_pk_add_f32 v[180:181], v[180:181], v[216:217] op_sel_hi:[1,0]
	v_pk_add_f32 v[182:183], v[182:183], v[216:217] op_sel_hi:[1,0]
	v_pk_add_f32 v[184:185], v[184:185], v[216:217] op_sel_hi:[1,0]
	v_pk_add_f32 v[186:187], v[186:187], v[216:217] op_sel_hi:[1,0]
	v_pk_add_f32 v[188:189], v[188:189], v[216:217] op_sel_hi:[1,0]
	v_pk_add_f32 v[190:191], v[190:191], v[216:217] op_sel_hi:[1,0]
	v_pk_add_f32 v[192:193], v[192:193], v[216:217] op_sel_hi:[1,0]
	v_pk_add_f32 v[194:195], v[194:195], v[216:217] op_sel_hi:[1,0]
	v_pk_add_f32 v[196:197], v[196:197], v[216:217] op_sel_hi:[1,0]
	v_pk_add_f32 v[198:199], v[198:199], v[216:217] op_sel_hi:[1,0]
	v_pk_add_f32 v[200:201], v[200:201], v[216:217] op_sel_hi:[1,0]
	v_pk_add_f32 v[202:203], v[202:203], v[216:217] op_sel_hi:[1,0]
	v_pk_add_f32 v[204:205], v[204:205], v[216:217] op_sel_hi:[1,0]
	v_pk_add_f32 v[206:207], v[206:207], v[216:217] op_sel_hi:[1,0]
	v_pk_mul_f32 v[236:237], v[176:177], v[176:177]
	v_pk_fma_f32 v[236:237], v[178:179], v[178:179], v[236:237]
	v_pk_fma_f32 v[236:237], v[180:181], v[180:181], v[236:237]
	v_pk_fma_f32 v[236:237], v[182:183], v[182:183], v[236:237]
	v_pk_fma_f32 v[236:237], v[184:185], v[184:185], v[236:237]
	v_pk_fma_f32 v[236:237], v[186:187], v[186:187], v[236:237]
	v_pk_fma_f32 v[236:237], v[188:189], v[188:189], v[236:237]
	v_pk_fma_f32 v[236:237], v[190:191], v[190:191], v[236:237]
	v_pk_fma_f32 v[236:237], v[192:193], v[192:193], v[236:237]
	v_pk_fma_f32 v[236:237], v[194:195], v[194:195], v[236:237]
	v_pk_fma_f32 v[236:237], v[196:197], v[196:197], v[236:237]
	v_pk_fma_f32 v[236:237], v[198:199], v[198:199], v[236:237]
	v_pk_fma_f32 v[236:237], v[200:201], v[200:201], v[236:237]
	v_pk_fma_f32 v[236:237], v[202:203], v[202:203], v[236:237]
	v_pk_fma_f32 v[236:237], v[204:205], v[204:205], v[236:237]
	v_pk_fma_f32 v[236:237], v[206:207], v[206:207], v[236:237]
	v_add_f32_e32 v235, v236, v237
	s_nop 1
	v_add_f32_dpp v235, v235, v235 quad_perm:[1,0,3,2] row_mask:0xf bank_mask:0xf
	s_nop 1
	v_add_f32_dpp v235, v235, v235 quad_perm:[2,3,0,1] row_mask:0xf bank_mask:0xf
	s_nop 1
	v_add_f32_dpp v235, v235, v235 row_half_mirror row_mask:0xf bank_mask:0xf
	s_nop 1
	v_add_f32_dpp v235, v235, v235 row_mirror row_mask:0xf bank_mask:0xf
	s_nop 0
	v_readlane_b32 s26, v235, 0
	v_readlane_b32 s27, v235, 16
	v_readlane_b32 s28, v235, 32
	v_readlane_b32 s29, v235, 48
	v_mov_b32_e32 v235, s26
	v_add_f32_e32 v235, s27, v235
	v_add_f32_e32 v235, s28, v235
	v_add_f32_e32 v235, s29, v235
	v_fmamk_f32 v235, v235, 0x3a000000, v246
	v_rsq_f32_e32 v217, v235
	s_lshl_b32 s23, s20, 13
	s_add_u32 s28, s18, s23
	s_addc_u32 s29, s19, 0
	s_lshr_b32 s23, s23, 1
	s_add_u32 s30, s2, s23
	s_addc_u32 s31, s3, 0
	v_pk_mul_f32 v[176:177], v[176:177], v[216:217] op_sel:[0,1] op_sel_hi:[1,1]
	v_pk_mul_f32 v[178:179], v[178:179], v[216:217] op_sel:[0,1] op_sel_hi:[1,1]
	v_pk_fma_f32 v[176:177], v[0:1], v[176:177], v[32:33]
	v_pk_fma_f32 v[178:179], v[2:3], v[178:179], v[34:35]
	v_pk_mul_f32 v[180:181], v[180:181], v[216:217] op_sel:[0,1] op_sel_hi:[1,1]
	v_pk_mul_f32 v[182:183], v[182:183], v[216:217] op_sel:[0,1] op_sel_hi:[1,1]
	v_pk_fma_f32 v[180:181], v[4:5], v[180:181], v[36:37]
	v_pk_fma_f32 v[182:183], v[6:7], v[182:183], v[38:39]
	v_cvt_pk_bf16_f32 v208, v176, v177
	v_cvt_pk_bf16_f32 v209, v178, v179
	v_cvt_pk_bf16_f32 v210, v180, v181
	v_cvt_pk_bf16_f32 v211, v182, v183
	global_store_dwordx4 v240, v[176:179], s[28:29]
	global_store_dwordx4 v240, v[180:183], s[28:29] offset:16
; __device__ __forceinline__ void ln_phase(const float* in, float* outf, bf16_t* outb, const float* g, const float* b, int wv0) {
;     ...
;   for (int row = wv; row < NTOK; row += nwv) {
;     f32x4 v[8]; float s = 0.f;
; #pragma unroll
;     for (int i = 0; i < 8; ++i) v[i] = vn[i];
;     if (row + nwv < NTOK) { const f32x4* ir = (const f32x4*)(in + (size_t)(row + nwv) * DM);
; #pragma unroll
;       for (int i = 0; i < 8; ++i) vn[i] = ir[i * 64 + lane]; }
; #pragma unroll
;     for (int i = 0; i < 8; ++i) s += v[i][0] + v[i][1] + v[i][2] + v[i][3];
;     s = wave_sum(s); const float mu = s * (1.0f / 2048.0f);
;     float sq = 0.f;
; #pragma unroll
;     for (int i = 0; i < 8; ++i) { v[i] -= mu; sq += v[i][0] * v[i][0] + v[i][1] * v[i][1] + v[i][2] * v[i][2] + v[i][3] * v[i][3]; }
;     sq = wave_sum(sq); const float rstd = __builtin_amdgcn_rsqf(sq * (1.0f / 2048.0f) + EPS);
; #pragma unroll
;     for (int i = 0; i < 8; ++i) {
;       const f32x4 y = v[i] * rstd * gg[i] + bb[i];
;       ((f32x4*)(outf + (size_t)row * DM))[i * 64 + lane] = y;
;       if (outb) { u32x2 w; w.x = pk2(y[0], y[1]); w.y = pk2(y[2], y[3]); ((u32x2*)(outb + (size_t)row * DM))[i * 64 + lane] = w; } }
	global_store_dwordx4 v242, v[208:211], s[30:31]
	v_pk_mul_f32 v[184:185], v[184:185], v[216:217] op_sel:[0,1] op_sel_hi:[1,1]
	v_pk_mul_f32 v[186:187], v[186:187], v[216:217] op_sel:[0,1] op_sel_hi:[1,1]
	v_pk_fma_f32 v[184:185], v[8:9], v[184:185], v[40:41]
	v_pk_fma_f32 v[186:187], v[10:11], v[186:187], v[42:43]
	v_pk_mul_f32 v[188:189], v[188:189], v[216:217] op_sel:[0,1] op_sel_hi:[1,1]
	v_pk_mul_f32 v[190:191], v[190:191], v[216:217] op_sel:[0,1] op_sel_hi:[1,1]
	v_pk_fma_f32 v[188:189], v[12:13], v[188:189], v[44:45]
	v_pk_fma_f32 v[190:191], v[14:15], v[190:191], v[46:47]
	v_cvt_pk_bf16_f32 v212, v184, v185
	v_cvt_pk_bf16_f32 v213, v186, v187
	v_cvt_pk_bf16_f32 v214, v188, v189
	v_cvt_pk_bf16_f32 v215, v190, v191
	global_store_dwordx4 v240, v[184:187], s[28:29] offset:2048
	global_store_dwordx4 v240, v[188:191], s[28:29] offset:2064
	global_store_dwordx4 v242, v[212:215], s[30:31] offset:1024
	v_pk_mul_f32 v[192:193], v[192:193], v[216:217] op_sel:[0,1] op_sel_hi:[1,1]
	v_pk_mul_f32 v[194:195], v[194:195], v[216:217] op_sel:[0,1] op_sel_hi:[1,1]
	v_pk_fma_f32 v[192:193], v[16:17], v[192:193], v[48:49]
	v_pk_fma_f32 v[194:195], v[18:19], v[194:195], v[50:51]
	v_pk_mul_f32 v[196:197], v[196:197], v[216:217] op_sel:[0,1] op_sel_hi:[1,1]
	v_pk_mul_f32 v[198:199], v[198:199], v[216:217] op_sel:[0,1] op_sel_hi:[1,1]
	v_pk_fma_f32 v[196:197], v[20:21], v[196:197], v[52:53]
	v_pk_fma_f32 v[198:199], v[22:23], v[198:199], v[54:55]
	v_cvt_pk_bf16_f32 v208, v192, v193
	v_cvt_pk_bf16_f32 v209, v194, v195
	v_cvt_pk_bf16_f32 v210, v196, v197
	v_cvt_pk_bf16_f32 v211, v198, v199
	global_store_dwordx4 v241, v[192:195], s[28:29]
	global_store_dwordx4 v241, v[196:199], s[28:29] offset:16
	global_store_dwordx4 v242, v[208:211], s[30:31] offset:2048
	v_pk_mul_f32 v[200:201], v[200:201], v[216:217] op_sel:[0,1] op_sel_hi:[1,1]
	v_pk_mul_f32 v[202:203], v[202:203], v[216:217] op_sel:[0,1] op_sel_hi:[1,1]
	v_pk_fma_f32 v[200:201], v[24:25], v[200:201], v[56:57]
	v_pk_fma_f32 v[202:203], v[26:27], v[202:203], v[58:59]
	v_pk_mul_f32 v[204:205], v[204:205], v[216:217] op_sel:[0,1] op_sel_hi:[1,1]
	v_pk_mul_f32 v[206:207], v[206:207], v[216:217] op_sel:[0,1] op_sel_hi:[1,1]
	v_pk_fma_f32 v[204:205], v[28:29], v[204:205], v[60:61]
	v_pk_fma_f32 v[206:207], v[30:31], v[206:207], v[62:63]
	v_cvt_pk_bf16_f32 v212, v200, v201
	v_cvt_pk_bf16_f32 v213, v202, v203
	v_cvt_pk_bf16_f32 v214, v204, v205
	v_cvt_pk_bf16_f32 v215, v206, v207
	global_store_dwordx4 v241, v[200:203], s[28:29] offset:2048
	global_store_dwordx4 v241, v[204:207], s[28:29] offset:2064
	global_store_dwordx4 v242, v[212:215], s[30:31] offset:3072
	s_add_u32 s20, s20, s21
	s_cmp_ge_u32 s20, 0x4000
	s_cbranch_scc1 .Lln2a_done
	s_mul_i32 s23, s21, 3
	s_add_u32 s23, s20, s23
	s_min_u32 s23, s23, 0x3fff
	s_lshl_b32 s23, s23, 13
	s_add_u32 s24, s12, s23
	s_addc_u32 s25, s13, 0
	global_load_dwordx4 v[176:179], v240, s[24:25]
	global_load_dwordx4 v[180:183], v240, s[24:25] offset:16
	global_load_dwordx4 v[184:187], v240, s[24:25] offset:2048
	global_load_dwordx4 v[188:191], v240, s[24:25] offset:2064
	global_load_dwordx4 v[192:195], v241, s[24:25]
	global_load_dwordx4 v[196:199], v241, s[24:25] offset:16
	global_load_dwordx4 v[200:203], v241, s[24:25] offset:2048
	global_load_dwordx4 v[204:207], v241, s[24:25] offset:2064
	s_waitcnt vmcnt(60)
	v_pk_add_f32 v[236:237], v[64:65], v[66:67]
	v_pk_add_f32 v[236:237], v[236:237], v[68:69]
	v_pk_add_f32 v[236:237], v[236:237], v[70:71]
	v_pk_add_f32 v[236:237], v[236:237], v[72:73]
	v_pk_add_f32 v[236:237], v[236:237], v[74:75]
	v_pk_add_f32 v[236:237], v[236:237], v[76:77]
	v_pk_add_f32 v[236:237], v[236:237], v[78:79]
	v_pk_add_f32 v[236:237], v[236:237], v[80:81]
	v_pk_add_f32 v[236:237], v[236:237], v[82:83]
	v_pk_add_f32 v[236:237], v[236:237], v[84:85]
	v_pk_add_f32 v[236:237], v[236:237], v[86:87]
	v_pk_add_f32 v[236:237], v[236:237], v[88:89]
	v_pk_add_f32 v[236:237], v[236:237], v[90:91]
	v_pk_add_f32 v[236:237], v[236:237], v[92:93]
	v_pk_add_f32 v[236:237], v[236:237], v[94:95]
	v_add_f32_e32 v234, v236, v237
	s_nop 1
	v_add_f32_dpp v234, v234, v234 quad_perm:[1,0,3,2] row_mask:0xf bank_mask:0xf
	s_nop 1
	v_add_f32_dpp v234, v234, v234 quad_perm:[2,3,0,1] row_mask:0xf bank_mask:0xf
	s_nop 1
	v_add_f32_dpp v234, v234, v234 row_half_mirror row_mask:0xf bank_mask:0xf
	s_nop 1
	v_add_f32_dpp v234, v234, v234 row_mirror row_mask:0xf bank_mask:0xf
	s_nop 0
	v_readlane_b32 s26, v234, 0
	v_readlane_b32 s27, v234, 16
	v_readlane_b32 s28, v234, 32
	v_readlane_b32 s29, v234, 48
	v_mov_b32_e32 v234, s26
	v_add_f32_e32 v234, s27, v234
	v_add_f32_e32 v234, s28, v234
	v_add_f32_e32 v234, s29, v234
	v_mul_f32_e32 v216, 0xba000000, v234
	v_pk_add_f32 v[64:65], v[64:65], v[216:217] op_sel_hi:[1,0]
	v_pk_add_f32 v[66:67], v[66:67], v[216:217] op_sel_hi:[1,0]
	v_pk_add_f32 v[68:69], v[68:69], v[216:217] op_sel_hi:[1,0]
	v_pk_add_f32 v[70:71], v[70:71], v[216:217] op_sel_hi:[1,0]
	v_pk_add_f32 v[72:73], v[72:73], v[216:217] op_sel_hi:[1,0]
	v_pk_add_f32 v[74:75], v[74:75], v[216:217] op_sel_hi:[1,0]
	v_pk_add_f32 v[76:77], v[76:77], v[216:217] op_sel_hi:[1,0]
	v_pk_add_f32 v[78:79], v[78:79], v[216:217] op_sel_hi:[1,0]
	v_pk_add_f32 v[80:81], v[80:81], v[216:217] op_sel_hi:[1,0]
	v_pk_add_f32 v[82:83], v[82:83], v[216:217] op_sel_hi:[1,0]
	v_pk_add_f32 v[84:85], v[84:85], v[216:217] op_sel_hi:[1,0]
	v_pk_add_f32 v[86:87], v[86:87], v[216:217] op_sel_hi:[1,0]
	v_pk_add_f32 v[88:89], v[88:89], v[216:217] op_sel_hi:[1,0]
	v_pk_add_f32 v[90:91], v[90:91], v[216:217] op_sel_hi:[1,0]
	v_pk_add_f32 v[92:93], v[92:93], v[216:217] op_sel_hi:[1,0]
	v_pk_add_f32 v[94:95], v[94:95], v[216:217] op_sel_hi:[1,0]
; __device__ __forceinline__ void ln_phase(const float* in, float* outf, bf16_t* outb, const float* g, const float* b, int wv0) {
;     ...
;     float sq = 0.f;
; #pragma unroll
;     for (int i = 0; i < 8; ++i) { v[i] -= mu; sq += v[i][0] * v[i][0] + v[i][1] * v[i][1] + v[i][2] * v[i][2] + v[i][3] * v[i][3]; }
;     sq = wave_sum(sq); const float rstd = __builtin_amdgcn_rsqf(sq * (1.0f / 2048.0f) + EPS);
; #pragma unroll
;     for (int i = 0; i < 8; ++i) {
;       const f32x4 y = v[i] * rstd * gg[i] + bb[i];
;       ((f32x4*)(outf + (size_t)row * DM))[i * 64 + lane] = y;
;       if (outb) { u32x2 w; w.x = pk2(y[0], y[1]); w.y = pk2(y[2], y[3]); ((u32x2*)(outb + (size_t)row * DM))[i * 64 + lane] = w; } }
	v_pk_mul_f32 v[236:237], v[64:65], v[64:65]
	v_pk_fma_f32 v[236:237], v[66:67], v[66:67], v[236:237]
	v_pk_fma_f32 v[236:237], v[68:69], v[68:69], v[236:237]
	v_pk_fma_f32 v[236:237], v[70:71], v[70:71], v[236:237]
	v_pk_fma_f32 v[236:237], v[72:73], v[72:73], v[236:237]
	v_pk_fma_f32 v[236:237], v[74:75], v[74:75], v[236:237]
	v_pk_fma_f32 v[236:237], v[76:77], v[76:77], v[236:237]
	v_pk_fma_f32 v[236:237], v[78:79], v[78:79], v[236:237]
	v_pk_fma_f32 v[236:237], v[80:81], v[80:81], v[236:237]
	v_pk_fma_f32 v[236:237], v[82:83], v[82:83], v[236:237]
	v_pk_fma_f32 v[236:237], v[84:85], v[84:85], v[236:237]
	v_pk_fma_f32 v[236:237], v[86:87], v[86:87], v[236:237]
	v_pk_fma_f32 v[236:237], v[88:89], v[88:89], v[236:237]
	v_pk_fma_f32 v[236:237], v[90:91], v[90:91], v[236:237]
	v_pk_fma_f32 v[236:237], v[92:93], v[92:93], v[236:237]
	v_pk_fma_f32 v[236:237], v[94:95], v[94:95], v[236:237]
	v_add_f32_e32 v235, v236, v237
	s_nop 1
	v_add_f32_dpp v235, v235, v235 quad_perm:[1,0,3,2] row_mask:0xf bank_mask:0xf
	s_nop 1
	v_add_f32_dpp v235, v235, v235 quad_perm:[2,3,0,1] row_mask:0xf bank_mask:0xf
	s_nop 1
	v_add_f32_dpp v235, v235, v235 row_half_mirror row_mask:0xf bank_mask:0xf
	s_nop 1
	v_add_f32_dpp v235, v235, v235 row_mirror row_mask:0xf bank_mask:0xf
	s_nop 0
	v_readlane_b32 s26, v235, 0
	v_readlane_b32 s27, v235, 16
	v_readlane_b32 s28, v235, 32
	v_readlane_b32 s29, v235, 48
	v_mov_b32_e32 v235, s26
	v_add_f32_e32 v235, s27, v235
	v_add_f32_e32 v235, s28, v235
	v_add_f32_e32 v235, s29, v235
	v_fmamk_f32 v235, v235, 0x3a000000, v246
	v_rsq_f32_e32 v217, v235
	s_lshl_b32 s23, s20, 13
	s_add_u32 s28, s18, s23
	s_addc_u32 s29, s19, 0
	s_lshr_b32 s23, s23, 1
	s_add_u32 s30, s2, s23
	s_addc_u32 s31, s3, 0
	v_pk_mul_f32 v[64:65], v[64:65], v[216:217] op_sel:[0,1] op_sel_hi:[1,1]
	v_pk_mul_f32 v[66:67], v[66:67], v[216:217] op_sel:[0,1] op_sel_hi:[1,1]
	v_pk_fma_f32 v[64:65], v[0:1], v[64:65], v[32:33]
	v_pk_fma_f32 v[66:67], v[2:3], v[66:67], v[34:35]
	v_pk_mul_f32 v[68:69], v[68:69], v[216:217] op_sel:[0,1] op_sel_hi:[1,1]
	v_pk_mul_f32 v[70:71], v[70:71], v[216:217] op_sel:[0,1] op_sel_hi:[1,1]
	v_pk_fma_f32 v[68:69], v[4:5], v[68:69], v[36:37]
	v_pk_fma_f32 v[70:71], v[6:7], v[70:71], v[38:39]
	v_cvt_pk_bf16_f32 v208, v64, v65
	v_cvt_pk_bf16_f32 v209, v66, v67
	v_cvt_pk_bf16_f32 v210, v68, v69
	v_cvt_pk_bf16_f32 v211, v70, v71
	global_store_dwordx4 v240, v[64:67], s[28:29]
	global_store_dwordx4 v240, v[68:71], s[28:29] offset:16
	global_store_dwordx4 v242, v[208:211], s[30:31]
	v_pk_mul_f32 v[72:73], v[72:73], v[216:217] op_sel:[0,1] op_sel_hi:[1,1]
	v_pk_mul_f32 v[74:75], v[74:75], v[216:217] op_sel:[0,1] op_sel_hi:[1,1]
	v_pk_fma_f32 v[72:73], v[8:9], v[72:73], v[40:41]
	v_pk_fma_f32 v[74:75], v[10:11], v[74:75], v[42:43]
	v_pk_mul_f32 v[76:77], v[76:77], v[216:217] op_sel:[0,1] op_sel_hi:[1,1]
	v_pk_mul_f32 v[78:79], v[78:79], v[216:217] op_sel:[0,1] op_sel_hi:[1,1]
	v_pk_fma_f32 v[76:77], v[12:13], v[76:77], v[44:45]
	v_pk_fma_f32 v[78:79], v[14:15], v[78:79], v[46:47]
	v_cvt_pk_bf16_f32 v212, v72, v73
	v_cvt_pk_bf16_f32 v213, v74, v75
	v_cvt_pk_bf16_f32 v214, v76, v77
	v_cvt_pk_bf16_f32 v215, v78, v79
	global_store_dwordx4 v240, v[72:75], s[28:29] offset:2048
	global_store_dwordx4 v240, v[76:79], s[28:29] offset:2064
	global_store_dwordx4 v242, v[212:215], s[30:31] offset:1024
	v_pk_mul_f32 v[80:81], v[80:81], v[216:217] op_sel:[0,1] op_sel_hi:[1,1]
	v_pk_mul_f32 v[82:83], v[82:83], v[216:217] op_sel:[0,1] op_sel_hi:[1,1]
	v_pk_fma_f32 v[80:81], v[16:17], v[80:81], v[48:49]
	v_pk_fma_f32 v[82:83], v[18:19], v[82:83], v[50:51]
	v_pk_mul_f32 v[84:85], v[84:85], v[216:217] op_sel:[0,1] op_sel_hi:[1,1]
	v_pk_mul_f32 v[86:87], v[86:87], v[216:217] op_sel:[0,1] op_sel_hi:[1,1]
	v_pk_fma_f32 v[84:85], v[20:21], v[84:85], v[52:53]
	v_pk_fma_f32 v[86:87], v[22:23], v[86:87], v[54:55]
	v_cvt_pk_bf16_f32 v208, v80, v81
	v_cvt_pk_bf16_f32 v209, v82, v83
	v_cvt_pk_bf16_f32 v210, v84, v85
	v_cvt_pk_bf16_f32 v211, v86, v87
	global_store_dwordx4 v241, v[80:83], s[28:29]
	global_store_dwordx4 v241, v[84:87], s[28:29] offset:16
	global_store_dwordx4 v242, v[208:211], s[30:31] offset:2048
	v_pk_mul_f32 v[88:89], v[88:89], v[216:217] op_sel:[0,1] op_sel_hi:[1,1]
	v_pk_mul_f32 v[90:91], v[90:91], v[216:217] op_sel:[0,1] op_sel_hi:[1,1]
	v_pk_fma_f32 v[88:89], v[24:25], v[88:89], v[56:57]
	v_pk_fma_f32 v[90:91], v[26:27], v[90:91], v[58:59]
	v_pk_mul_f32 v[92:93], v[92:93], v[216:217] op_sel:[0,1] op_sel_hi:[1,1]
	v_pk_mul_f32 v[94:95], v[94:95], v[216:217] op_sel:[0,1] op_sel_hi:[1,1]
	v_pk_fma_f32 v[92:93], v[28:29], v[92:93], v[60:61]
	v_pk_fma_f32 v[94:95], v[30:31], v[94:95], v[62:63]
	v_cvt_pk_bf16_f32 v212, v88, v89
	v_cvt_pk_bf16_f32 v213, v90, v91
	v_cvt_pk_bf16_f32 v214, v92, v93
	v_cvt_pk_bf16_f32 v215, v94, v95
	global_store_dwordx4 v241, v[88:91], s[28:29] offset:2048
	global_store_dwordx4 v241, v[92:95], s[28:29] offset:2064
	global_store_dwordx4 v242, v[212:215], s[30:31] offset:3072
	s_add_u32 s20, s20, s21
	s_cmp_ge_u32 s20, 0x4000
	s_cbranch_scc1 .Lln2a_done
; __device__ __forceinline__ void ln_phase(const float* in, float* outf, bf16_t* outb, const float* g, const float* b, int wv0) {
;     ...
;   for (int row = wv; row < NTOK; row += nwv) {
;     f32x4 v[8]; float s = 0.f;
; #pragma unroll
;     for (int i = 0; i < 8; ++i) v[i] = vn[i];
;     if (row + nwv < NTOK) { const f32x4* ir = (const f32x4*)(in + (size_t)(row + nwv) * DM);
; #pragma unroll
;       for (int i = 0; i < 8; ++i) vn[i] = ir[i * 64 + lane]; }
; #pragma unroll
;     for (int i = 0; i < 8; ++i) s += v[i][0] + v[i][1] + v[i][2] + v[i][3];
;     s = wave_sum(s); const float mu = s * (1.0f / 2048.0f);
;     float sq = 0.f;
; #pragma unroll
;     for (int i = 0; i < 8; ++i) { v[i] -= mu; sq += v[i][0] * v[i][0] + v[i][1] * v[i][1] + v[i][2] * v[i][2] + v[i][3] * v[i][3]; }
;     sq = wave_sum(sq); const float rstd = __builtin_amdgcn_rsqf(sq * (1.0f / 2048.0f) + EPS);
; #pragma unroll
;     for (int i = 0; i < 8; ++i) {
;       const f32x4 y = v[i] * rstd * gg[i] + bb[i];
;       ((f32x4*)(outf + (size_t)row * DM))[i * 64 + lane] = y;
;       if (outb) { u32x2 w; w.x = pk2(y[0], y[1]); w.y = pk2(y[2], y[3]); ((u32x2*)(outb + (size_t)row * DM))[i * 64 + lane] = w; } }
	s_mul_i32 s23, s21, 3
	s_add_u32 s23, s20, s23
	s_min_u32 s23, s23, 0x3fff
	s_lshl_b32 s23, s23, 13
	s_add_u32 s24, s12, s23
	s_addc_u32 s25, s13, 0
	global_load_dwordx4 v[64:67], v240, s[24:25]
	global_load_dwordx4 v[68:71], v240, s[24:25] offset:16
	global_load_dwordx4 v[72:75], v240, s[24:25] offset:2048
	global_load_dwordx4 v[76:79], v240, s[24:25] offset:2064
	global_load_dwordx4 v[80:83], v241, s[24:25]
	global_load_dwordx4 v[84:87], v241, s[24:25] offset:16
	global_load_dwordx4 v[88:91], v241, s[24:25] offset:2048
	global_load_dwordx4 v[92:95], v241, s[24:25] offset:2064
	s_waitcnt vmcnt(60)
	v_pk_add_f32 v[236:237], v[96:97], v[98:99]
	v_pk_add_f32 v[236:237], v[236:237], v[100:101]
	v_pk_add_f32 v[236:237], v[236:237], v[102:103]
	v_pk_add_f32 v[236:237], v[236:237], v[104:105]
	v_pk_add_f32 v[236:237], v[236:237], v[106:107]
	v_pk_add_f32 v[236:237], v[236:237], v[108:109]
	v_pk_add_f32 v[236:237], v[236:237], v[110:111]
	v_pk_add_f32 v[236:237], v[236:237], v[112:113]
	v_pk_add_f32 v[236:237], v[236:237], v[114:115]
	v_pk_add_f32 v[236:237], v[236:237], v[116:117]
	v_pk_add_f32 v[236:237], v[236:237], v[118:119]
	v_pk_add_f32 v[236:237], v[236:237], v[120:121]
	v_pk_add_f32 v[236:237], v[236:237], v[122:123]
	v_pk_add_f32 v[236:237], v[236:237], v[124:125]
	v_pk_add_f32 v[236:237], v[236:237], v[126:127]
	v_add_f32_e32 v234, v236, v237
	s_nop 1
	v_add_f32_dpp v234, v234, v234 quad_perm:[1,0,3,2] row_mask:0xf bank_mask:0xf
	s_nop 1
	v_add_f32_dpp v234, v234, v234 quad_perm:[2,3,0,1] row_mask:0xf bank_mask:0xf
	s_nop 1
	v_add_f32_dpp v234, v234, v234 row_half_mirror row_mask:0xf bank_mask:0xf
	s_nop 1
	v_add_f32_dpp v234, v234, v234 row_mirror row_mask:0xf bank_mask:0xf
	s_nop 0
	v_readlane_b32 s26, v234, 0
	v_readlane_b32 s27, v234, 16
	v_readlane_b32 s28, v234, 32
	v_readlane_b32 s29, v234, 48
	v_mov_b32_e32 v234, s26
	v_add_f32_e32 v234, s27, v234
	v_add_f32_e32 v234, s28, v234
	v_add_f32_e32 v234, s29, v234
	v_mul_f32_e32 v216, 0xba000000, v234
	v_pk_add_f32 v[96:97], v[96:97], v[216:217] op_sel_hi:[1,0]
	v_pk_add_f32 v[98:99], v[98:99], v[216:217] op_sel_hi:[1,0]
	v_pk_add_f32 v[100:101], v[100:101], v[216:217] op_sel_hi:[1,0]
	v_pk_add_f32 v[102:103], v[102:103], v[216:217] op_sel_hi:[1,0]
	v_pk_add_f32 v[104:105], v[104:105], v[216:217] op_sel_hi:[1,0]
	v_pk_add_f32 v[106:107], v[106:107], v[216:217] op_sel_hi:[1,0]
	v_pk_add_f32 v[108:109], v[108:109], v[216:217] op_sel_hi:[1,0]
	v_pk_add_f32 v[110:111], v[110:111], v[216:217] op_sel_hi:[1,0]
	v_pk_add_f32 v[112:113], v[112:113], v[216:217] op_sel_hi:[1,0]
	v_pk_add_f32 v[114:115], v[114:115], v[216:217] op_sel_hi:[1,0]
	v_pk_add_f32 v[116:117], v[116:117], v[216:217] op_sel_hi:[1,0]
	v_pk_add_f32 v[118:119], v[118:119], v[216:217] op_sel_hi:[1,0]
	v_pk_add_f32 v[120:121], v[120:121], v[216:217] op_sel_hi:[1,0]
	v_pk_add_f32 v[122:123], v[122:123], v[216:217] op_sel_hi:[1,0]
	v_pk_add_f32 v[124:125], v[124:125], v[216:217] op_sel_hi:[1,0]
	v_pk_add_f32 v[126:127], v[126:127], v[216:217] op_sel_hi:[1,0]
	v_pk_mul_f32 v[236:237], v[96:97], v[96:97]
	v_pk_fma_f32 v[236:237], v[98:99], v[98:99], v[236:237]
	v_pk_fma_f32 v[236:237], v[100:101], v[100:101], v[236:237]
	v_pk_fma_f32 v[236:237], v[102:103], v[102:103], v[236:237]
	v_pk_fma_f32 v[236:237], v[104:105], v[104:105], v[236:237]
	v_pk_fma_f32 v[236:237], v[106:107], v[106:107], v[236:237]
	v_pk_fma_f32 v[236:237], v[108:109], v[108:109], v[236:237]
	v_pk_fma_f32 v[236:237], v[110:111], v[110:111], v[236:237]
	v_pk_fma_f32 v[236:237], v[112:113], v[112:113], v[236:237]
	v_pk_fma_f32 v[236:237], v[114:115], v[114:115], v[236:237]
	v_pk_fma_f32 v[236:237], v[116:117], v[116:117], v[236:237]
	v_pk_fma_f32 v[236:237], v[118:119], v[118:119], v[236:237]
	v_pk_fma_f32 v[236:237], v[120:121], v[120:121], v[236:237]
	v_pk_fma_f32 v[236:237], v[122:123], v[122:123], v[236:237]
	v_pk_fma_f32 v[236:237], v[124:125], v[124:125], v[236:237]
	v_pk_fma_f32 v[236:237], v[126:127], v[126:127], v[236:237]
	v_add_f32_e32 v235, v236, v237
	s_nop 1
	v_add_f32_dpp v235, v235, v235 quad_perm:[1,0,3,2] row_mask:0xf bank_mask:0xf
	s_nop 1
	v_add_f32_dpp v235, v235, v235 quad_perm:[2,3,0,1] row_mask:0xf bank_mask:0xf
	s_nop 1
	v_add_f32_dpp v235, v235, v235 row_half_mirror row_mask:0xf bank_mask:0xf
	s_nop 1
	v_add_f32_dpp v235, v235, v235 row_mirror row_mask:0xf bank_mask:0xf
	s_nop 0
	v_readlane_b32 s26, v235, 0
	v_readlane_b32 s27, v235, 16
	v_readlane_b32 s28, v235, 32
	v_readlane_b32 s29, v235, 48
	v_mov_b32_e32 v235, s26
	v_add_f32_e32 v235, s27, v235
	v_add_f32_e32 v235, s28, v235
	v_add_f32_e32 v235, s29, v235
	v_fmamk_f32 v235, v235, 0x3a000000, v246
	v_rsq_f32_e32 v217, v235
	s_lshl_b32 s23, s20, 13
	s_add_u32 s28, s18, s23
	s_addc_u32 s29, s19, 0
	s_lshr_b32 s23, s23, 1
	s_add_u32 s30, s2, s23
	s_addc_u32 s31, s3, 0
	v_pk_mul_f32 v[96:97], v[96:97], v[216:217] op_sel:[0,1] op_sel_hi:[1,1]
	v_pk_mul_f32 v[98:99], v[98:99], v[216:217] op_sel:[0,1] op_sel_hi:[1,1]
	v_pk_fma_f32 v[96:97], v[0:1], v[96:97], v[32:33]
	v_pk_fma_f32 v[98:99], v[2:3], v[98:99], v[34:35]
	v_pk_mul_f32 v[100:101], v[100:101], v[216:217] op_sel:[0,1] op_sel_hi:[1,1]
	v_pk_mul_f32 v[102:103], v[102:103], v[216:217] op_sel:[0,1] op_sel_hi:[1,1]
	v_pk_fma_f32 v[100:101], v[4:5], v[100:101], v[36:37]
	v_pk_fma_f32 v[102:103], v[6:7], v[102:103], v[38:39]
	v_cvt_pk_bf16_f32 v208, v96, v97
	v_cvt_pk_bf16_f32 v209, v98, v99
	v_cvt_pk_bf16_f32 v210, v100, v101
	v_cvt_pk_bf16_f32 v211, v102, v103
	global_store_dwordx4 v240, v[96:99], s[28:29]
	global_store_dwordx4 v240, v[100:103], s[28:29] offset:16
	global_store_dwordx4 v242, v[208:211], s[30:31]
; __device__ __forceinline__ void ln_phase(const float* in, float* outf, bf16_t* outb, const float* g, const float* b, int wv0) {
;     ...
;   for (int row = wv; row < NTOK; row += nwv) {
;     f32x4 v[8]; float s = 0.f;
; #pragma unroll
;     for (int i = 0; i < 8; ++i) v[i] = vn[i];
;     if (row + nwv < NTOK) { const f32x4* ir = (const f32x4*)(in + (size_t)(row + nwv) * DM);
; #pragma unroll
;       for (int i = 0; i < 8; ++i) vn[i] = ir[i * 64 + lane]; }
; #pragma unroll
;     for (int i = 0; i < 8; ++i) s += v[i][0] + v[i][1] + v[i][2] + v[i][3];
;     s = wave_sum(s); const float mu = s * (1.0f / 2048.0f);
;     float sq = 0.f;
; #pragma unroll
;     for (int i = 0; i < 8; ++i) { v[i] -= mu; sq += v[i][0] * v[i][0] + v[i][1] * v[i][1] + v[i][2] * v[i][2] + v[i][3] * v[i][3]; }
	v_pk_mul_f32 v[104:105], v[104:105], v[216:217] op_sel:[0,1] op_sel_hi:[1,1]
	v_pk_mul_f32 v[106:107], v[106:107], v[216:217] op_sel:[0,1] op_sel_hi:[1,1]
	v_pk_fma_f32 v[104:105], v[8:9], v[104:105], v[40:41]
	v_pk_fma_f32 v[106:107], v[10:11], v[106:107], v[42:43]
	v_pk_mul_f32 v[108:109], v[108:109], v[216:217] op_sel:[0,1] op_sel_hi:[1,1]
	v_pk_mul_f32 v[110:111], v[110:111], v[216:217] op_sel:[0,1] op_sel_hi:[1,1]
	v_pk_fma_f32 v[108:109], v[12:13], v[108:109], v[44:45]
	v_pk_fma_f32 v[110:111], v[14:15], v[110:111], v[46:47]
	v_cvt_pk_bf16_f32 v212, v104, v105
	v_cvt_pk_bf16_f32 v213, v106, v107
	v_cvt_pk_bf16_f32 v214, v108, v109
	v_cvt_pk_bf16_f32 v215, v110, v111
	global_store_dwordx4 v240, v[104:107], s[28:29] offset:2048
	global_store_dwordx4 v240, v[108:111], s[28:29] offset:2064
	global_store_dwordx4 v242, v[212:215], s[30:31] offset:1024
	v_pk_mul_f32 v[112:113], v[112:113], v[216:217] op_sel:[0,1] op_sel_hi:[1,1]
	v_pk_mul_f32 v[114:115], v[114:115], v[216:217] op_sel:[0,1] op_sel_hi:[1,1]
	v_pk_fma_f32 v[112:113], v[16:17], v[112:113], v[48:49]
	v_pk_fma_f32 v[114:115], v[18:19], v[114:115], v[50:51]
	v_pk_mul_f32 v[116:117], v[116:117], v[216:217] op_sel:[0,1] op_sel_hi:[1,1]
	v_pk_mul_f32 v[118:119], v[118:119], v[216:217] op_sel:[0,1] op_sel_hi:[1,1]
	v_pk_fma_f32 v[116:117], v[20:21], v[116:117], v[52:53]
	v_pk_fma_f32 v[118:119], v[22:23], v[118:119], v[54:55]
	v_cvt_pk_bf16_f32 v208, v112, v113
	v_cvt_pk_bf16_f32 v209, v114, v115
	v_cvt_pk_bf16_f32 v210, v116, v117
	v_cvt_pk_bf16_f32 v211, v118, v119
	global_store_dwordx4 v241, v[112:115], s[28:29]
	global_store_dwordx4 v241, v[116:119], s[28:29] offset:16
	global_store_dwordx4 v242, v[208:211], s[30:31] offset:2048
	v_pk_mul_f32 v[120:121], v[120:121], v[216:217] op_sel:[0,1] op_sel_hi:[1,1]
	v_pk_mul_f32 v[122:123], v[122:123], v[216:217] op_sel:[0,1] op_sel_hi:[1,1]
	v_pk_fma_f32 v[120:121], v[24:25], v[120:121], v[56:57]
	v_pk_fma_f32 v[122:123], v[26:27], v[122:123], v[58:59]
	v_pk_mul_f32 v[124:125], v[124:125], v[216:217] op_sel:[0,1] op_sel_hi:[1,1]
	v_pk_mul_f32 v[126:127], v[126:127], v[216:217] op_sel:[0,1] op_sel_hi:[1,1]
	v_pk_fma_f32 v[124:125], v[28:29], v[124:125], v[60:61]
	v_pk_fma_f32 v[126:127], v[30:31], v[126:127], v[62:63]
	v_cvt_pk_bf16_f32 v212, v120, v121
	v_cvt_pk_bf16_f32 v213, v122, v123
	v_cvt_pk_bf16_f32 v214, v124, v125
	v_cvt_pk_bf16_f32 v215, v126, v127
	global_store_dwordx4 v241, v[120:123], s[28:29] offset:2048
	global_store_dwordx4 v241, v[124:127], s[28:29] offset:2064
	global_store_dwordx4 v242, v[212:215], s[30:31] offset:3072
	s_add_u32 s20, s20, s21
	s_cmp_ge_u32 s20, 0x4000
	s_cbranch_scc1 .Lln2a_done
	s_mul_i32 s23, s21, 3
	s_add_u32 s23, s20, s23
	s_min_u32 s23, s23, 0x3fff
	s_lshl_b32 s23, s23, 13
	s_add_u32 s24, s12, s23
	s_addc_u32 s25, s13, 0
	global_load_dwordx4 v[96:99], v240, s[24:25]
	global_load_dwordx4 v[100:103], v240, s[24:25] offset:16
	global_load_dwordx4 v[104:107], v240, s[24:25] offset:2048
	global_load_dwordx4 v[108:111], v240, s[24:25] offset:2064
	global_load_dwordx4 v[112:115], v241, s[24:25]
	global_load_dwordx4 v[116:119], v241, s[24:25] offset:16
	global_load_dwordx4 v[120:123], v241, s[24:25] offset:2048
	global_load_dwordx4 v[124:127], v241, s[24:25] offset:2064
	s_waitcnt vmcnt(60)
	v_pk_add_f32 v[236:237], v[128:129], v[130:131]
	v_pk_add_f32 v[236:237], v[236:237], v[132:133]
	v_pk_add_f32 v[236:237], v[236:237], v[134:135]
	v_pk_add_f32 v[236:237], v[236:237], v[136:137]
	v_pk_add_f32 v[236:237], v[236:237], v[138:139]
	v_pk_add_f32 v[236:237], v[236:237], v[140:141]
	v_pk_add_f32 v[236:237], v[236:237], v[142:143]
	v_pk_add_f32 v[236:237], v[236:237], v[144:145]
	v_pk_add_f32 v[236:237], v[236:237], v[146:147]
	v_pk_add_f32 v[236:237], v[236:237], v[148:149]
	v_pk_add_f32 v[236:237], v[236:237], v[150:151]
	v_pk_add_f32 v[236:237], v[236:237], v[152:153]
	v_pk_add_f32 v[236:237], v[236:237], v[154:155]
	v_pk_add_f32 v[236:237], v[236:237], v[156:157]
	v_pk_add_f32 v[236:237], v[236:237], v[158:159]
	v_add_f32_e32 v234, v236, v237
	s_nop 1
	v_add_f32_dpp v234, v234, v234 quad_perm:[1,0,3,2] row_mask:0xf bank_mask:0xf
	s_nop 1
	v_add_f32_dpp v234, v234, v234 quad_perm:[2,3,0,1] row_mask:0xf bank_mask:0xf
	s_nop 1
	v_add_f32_dpp v234, v234, v234 row_half_mirror row_mask:0xf bank_mask:0xf
	s_nop 1
	v_add_f32_dpp v234, v234, v234 row_mirror row_mask:0xf bank_mask:0xf
	s_nop 0
	v_readlane_b32 s26, v234, 0
	v_readlane_b32 s27, v234, 16
	v_readlane_b32 s28, v234, 32
	v_readlane_b32 s29, v234, 48
	v_mov_b32_e32 v234, s26
	v_add_f32_e32 v234, s27, v234
	v_add_f32_e32 v234, s28, v234
	v_add_f32_e32 v234, s29, v234
	v_mul_f32_e32 v216, 0xba000000, v234
	v_pk_add_f32 v[128:129], v[128:129], v[216:217] op_sel_hi:[1,0]
	v_pk_add_f32 v[130:131], v[130:131], v[216:217] op_sel_hi:[1,0]
	v_pk_add_f32 v[132:133], v[132:133], v[216:217] op_sel_hi:[1,0]
	v_pk_add_f32 v[134:135], v[134:135], v[216:217] op_sel_hi:[1,0]
	v_pk_add_f32 v[136:137], v[136:137], v[216:217] op_sel_hi:[1,0]
	v_pk_add_f32 v[138:139], v[138:139], v[216:217] op_sel_hi:[1,0]
	v_pk_add_f32 v[140:141], v[140:141], v[216:217] op_sel_hi:[1,0]
	v_pk_add_f32 v[142:143], v[142:143], v[216:217] op_sel_hi:[1,0]
	v_pk_add_f32 v[144:145], v[144:145], v[216:217] op_sel_hi:[1,0]
	v_pk_add_f32 v[146:147], v[146:147], v[216:217] op_sel_hi:[1,0]
	v_pk_add_f32 v[148:149], v[148:149], v[216:217] op_sel_hi:[1,0]
	v_pk_add_f32 v[150:151], v[150:151], v[216:217] op_sel_hi:[1,0]
	v_pk_add_f32 v[152:153], v[152:153], v[216:217] op_sel_hi:[1,0]
	v_pk_add_f32 v[154:155], v[154:155], v[216:217] op_sel_hi:[1,0]
	v_pk_add_f32 v[156:157], v[156:157], v[216:217] op_sel_hi:[1,0]
; __device__ __forceinline__ void ln_phase(const float* in, float* outf, bf16_t* outb, const float* g, const float* b, int wv0) {
;     ...
;     float sq = 0.f;
; #pragma unroll
;     for (int i = 0; i < 8; ++i) { v[i] -= mu; sq += v[i][0] * v[i][0] + v[i][1] * v[i][1] + v[i][2] * v[i][2] + v[i][3] * v[i][3]; }
;     sq = wave_sum(sq); const float rstd = __builtin_amdgcn_rsqf(sq * (1.0f / 2048.0f) + EPS);
; #pragma unroll
;     for (int i = 0; i < 8; ++i) {
;       const f32x4 y = v[i] * rstd * gg[i] + bb[i];
;       ((f32x4*)(outf + (size_t)row * DM))[i * 64 + lane] = y;
;       if (outb) { u32x2 w; w.x = pk2(y[0], y[1]); w.y = pk2(y[2], y[3]); ((u32x2*)(outb + (size_t)row * DM))[i * 64 + lane] = w; } }
;   }
	v_pk_add_f32 v[158:159], v[158:159], v[216:217] op_sel_hi:[1,0]
	v_pk_mul_f32 v[236:237], v[128:129], v[128:129]
	v_pk_fma_f32 v[236:237], v[130:131], v[130:131], v[236:237]
	v_pk_fma_f32 v[236:237], v[132:133], v[132:133], v[236:237]
	v_pk_fma_f32 v[236:237], v[134:135], v[134:135], v[236:237]
	v_pk_fma_f32 v[236:237], v[136:137], v[136:137], v[236:237]
	v_pk_fma_f32 v[236:237], v[138:139], v[138:139], v[236:237]
	v_pk_fma_f32 v[236:237], v[140:141], v[140:141], v[236:237]
	v_pk_fma_f32 v[236:237], v[142:143], v[142:143], v[236:237]
	v_pk_fma_f32 v[236:237], v[144:145], v[144:145], v[236:237]
	v_pk_fma_f32 v[236:237], v[146:147], v[146:147], v[236:237]
	v_pk_fma_f32 v[236:237], v[148:149], v[148:149], v[236:237]
	v_pk_fma_f32 v[236:237], v[150:151], v[150:151], v[236:237]
	v_pk_fma_f32 v[236:237], v[152:153], v[152:153], v[236:237]
	v_pk_fma_f32 v[236:237], v[154:155], v[154:155], v[236:237]
	v_pk_fma_f32 v[236:237], v[156:157], v[156:157], v[236:237]
	v_pk_fma_f32 v[236:237], v[158:159], v[158:159], v[236:237]
	v_add_f32_e32 v235, v236, v237
	s_nop 1
	v_add_f32_dpp v235, v235, v235 quad_perm:[1,0,3,2] row_mask:0xf bank_mask:0xf
	s_nop 1
	v_add_f32_dpp v235, v235, v235 quad_perm:[2,3,0,1] row_mask:0xf bank_mask:0xf
	s_nop 1
	v_add_f32_dpp v235, v235, v235 row_half_mirror row_mask:0xf bank_mask:0xf
	s_nop 1
	v_add_f32_dpp v235, v235, v235 row_mirror row_mask:0xf bank_mask:0xf
	s_nop 0
	v_readlane_b32 s26, v235, 0
	v_readlane_b32 s27, v235, 16
	v_readlane_b32 s28, v235, 32
	v_readlane_b32 s29, v235, 48
	v_mov_b32_e32 v235, s26
	v_add_f32_e32 v235, s27, v235
	v_add_f32_e32 v235, s28, v235
	v_add_f32_e32 v235, s29, v235
	v_fmamk_f32 v235, v235, 0x3a000000, v246
	v_rsq_f32_e32 v217, v235
	s_lshl_b32 s23, s20, 13
	s_add_u32 s28, s18, s23
	s_addc_u32 s29, s19, 0
	s_lshr_b32 s23, s23, 1
	s_add_u32 s30, s2, s23
	s_addc_u32 s31, s3, 0
	v_pk_mul_f32 v[128:129], v[128:129], v[216:217] op_sel:[0,1] op_sel_hi:[1,1]
	v_pk_mul_f32 v[130:131], v[130:131], v[216:217] op_sel:[0,1] op_sel_hi:[1,1]
	v_pk_fma_f32 v[128:129], v[0:1], v[128:129], v[32:33]
	v_pk_fma_f32 v[130:131], v[2:3], v[130:131], v[34:35]
	v_pk_mul_f32 v[132:133], v[132:133], v[216:217] op_sel:[0,1] op_sel_hi:[1,1]
	v_pk_mul_f32 v[134:135], v[134:135], v[216:217] op_sel:[0,1] op_sel_hi:[1,1]
	v_pk_fma_f32 v[132:133], v[4:5], v[132:133], v[36:37]
	v_pk_fma_f32 v[134:135], v[6:7], v[134:135], v[38:39]
	v_cvt_pk_bf16_f32 v208, v128, v129
	v_cvt_pk_bf16_f32 v209, v130, v131
	v_cvt_pk_bf16_f32 v210, v132, v133
	v_cvt_pk_bf16_f32 v211, v134, v135
	global_store_dwordx4 v240, v[128:131], s[28:29]
	global_store_dwordx4 v240, v[132:135], s[28:29] offset:16
	global_store_dwordx4 v242, v[208:211], s[30:31]
	v_pk_mul_f32 v[136:137], v[136:137], v[216:217] op_sel:[0,1] op_sel_hi:[1,1]
	v_pk_mul_f32 v[138:139], v[138:139], v[216:217] op_sel:[0,1] op_sel_hi:[1,1]
	v_pk_fma_f32 v[136:137], v[8:9], v[136:137], v[40:41]
	v_pk_fma_f32 v[138:139], v[10:11], v[138:139], v[42:43]
	v_pk_mul_f32 v[140:141], v[140:141], v[216:217] op_sel:[0,1] op_sel_hi:[1,1]
	v_pk_mul_f32 v[142:143], v[142:143], v[216:217] op_sel:[0,1] op_sel_hi:[1,1]
	v_pk_fma_f32 v[140:141], v[12:13], v[140:141], v[44:45]
	v_pk_fma_f32 v[142:143], v[14:15], v[142:143], v[46:47]
	v_cvt_pk_bf16_f32 v212, v136, v137
	v_cvt_pk_bf16_f32 v213, v138, v139
	v_cvt_pk_bf16_f32 v214, v140, v141
	v_cvt_pk_bf16_f32 v215, v142, v143
	global_store_dwordx4 v240, v[136:139], s[28:29] offset:2048
	global_store_dwordx4 v240, v[140:143], s[28:29] offset:2064
	global_store_dwordx4 v242, v[212:215], s[30:31] offset:1024
	v_pk_mul_f32 v[144:145], v[144:145], v[216:217] op_sel:[0,1] op_sel_hi:[1,1]
	v_pk_mul_f32 v[146:147], v[146:147], v[216:217] op_sel:[0,1] op_sel_hi:[1,1]
	v_pk_fma_f32 v[144:145], v[16:17], v[144:145], v[48:49]
	v_pk_fma_f32 v[146:147], v[18:19], v[146:147], v[50:51]
	v_pk_mul_f32 v[148:149], v[148:149], v[216:217] op_sel:[0,1] op_sel_hi:[1,1]
	v_pk_mul_f32 v[150:151], v[150:151], v[216:217] op_sel:[0,1] op_sel_hi:[1,1]
	v_pk_fma_f32 v[148:149], v[20:21], v[148:149], v[52:53]
	v_pk_fma_f32 v[150:151], v[22:23], v[150:151], v[54:55]
	v_cvt_pk_bf16_f32 v208, v144, v145
	v_cvt_pk_bf16_f32 v209, v146, v147
	v_cvt_pk_bf16_f32 v210, v148, v149
	v_cvt_pk_bf16_f32 v211, v150, v151
	global_store_dwordx4 v241, v[144:147], s[28:29]
	global_store_dwordx4 v241, v[148:151], s[28:29] offset:16
	global_store_dwordx4 v242, v[208:211], s[30:31] offset:2048
	v_pk_mul_f32 v[152:153], v[152:153], v[216:217] op_sel:[0,1] op_sel_hi:[1,1]
	v_pk_mul_f32 v[154:155], v[154:155], v[216:217] op_sel:[0,1] op_sel_hi:[1,1]
	v_pk_fma_f32 v[152:153], v[24:25], v[152:153], v[56:57]
	v_pk_fma_f32 v[154:155], v[26:27], v[154:155], v[58:59]
	v_pk_mul_f32 v[156:157], v[156:157], v[216:217] op_sel:[0,1] op_sel_hi:[1,1]
	v_pk_mul_f32 v[158:159], v[158:159], v[216:217] op_sel:[0,1] op_sel_hi:[1,1]
	v_pk_fma_f32 v[156:157], v[28:29], v[156:157], v[60:61]
	v_pk_fma_f32 v[158:159], v[30:31], v[158:159], v[62:63]
	v_cvt_pk_bf16_f32 v212, v152, v153
	v_cvt_pk_bf16_f32 v213, v154, v155
	v_cvt_pk_bf16_f32 v214, v156, v157
	v_cvt_pk_bf16_f32 v215, v158, v159
	global_store_dwordx4 v241, v[152:155], s[28:29] offset:2048
	global_store_dwordx4 v241, v[156:159], s[28:29] offset:2064
	global_store_dwordx4 v242, v[212:215], s[30:31] offset:3072
	s_add_u32 s20, s20, s21
	s_cmp_ge_u32 s20, 0x4000
	s_cbranch_scc1 .Lln2a_done
	s_branch .Lln2a_loop
.Lln2a_done:
	s_waitcnt vmcnt(0)
	s_branch .Lln2_end
; __device__ __forceinline__ int otid(int wv0) { int t = (wv0 << 6) | olane(); asm volatile("" : "+v"(t)); return t; }
; __device__ __forceinline__ int obid() { int b = blockIdx.x; asm volatile("" : "+s"(b)); return b; }
; __device__ __forceinline__ int ogrid() { int g = gridDim.x; asm volatile("" : "+s"(g)); return g; }
; __device__ __forceinline__ void ln_phase(const float* in, float* outf, bf16_t* outb, const float* g, const float* b, int wv0) {
;   const int tid_ = otid(wv0); const int lane = tid_ & 63, wv = obid() * 8 + (tid_ >> 6), nwv = ogrid() * 8;
;   f32x4 gg[8], bb[8];
; #pragma unroll
;   for (int i = 0; i < 8; ++i) { gg[i] = ((const f32x4*)g)[i * 64 + lane]; bb[i] = ((const f32x4*)b)[i * 64 + lane]; }
;   f32x4 vn[8];
;   if (wv < NTOK) { const f32x4* ir = (const f32x4*)(in + (size_t)wv * DM);
; #pragma unroll
;     for (int i = 0; i < 8; ++i) vn[i] = ir[i * 64 + lane]; }
;   for (int row = wv; row < NTOK; row += nwv) {
;     f32x4 v[8]; float s = 0.f;
; #pragma unroll
;     for (int i = 0; i < 8; ++i) v[i] = vn[i];
;     if (row + nwv < NTOK) { const f32x4* ir = (const f32x4*)(in + (size_t)(row + nwv) * DM);
; #pragma unroll
;       for (int i = 0; i < 8; ++i) vn[i] = ir[i * 64 + lane]; }
; #pragma unroll
;     for (int i = 0; i < 8; ++i) s += v[i][0] + v[i][1] + v[i][2] + v[i][3];
;     s = wave_sum(s); const float mu = s * (1.0f / 2048.0f);
.Lln2_last:
	v_mbcnt_lo_u32_b32 v243, -1, 0
	v_mbcnt_hi_u32_b32 v243, -1, v243
	v_lshlrev_b32_e32 v240, 5, v243
	v_add_u32_e32 v241, 0x1000, v240
	v_lshlrev_b32_e32 v242, 4, v243
	s_lshl_b32 s20, s82, 3
	s_add_u32 s20, s20, s53
	s_lshl_b32 s21, s60, 3
	global_load_dwordx4 v[0:3], v240, s[16:17]
	global_load_dwordx4 v[4:7], v240, s[16:17] offset:16
	global_load_dwordx4 v[8:11], v240, s[16:17] offset:2048
	global_load_dwordx4 v[12:15], v240, s[16:17] offset:2064
	global_load_dwordx4 v[16:19], v241, s[16:17]
	global_load_dwordx4 v[20:23], v241, s[16:17] offset:16
	global_load_dwordx4 v[24:27], v241, s[16:17] offset:2048
	global_load_dwordx4 v[28:31], v241, s[16:17] offset:2064
	global_load_dwordx4 v[32:35], v240, s[14:15]
	global_load_dwordx4 v[36:39], v240, s[14:15] offset:16
	global_load_dwordx4 v[40:43], v240, s[14:15] offset:2048
	global_load_dwordx4 v[44:47], v240, s[14:15] offset:2064
	global_load_dwordx4 v[48:51], v241, s[14:15]
	global_load_dwordx4 v[52:55], v241, s[14:15] offset:16
	global_load_dwordx4 v[56:59], v241, s[14:15] offset:2048
	global_load_dwordx4 v[60:63], v241, s[14:15] offset:2064
	s_mov_b32 s23, s20
	s_min_u32 s23, s23, 0x3fff
	s_lshl_b32 s23, s23, 13
	s_add_u32 s24, s12, s23
	s_addc_u32 s25, s13, 0
	global_load_dwordx4 v[64:67], v240, s[24:25]
	global_load_dwordx4 v[68:71], v240, s[24:25] offset:16
	global_load_dwordx4 v[72:75], v240, s[24:25] offset:2048
	global_load_dwordx4 v[76:79], v240, s[24:25] offset:2064
	global_load_dwordx4 v[80:83], v241, s[24:25]
	global_load_dwordx4 v[84:87], v241, s[24:25] offset:16
	global_load_dwordx4 v[88:91], v241, s[24:25] offset:2048
	global_load_dwordx4 v[92:95], v241, s[24:25] offset:2064
	s_mul_i32 s23, s21, 1
	s_add_u32 s23, s20, s23
	s_min_u32 s23, s23, 0x3fff
	s_lshl_b32 s23, s23, 13
	s_add_u32 s24, s12, s23
	s_addc_u32 s25, s13, 0
	global_load_dwordx4 v[96:99], v240, s[24:25]
	global_load_dwordx4 v[100:103], v240, s[24:25] offset:16
	global_load_dwordx4 v[104:107], v240, s[24:25] offset:2048
	global_load_dwordx4 v[108:111], v240, s[24:25] offset:2064
	global_load_dwordx4 v[112:115], v241, s[24:25]
	global_load_dwordx4 v[116:119], v241, s[24:25] offset:16
	global_load_dwordx4 v[120:123], v241, s[24:25] offset:2048
	global_load_dwordx4 v[124:127], v241, s[24:25] offset:2064
	s_mul_i32 s23, s21, 2
	s_add_u32 s23, s20, s23
	s_min_u32 s23, s23, 0x3fff
	s_lshl_b32 s23, s23, 13
	s_add_u32 s24, s12, s23
	s_addc_u32 s25, s13, 0
	global_load_dwordx4 v[128:131], v240, s[24:25]
	global_load_dwordx4 v[132:135], v240, s[24:25] offset:16
	global_load_dwordx4 v[136:139], v240, s[24:25] offset:2048
	global_load_dwordx4 v[140:143], v240, s[24:25] offset:2064
	global_load_dwordx4 v[144:147], v241, s[24:25]
	global_load_dwordx4 v[148:151], v241, s[24:25] offset:16
	global_load_dwordx4 v[152:155], v241, s[24:25] offset:2048
	global_load_dwordx4 v[156:159], v241, s[24:25] offset:2064
	s_mul_i32 s23, s21, 3
	s_add_u32 s23, s20, s23
	s_min_u32 s23, s23, 0x3fff
	s_lshl_b32 s23, s23, 13
	s_add_u32 s24, s12, s23
	s_addc_u32 s25, s13, 0
	global_load_dwordx4 v[176:179], v240, s[24:25]
	global_load_dwordx4 v[180:183], v240, s[24:25] offset:16
	global_load_dwordx4 v[184:187], v240, s[24:25] offset:2048
	global_load_dwordx4 v[188:191], v240, s[24:25] offset:2064
	global_load_dwordx4 v[192:195], v241, s[24:25]
	global_load_dwordx4 v[196:199], v241, s[24:25] offset:16
	global_load_dwordx4 v[200:203], v241, s[24:25] offset:2048
	global_load_dwordx4 v[204:207], v241, s[24:25] offset:2064
	s_waitcnt vmcnt(24)
	v_pk_add_f32 v[236:237], v[64:65], v[66:67]
	v_pk_add_f32 v[236:237], v[236:237], v[68:69]
	v_pk_add_f32 v[236:237], v[236:237], v[70:71]
	v_pk_add_f32 v[236:237], v[236:237], v[72:73]
	v_pk_add_f32 v[236:237], v[236:237], v[74:75]
	v_pk_add_f32 v[236:237], v[236:237], v[76:77]
	v_pk_add_f32 v[236:237], v[236:237], v[78:79]
	v_pk_add_f32 v[236:237], v[236:237], v[80:81]
	v_pk_add_f32 v[236:237], v[236:237], v[82:83]
	v_pk_add_f32 v[236:237], v[236:237], v[84:85]
	v_pk_add_f32 v[236:237], v[236:237], v[86:87]
	v_pk_add_f32 v[236:237], v[236:237], v[88:89]
	v_pk_add_f32 v[236:237], v[236:237], v[90:91]
	v_pk_add_f32 v[236:237], v[236:237], v[92:93]
	v_pk_add_f32 v[236:237], v[236:237], v[94:95]
	v_add_f32_e32 v234, v236, v237
	s_nop 1
	v_add_f32_dpp v234, v234, v234 quad_perm:[1,0,3,2] row_mask:0xf bank_mask:0xf
	s_nop 1
	v_add_f32_dpp v234, v234, v234 quad_perm:[2,3,0,1] row_mask:0xf bank_mask:0xf
	s_nop 1
	v_add_f32_dpp v234, v234, v234 row_half_mirror row_mask:0xf bank_mask:0xf
	s_nop 1
	v_add_f32_dpp v234, v234, v234 row_mirror row_mask:0xf bank_mask:0xf
	s_nop 0
	v_readlane_b32 s26, v234, 0
	v_readlane_b32 s27, v234, 16
	v_readlane_b32 s28, v234, 32
	v_readlane_b32 s29, v234, 48
	v_mov_b32_e32 v234, s26
	v_add_f32_e32 v234, s27, v234
	v_add_f32_e32 v234, s28, v234
	v_add_f32_e32 v234, s29, v234
	v_mul_f32_e32 v216, 0xba000000, v234
	v_pk_add_f32 v[64:65], v[64:65], v[216:217] op_sel_hi:[1,0]
	v_pk_add_f32 v[66:67], v[66:67], v[216:217] op_sel_hi:[1,0]
	v_pk_add_f32 v[68:69], v[68:69], v[216:217] op_sel_hi:[1,0]
	v_pk_add_f32 v[70:71], v[70:71], v[216:217] op_sel_hi:[1,0]
	v_pk_add_f32 v[72:73], v[72:73], v[216:217] op_sel_hi:[1,0]
	v_pk_add_f32 v[74:75], v[74:75], v[216:217] op_sel_hi:[1,0]
	v_pk_add_f32 v[76:77], v[76:77], v[216:217] op_sel_hi:[1,0]
	v_pk_add_f32 v[78:79], v[78:79], v[216:217] op_sel_hi:[1,0]
	v_pk_add_f32 v[80:81], v[80:81], v[216:217] op_sel_hi:[1,0]
	v_pk_add_f32 v[82:83], v[82:83], v[216:217] op_sel_hi:[1,0]
	v_pk_add_f32 v[84:85], v[84:85], v[216:217] op_sel_hi:[1,0]
	v_pk_add_f32 v[86:87], v[86:87], v[216:217] op_sel_hi:[1,0]
	v_pk_add_f32 v[88:89], v[88:89], v[216:217] op_sel_hi:[1,0]
; __device__ __forceinline__ void ln_phase(const float* in, float* outf, bf16_t* outb, const float* g, const float* b, int wv0) {
;     ...
;     s = wave_sum(s); const float mu = s * (1.0f / 2048.0f);
;     float sq = 0.f;
; #pragma unroll
;     for (int i = 0; i < 8; ++i) { v[i] -= mu; sq += v[i][0] * v[i][0] + v[i][1] * v[i][1] + v[i][2] * v[i][2] + v[i][3] * v[i][3]; }
;     sq = wave_sum(sq); const float rstd = __builtin_amdgcn_rsqf(sq * (1.0f / 2048.0f) + EPS);
; #pragma unroll
;     for (int i = 0; i < 8; ++i) {
;       const f32x4 y = v[i] * rstd * gg[i] + bb[i];
;       ((f32x4*)(outf + (size_t)row * DM))[i * 64 + lane] = y;
;       if (outb) { u32x2 w; w.x = pk2(y[0], y[1]); w.y = pk2(y[2], y[3]); ((u32x2*)(outb + (size_t)row * DM))[i * 64 + lane] = w; } }
	v_pk_add_f32 v[90:91], v[90:91], v[216:217] op_sel_hi:[1,0]
	v_pk_add_f32 v[92:93], v[92:93], v[216:217] op_sel_hi:[1,0]
	v_pk_add_f32 v[94:95], v[94:95], v[216:217] op_sel_hi:[1,0]
	v_pk_mul_f32 v[236:237], v[64:65], v[64:65]
	v_pk_fma_f32 v[236:237], v[66:67], v[66:67], v[236:237]
	v_pk_fma_f32 v[236:237], v[68:69], v[68:69], v[236:237]
	v_pk_fma_f32 v[236:237], v[70:71], v[70:71], v[236:237]
	v_pk_fma_f32 v[236:237], v[72:73], v[72:73], v[236:237]
	v_pk_fma_f32 v[236:237], v[74:75], v[74:75], v[236:237]
	v_pk_fma_f32 v[236:237], v[76:77], v[76:77], v[236:237]
	v_pk_fma_f32 v[236:237], v[78:79], v[78:79], v[236:237]
	v_pk_fma_f32 v[236:237], v[80:81], v[80:81], v[236:237]
	v_pk_fma_f32 v[236:237], v[82:83], v[82:83], v[236:237]
	v_pk_fma_f32 v[236:237], v[84:85], v[84:85], v[236:237]
	v_pk_fma_f32 v[236:237], v[86:87], v[86:87], v[236:237]
	v_pk_fma_f32 v[236:237], v[88:89], v[88:89], v[236:237]
	v_pk_fma_f32 v[236:237], v[90:91], v[90:91], v[236:237]
	v_pk_fma_f32 v[236:237], v[92:93], v[92:93], v[236:237]
	v_pk_fma_f32 v[236:237], v[94:95], v[94:95], v[236:237]
	v_add_f32_e32 v235, v236, v237
	s_nop 1
	v_add_f32_dpp v235, v235, v235 quad_perm:[1,0,3,2] row_mask:0xf bank_mask:0xf
	s_nop 1
	v_add_f32_dpp v235, v235, v235 quad_perm:[2,3,0,1] row_mask:0xf bank_mask:0xf
	s_nop 1
	v_add_f32_dpp v235, v235, v235 row_half_mirror row_mask:0xf bank_mask:0xf
	s_nop 1
	v_add_f32_dpp v235, v235, v235 row_mirror row_mask:0xf bank_mask:0xf
	s_nop 0
	v_readlane_b32 s26, v235, 0
	v_readlane_b32 s27, v235, 16
	v_readlane_b32 s28, v235, 32
	v_readlane_b32 s29, v235, 48
	v_mov_b32_e32 v235, s26
	v_add_f32_e32 v235, s27, v235
	v_add_f32_e32 v235, s28, v235
	v_add_f32_e32 v235, s29, v235
	v_fmamk_f32 v235, v235, 0x3a000000, v246
	v_rsq_f32_e32 v217, v235
	s_lshl_b32 s23, s20, 13
	s_add_u32 s28, s18, s23
	s_addc_u32 s29, s19, 0
	v_pk_mul_f32 v[64:65], v[64:65], v[216:217] op_sel:[0,1] op_sel_hi:[1,1]
	v_pk_mul_f32 v[66:67], v[66:67], v[216:217] op_sel:[0,1] op_sel_hi:[1,1]
	v_pk_fma_f32 v[64:65], v[0:1], v[64:65], v[32:33]
	v_pk_fma_f32 v[66:67], v[2:3], v[66:67], v[34:35]
	v_pk_mul_f32 v[68:69], v[68:69], v[216:217] op_sel:[0,1] op_sel_hi:[1,1]
	v_pk_mul_f32 v[70:71], v[70:71], v[216:217] op_sel:[0,1] op_sel_hi:[1,1]
	v_pk_fma_f32 v[68:69], v[4:5], v[68:69], v[36:37]
	v_pk_fma_f32 v[70:71], v[6:7], v[70:71], v[38:39]
	global_store_dwordx4 v240, v[64:67], s[28:29]
	global_store_dwordx4 v240, v[68:71], s[28:29] offset:16
	v_pk_mul_f32 v[72:73], v[72:73], v[216:217] op_sel:[0,1] op_sel_hi:[1,1]
	v_pk_mul_f32 v[74:75], v[74:75], v[216:217] op_sel:[0,1] op_sel_hi:[1,1]
	v_pk_fma_f32 v[72:73], v[8:9], v[72:73], v[40:41]
	v_pk_fma_f32 v[74:75], v[10:11], v[74:75], v[42:43]
	v_pk_mul_f32 v[76:77], v[76:77], v[216:217] op_sel:[0,1] op_sel_hi:[1,1]
	v_pk_mul_f32 v[78:79], v[78:79], v[216:217] op_sel:[0,1] op_sel_hi:[1,1]
	v_pk_fma_f32 v[76:77], v[12:13], v[76:77], v[44:45]
	v_pk_fma_f32 v[78:79], v[14:15], v[78:79], v[46:47]
	global_store_dwordx4 v240, v[72:75], s[28:29] offset:2048
	global_store_dwordx4 v240, v[76:79], s[28:29] offset:2064
	v_pk_mul_f32 v[80:81], v[80:81], v[216:217] op_sel:[0,1] op_sel_hi:[1,1]
	v_pk_mul_f32 v[82:83], v[82:83], v[216:217] op_sel:[0,1] op_sel_hi:[1,1]
	v_pk_fma_f32 v[80:81], v[16:17], v[80:81], v[48:49]
	v_pk_fma_f32 v[82:83], v[18:19], v[82:83], v[50:51]
	v_pk_mul_f32 v[84:85], v[84:85], v[216:217] op_sel:[0,1] op_sel_hi:[1,1]
	v_pk_mul_f32 v[86:87], v[86:87], v[216:217] op_sel:[0,1] op_sel_hi:[1,1]
	v_pk_fma_f32 v[84:85], v[20:21], v[84:85], v[52:53]
	v_pk_fma_f32 v[86:87], v[22:23], v[86:87], v[54:55]
	global_store_dwordx4 v241, v[80:83], s[28:29]
	global_store_dwordx4 v241, v[84:87], s[28:29] offset:16
	v_pk_mul_f32 v[88:89], v[88:89], v[216:217] op_sel:[0,1] op_sel_hi:[1,1]
	v_pk_mul_f32 v[90:91], v[90:91], v[216:217] op_sel:[0,1] op_sel_hi:[1,1]
	v_pk_fma_f32 v[88:89], v[24:25], v[88:89], v[56:57]
	v_pk_fma_f32 v[90:91], v[26:27], v[90:91], v[58:59]
	v_pk_mul_f32 v[92:93], v[92:93], v[216:217] op_sel:[0,1] op_sel_hi:[1,1]
	v_pk_mul_f32 v[94:95], v[94:95], v[216:217] op_sel:[0,1] op_sel_hi:[1,1]
	v_pk_fma_f32 v[92:93], v[28:29], v[92:93], v[60:61]
	v_pk_fma_f32 v[94:95], v[30:31], v[94:95], v[62:63]
	global_store_dwordx4 v241, v[88:91], s[28:29] offset:2048
	global_store_dwordx4 v241, v[92:95], s[28:29] offset:2064
	s_add_u32 s20, s20, s21
	s_cmp_ge_u32 s20, 0x4000
	s_cbranch_scc1 .Lln2b_done
; __device__ __forceinline__ void ln_phase(const float* in, float* outf, bf16_t* outb, const float* g, const float* b, int wv0) {
;     ...
;   for (int row = wv; row < NTOK; row += nwv) {
;     f32x4 v[8]; float s = 0.f;
; #pragma unroll
;     for (int i = 0; i < 8; ++i) v[i] = vn[i];
;     if (row + nwv < NTOK) { const f32x4* ir = (const f32x4*)(in + (size_t)(row + nwv) * DM);
; #pragma unroll
;       for (int i = 0; i < 8; ++i) vn[i] = ir[i * 64 + lane]; }
; #pragma unroll
;     for (int i = 0; i < 8; ++i) s += v[i][0] + v[i][1] + v[i][2] + v[i][3];
;     s = wave_sum(s); const float mu = s * (1.0f / 2048.0f);
;     float sq = 0.f;
; #pragma unroll
;     for (int i = 0; i < 8; ++i) { v[i] -= mu; sq += v[i][0] * v[i][0] + v[i][1] * v[i][1] + v[i][2] * v[i][2] + v[i][3] * v[i][3]; }
;     sq = wave_sum(sq); const float rstd = __builtin_amdgcn_rsqf(sq * (1.0f / 2048.0f) + EPS);
; #pragma unroll
;     for (int i = 0; i < 8; ++i) {
;       const f32x4 y = v[i] * rstd * gg[i] + bb[i];
;       ((f32x4*)(outf + (size_t)row * DM))[i * 64 + lane] = y;
;       if (outb) { u32x2 w; w.x = pk2(y[0], y[1]); w.y = pk2(y[2], y[3]); ((u32x2*)(outb + (size_t)row * DM))[i * 64 + lane] = w; } }
	s_mul_i32 s23, s21, 3
	s_add_u32 s23, s20, s23
	s_min_u32 s23, s23, 0x3fff
	s_lshl_b32 s23, s23, 13
	s_add_u32 s24, s12, s23
	s_addc_u32 s25, s13, 0
	global_load_dwordx4 v[64:67], v240, s[24:25]
	global_load_dwordx4 v[68:71], v240, s[24:25] offset:16
	global_load_dwordx4 v[72:75], v240, s[24:25] offset:2048
	global_load_dwordx4 v[76:79], v240, s[24:25] offset:2064
	global_load_dwordx4 v[80:83], v241, s[24:25]
	global_load_dwordx4 v[84:87], v241, s[24:25] offset:16
	global_load_dwordx4 v[88:91], v241, s[24:25] offset:2048
	global_load_dwordx4 v[92:95], v241, s[24:25] offset:2064
	s_waitcnt vmcnt(32)
	v_pk_add_f32 v[236:237], v[96:97], v[98:99]
	v_pk_add_f32 v[236:237], v[236:237], v[100:101]
	v_pk_add_f32 v[236:237], v[236:237], v[102:103]
	v_pk_add_f32 v[236:237], v[236:237], v[104:105]
	v_pk_add_f32 v[236:237], v[236:237], v[106:107]
	v_pk_add_f32 v[236:237], v[236:237], v[108:109]
	v_pk_add_f32 v[236:237], v[236:237], v[110:111]
	v_pk_add_f32 v[236:237], v[236:237], v[112:113]
	v_pk_add_f32 v[236:237], v[236:237], v[114:115]
	v_pk_add_f32 v[236:237], v[236:237], v[116:117]
	v_pk_add_f32 v[236:237], v[236:237], v[118:119]
	v_pk_add_f32 v[236:237], v[236:237], v[120:121]
	v_pk_add_f32 v[236:237], v[236:237], v[122:123]
	v_pk_add_f32 v[236:237], v[236:237], v[124:125]
	v_pk_add_f32 v[236:237], v[236:237], v[126:127]
	v_add_f32_e32 v234, v236, v237
	s_nop 1
	v_add_f32_dpp v234, v234, v234 quad_perm:[1,0,3,2] row_mask:0xf bank_mask:0xf
	s_nop 1
	v_add_f32_dpp v234, v234, v234 quad_perm:[2,3,0,1] row_mask:0xf bank_mask:0xf
	s_nop 1
	v_add_f32_dpp v234, v234, v234 row_half_mirror row_mask:0xf bank_mask:0xf
	s_nop 1
	v_add_f32_dpp v234, v234, v234 row_mirror row_mask:0xf bank_mask:0xf
	s_nop 0
	v_readlane_b32 s26, v234, 0
	v_readlane_b32 s27, v234, 16
	v_readlane_b32 s28, v234, 32
	v_readlane_b32 s29, v234, 48
	v_mov_b32_e32 v234, s26
	v_add_f32_e32 v234, s27, v234
	v_add_f32_e32 v234, s28, v234
	v_add_f32_e32 v234, s29, v234
	v_mul_f32_e32 v216, 0xba000000, v234
	v_pk_add_f32 v[96:97], v[96:97], v[216:217] op_sel_hi:[1,0]
	v_pk_add_f32 v[98:99], v[98:99], v[216:217] op_sel_hi:[1,0]
	v_pk_add_f32 v[100:101], v[100:101], v[216:217] op_sel_hi:[1,0]
	v_pk_add_f32 v[102:103], v[102:103], v[216:217] op_sel_hi:[1,0]
	v_pk_add_f32 v[104:105], v[104:105], v[216:217] op_sel_hi:[1,0]
	v_pk_add_f32 v[106:107], v[106:107], v[216:217] op_sel_hi:[1,0]
	v_pk_add_f32 v[108:109], v[108:109], v[216:217] op_sel_hi:[1,0]
	v_pk_add_f32 v[110:111], v[110:111], v[216:217] op_sel_hi:[1,0]
	v_pk_add_f32 v[112:113], v[112:113], v[216:217] op_sel_hi:[1,0]
	v_pk_add_f32 v[114:115], v[114:115], v[216:217] op_sel_hi:[1,0]
	v_pk_add_f32 v[116:117], v[116:117], v[216:217] op_sel_hi:[1,0]
	v_pk_add_f32 v[118:119], v[118:119], v[216:217] op_sel_hi:[1,0]
	v_pk_add_f32 v[120:121], v[120:121], v[216:217] op_sel_hi:[1,0]
	v_pk_add_f32 v[122:123], v[122:123], v[216:217] op_sel_hi:[1,0]
	v_pk_add_f32 v[124:125], v[124:125], v[216:217] op_sel_hi:[1,0]
	v_pk_add_f32 v[126:127], v[126:127], v[216:217] op_sel_hi:[1,0]
	v_pk_mul_f32 v[236:237], v[96:97], v[96:97]
	v_pk_fma_f32 v[236:237], v[98:99], v[98:99], v[236:237]
	v_pk_fma_f32 v[236:237], v[100:101], v[100:101], v[236:237]
	v_pk_fma_f32 v[236:237], v[102:103], v[102:103], v[236:237]
	v_pk_fma_f32 v[236:237], v[104:105], v[104:105], v[236:237]
	v_pk_fma_f32 v[236:237], v[106:107], v[106:107], v[236:237]
	v_pk_fma_f32 v[236:237], v[108:109], v[108:109], v[236:237]
	v_pk_fma_f32 v[236:237], v[110:111], v[110:111], v[236:237]
	v_pk_fma_f32 v[236:237], v[112:113], v[112:113], v[236:237]
	v_pk_fma_f32 v[236:237], v[114:115], v[114:115], v[236:237]
	v_pk_fma_f32 v[236:237], v[116:117], v[116:117], v[236:237]
	v_pk_fma_f32 v[236:237], v[118:119], v[118:119], v[236:237]
	v_pk_fma_f32 v[236:237], v[120:121], v[120:121], v[236:237]
	v_pk_fma_f32 v[236:237], v[122:123], v[122:123], v[236:237]
	v_pk_fma_f32 v[236:237], v[124:125], v[124:125], v[236:237]
	v_pk_fma_f32 v[236:237], v[126:127], v[126:127], v[236:237]
	v_add_f32_e32 v235, v236, v237
	s_nop 1
	v_add_f32_dpp v235, v235, v235 quad_perm:[1,0,3,2] row_mask:0xf bank_mask:0xf
	s_nop 1
	v_add_f32_dpp v235, v235, v235 quad_perm:[2,3,0,1] row_mask:0xf bank_mask:0xf
	s_nop 1
	v_add_f32_dpp v235, v235, v235 row_half_mirror row_mask:0xf bank_mask:0xf
	s_nop 1
	v_add_f32_dpp v235, v235, v235 row_mirror row_mask:0xf bank_mask:0xf
	s_nop 0
	v_readlane_b32 s26, v235, 0
	v_readlane_b32 s27, v235, 16
	v_readlane_b32 s28, v235, 32
	v_readlane_b32 s29, v235, 48
	v_mov_b32_e32 v235, s26
	v_add_f32_e32 v235, s27, v235
	v_add_f32_e32 v235, s28, v235
	v_add_f32_e32 v235, s29, v235
	v_fmamk_f32 v235, v235, 0x3a000000, v246
	v_rsq_f32_e32 v217, v235
	s_lshl_b32 s23, s20, 13
	s_add_u32 s28, s18, s23
	s_addc_u32 s29, s19, 0
	v_pk_mul_f32 v[96:97], v[96:97], v[216:217] op_sel:[0,1] op_sel_hi:[1,1]
	v_pk_mul_f32 v[98:99], v[98:99], v[216:217] op_sel:[0,1] op_sel_hi:[1,1]
	v_pk_fma_f32 v[96:97], v[0:1], v[96:97], v[32:33]
	v_pk_fma_f32 v[98:99], v[2:3], v[98:99], v[34:35]
	v_pk_mul_f32 v[100:101], v[100:101], v[216:217] op_sel:[0,1] op_sel_hi:[1,1]
	v_pk_mul_f32 v[102:103], v[102:103], v[216:217] op_sel:[0,1] op_sel_hi:[1,1]
	v_pk_fma_f32 v[100:101], v[4:5], v[100:101], v[36:37]
	v_pk_fma_f32 v[102:103], v[6:7], v[102:103], v[38:39]
	global_store_dwordx4 v240, v[96:99], s[28:29]
	global_store_dwordx4 v240, v[100:103], s[28:29] offset:16
	v_pk_mul_f32 v[104:105], v[104:105], v[216:217] op_sel:[0,1] op_sel_hi:[1,1]
	v_pk_mul_f32 v[106:107], v[106:107], v[216:217] op_sel:[0,1] op_sel_hi:[1,1]
	v_pk_fma_f32 v[104:105], v[8:9], v[104:105], v[40:41]
	v_pk_fma_f32 v[106:107], v[10:11], v[106:107], v[42:43]
; __device__ __forceinline__ void ln_phase(const float* in, float* outf, bf16_t* outb, const float* g, const float* b, int wv0) {
;     ...
;   for (int row = wv; row < NTOK; row += nwv) {
;     f32x4 v[8]; float s = 0.f;
; #pragma unroll
;     for (int i = 0; i < 8; ++i) v[i] = vn[i];
;     if (row + nwv < NTOK) { const f32x4* ir = (const f32x4*)(in + (size_t)(row + nwv) * DM);
; #pragma unroll
;       for (int i = 0; i < 8; ++i) vn[i] = ir[i * 64 + lane]; }
; #pragma unroll
;     for (int i = 0; i < 8; ++i) s += v[i][0] + v[i][1] + v[i][2] + v[i][3];
;     s = wave_sum(s); const float mu = s * (1.0f / 2048.0f);
;     float sq = 0.f;
; #pragma unroll
;     for (int i = 0; i < 8; ++i) { v[i] -= mu; sq += v[i][0] * v[i][0] + v[i][1] * v[i][1] + v[i][2] * v[i][2] + v[i][3] * v[i][3]; }
	v_pk_mul_f32 v[108:109], v[108:109], v[216:217] op_sel:[0,1] op_sel_hi:[1,1]
	v_pk_mul_f32 v[110:111], v[110:111], v[216:217] op_sel:[0,1] op_sel_hi:[1,1]
	v_pk_fma_f32 v[108:109], v[12:13], v[108:109], v[44:45]
	v_pk_fma_f32 v[110:111], v[14:15], v[110:111], v[46:47]
	global_store_dwordx4 v240, v[104:107], s[28:29] offset:2048
	global_store_dwordx4 v240, v[108:111], s[28:29] offset:2064
	v_pk_mul_f32 v[112:113], v[112:113], v[216:217] op_sel:[0,1] op_sel_hi:[1,1]
	v_pk_mul_f32 v[114:115], v[114:115], v[216:217] op_sel:[0,1] op_sel_hi:[1,1]
	v_pk_fma_f32 v[112:113], v[16:17], v[112:113], v[48:49]
	v_pk_fma_f32 v[114:115], v[18:19], v[114:115], v[50:51]
	v_pk_mul_f32 v[116:117], v[116:117], v[216:217] op_sel:[0,1] op_sel_hi:[1,1]
	v_pk_mul_f32 v[118:119], v[118:119], v[216:217] op_sel:[0,1] op_sel_hi:[1,1]
	v_pk_fma_f32 v[116:117], v[20:21], v[116:117], v[52:53]
	v_pk_fma_f32 v[118:119], v[22:23], v[118:119], v[54:55]
	global_store_dwordx4 v241, v[112:115], s[28:29]
	global_store_dwordx4 v241, v[116:119], s[28:29] offset:16
	v_pk_mul_f32 v[120:121], v[120:121], v[216:217] op_sel:[0,1] op_sel_hi:[1,1]
	v_pk_mul_f32 v[122:123], v[122:123], v[216:217] op_sel:[0,1] op_sel_hi:[1,1]
	v_pk_fma_f32 v[120:121], v[24:25], v[120:121], v[56:57]
	v_pk_fma_f32 v[122:123], v[26:27], v[122:123], v[58:59]
	v_pk_mul_f32 v[124:125], v[124:125], v[216:217] op_sel:[0,1] op_sel_hi:[1,1]
	v_pk_mul_f32 v[126:127], v[126:127], v[216:217] op_sel:[0,1] op_sel_hi:[1,1]
	v_pk_fma_f32 v[124:125], v[28:29], v[124:125], v[60:61]
	v_pk_fma_f32 v[126:127], v[30:31], v[126:127], v[62:63]
	global_store_dwordx4 v241, v[120:123], s[28:29] offset:2048
	global_store_dwordx4 v241, v[124:127], s[28:29] offset:2064
	s_add_u32 s20, s20, s21
	s_cmp_ge_u32 s20, 0x4000
	s_cbranch_scc1 .Lln2b_done
	s_mul_i32 s23, s21, 3
	s_add_u32 s23, s20, s23
	s_min_u32 s23, s23, 0x3fff
	s_lshl_b32 s23, s23, 13
	s_add_u32 s24, s12, s23
	s_addc_u32 s25, s13, 0
	global_load_dwordx4 v[96:99], v240, s[24:25]
	global_load_dwordx4 v[100:103], v240, s[24:25] offset:16
	global_load_dwordx4 v[104:107], v240, s[24:25] offset:2048
	global_load_dwordx4 v[108:111], v240, s[24:25] offset:2064
	global_load_dwordx4 v[112:115], v241, s[24:25]
	global_load_dwordx4 v[116:119], v241, s[24:25] offset:16
	global_load_dwordx4 v[120:123], v241, s[24:25] offset:2048
	global_load_dwordx4 v[124:127], v241, s[24:25] offset:2064
	s_waitcnt vmcnt(40)
	v_pk_add_f32 v[236:237], v[128:129], v[130:131]
	v_pk_add_f32 v[236:237], v[236:237], v[132:133]
	v_pk_add_f32 v[236:237], v[236:237], v[134:135]
	v_pk_add_f32 v[236:237], v[236:237], v[136:137]
	v_pk_add_f32 v[236:237], v[236:237], v[138:139]
	v_pk_add_f32 v[236:237], v[236:237], v[140:141]
	v_pk_add_f32 v[236:237], v[236:237], v[142:143]
	v_pk_add_f32 v[236:237], v[236:237], v[144:145]
	v_pk_add_f32 v[236:237], v[236:237], v[146:147]
	v_pk_add_f32 v[236:237], v[236:237], v[148:149]
	v_pk_add_f32 v[236:237], v[236:237], v[150:151]
	v_pk_add_f32 v[236:237], v[236:237], v[152:153]
	v_pk_add_f32 v[236:237], v[236:237], v[154:155]
	v_pk_add_f32 v[236:237], v[236:237], v[156:157]
	v_pk_add_f32 v[236:237], v[236:237], v[158:159]
	v_add_f32_e32 v234, v236, v237
	s_nop 1
	v_add_f32_dpp v234, v234, v234 quad_perm:[1,0,3,2] row_mask:0xf bank_mask:0xf
	s_nop 1
	v_add_f32_dpp v234, v234, v234 quad_perm:[2,3,0,1] row_mask:0xf bank_mask:0xf
	s_nop 1
	v_add_f32_dpp v234, v234, v234 row_half_mirror row_mask:0xf bank_mask:0xf
	s_nop 1
	v_add_f32_dpp v234, v234, v234 row_mirror row_mask:0xf bank_mask:0xf
	s_nop 0
	v_readlane_b32 s26, v234, 0
	v_readlane_b32 s27, v234, 16
	v_readlane_b32 s28, v234, 32
	v_readlane_b32 s29, v234, 48
	v_mov_b32_e32 v234, s26
	v_add_f32_e32 v234, s27, v234
	v_add_f32_e32 v234, s28, v234
	v_add_f32_e32 v234, s29, v234
	v_mul_f32_e32 v216, 0xba000000, v234
	v_pk_add_f32 v[128:129], v[128:129], v[216:217] op_sel_hi:[1,0]
	v_pk_add_f32 v[130:131], v[130:131], v[216:217] op_sel_hi:[1,0]
	v_pk_add_f32 v[132:133], v[132:133], v[216:217] op_sel_hi:[1,0]
	v_pk_add_f32 v[134:135], v[134:135], v[216:217] op_sel_hi:[1,0]
	v_pk_add_f32 v[136:137], v[136:137], v[216:217] op_sel_hi:[1,0]
	v_pk_add_f32 v[138:139], v[138:139], v[216:217] op_sel_hi:[1,0]
	v_pk_add_f32 v[140:141], v[140:141], v[216:217] op_sel_hi:[1,0]
	v_pk_add_f32 v[142:143], v[142:143], v[216:217] op_sel_hi:[1,0]
	v_pk_add_f32 v[144:145], v[144:145], v[216:217] op_sel_hi:[1,0]
	v_pk_add_f32 v[146:147], v[146:147], v[216:217] op_sel_hi:[1,0]
	v_pk_add_f32 v[148:149], v[148:149], v[216:217] op_sel_hi:[1,0]
	v_pk_add_f32 v[150:151], v[150:151], v[216:217] op_sel_hi:[1,0]
	v_pk_add_f32 v[152:153], v[152:153], v[216:217] op_sel_hi:[1,0]
	v_pk_add_f32 v[154:155], v[154:155], v[216:217] op_sel_hi:[1,0]
	v_pk_add_f32 v[156:157], v[156:157], v[216:217] op_sel_hi:[1,0]
	v_pk_add_f32 v[158:159], v[158:159], v[216:217] op_sel_hi:[1,0]
	v_pk_mul_f32 v[236:237], v[128:129], v[128:129]
	v_pk_fma_f32 v[236:237], v[130:131], v[130:131], v[236:237]
	v_pk_fma_f32 v[236:237], v[132:133], v[132:133], v[236:237]
	v_pk_fma_f32 v[236:237], v[134:135], v[134:135], v[236:237]
	v_pk_fma_f32 v[236:237], v[136:137], v[136:137], v[236:237]
	v_pk_fma_f32 v[236:237], v[138:139], v[138:139], v[236:237]
	v_pk_fma_f32 v[236:237], v[140:141], v[140:141], v[236:237]
	v_pk_fma_f32 v[236:237], v[142:143], v[142:143], v[236:237]
	v_pk_fma_f32 v[236:237], v[144:145], v[144:145], v[236:237]
	v_pk_fma_f32 v[236:237], v[146:147], v[146:147], v[236:237]
	v_pk_fma_f32 v[236:237], v[148:149], v[148:149], v[236:237]
	v_pk_fma_f32 v[236:237], v[150:151], v[150:151], v[236:237]
	v_pk_fma_f32 v[236:237], v[152:153], v[152:153], v[236:237]
; __device__ __forceinline__ void ln_phase(const float* in, float* outf, bf16_t* outb, const float* g, const float* b, int wv0) {
;     ...
;   for (int row = wv; row < NTOK; row += nwv) {
;     f32x4 v[8]; float s = 0.f;
; #pragma unroll
;     for (int i = 0; i < 8; ++i) v[i] = vn[i];
;     if (row + nwv < NTOK) { const f32x4* ir = (const f32x4*)(in + (size_t)(row + nwv) * DM);
; #pragma unroll
;       for (int i = 0; i < 8; ++i) vn[i] = ir[i * 64 + lane]; }
; #pragma unroll
;     for (int i = 0; i < 8; ++i) s += v[i][0] + v[i][1] + v[i][2] + v[i][3];
;     s = wave_sum(s); const float mu = s * (1.0f / 2048.0f);
;     float sq = 0.f;
; #pragma unroll
;     for (int i = 0; i < 8; ++i) { v[i] -= mu; sq += v[i][0] * v[i][0] + v[i][1] * v[i][1] + v[i][2] * v[i][2] + v[i][3] * v[i][3]; }
;     sq = wave_sum(sq); const float rstd = __builtin_amdgcn_rsqf(sq * (1.0f / 2048.0f) + EPS);
; #pragma unroll
;     for (int i = 0; i < 8; ++i) {
;       const f32x4 y = v[i] * rstd * gg[i] + bb[i];
;       ((f32x4*)(outf + (size_t)row * DM))[i * 64 + lane] = y;
;       if (outb) { u32x2 w; w.x = pk2(y[0], y[1]); w.y = pk2(y[2], y[3]); ((u32x2*)(outb + (size_t)row * DM))[i * 64 + lane] = w; } }
	v_pk_fma_f32 v[236:237], v[154:155], v[154:155], v[236:237]
	v_pk_fma_f32 v[236:237], v[156:157], v[156:157], v[236:237]
	v_pk_fma_f32 v[236:237], v[158:159], v[158:159], v[236:237]
	v_add_f32_e32 v235, v236, v237
	s_nop 1
	v_add_f32_dpp v235, v235, v235 quad_perm:[1,0,3,2] row_mask:0xf bank_mask:0xf
	s_nop 1
	v_add_f32_dpp v235, v235, v235 quad_perm:[2,3,0,1] row_mask:0xf bank_mask:0xf
	s_nop 1
	v_add_f32_dpp v235, v235, v235 row_half_mirror row_mask:0xf bank_mask:0xf
	s_nop 1
	v_add_f32_dpp v235, v235, v235 row_mirror row_mask:0xf bank_mask:0xf
	s_nop 0
	v_readlane_b32 s26, v235, 0
	v_readlane_b32 s27, v235, 16
	v_readlane_b32 s28, v235, 32
	v_readlane_b32 s29, v235, 48
	v_mov_b32_e32 v235, s26
	v_add_f32_e32 v235, s27, v235
	v_add_f32_e32 v235, s28, v235
	v_add_f32_e32 v235, s29, v235
	v_fmamk_f32 v235, v235, 0x3a000000, v246
	v_rsq_f32_e32 v217, v235
	s_lshl_b32 s23, s20, 13
	s_add_u32 s28, s18, s23
	s_addc_u32 s29, s19, 0
	v_pk_mul_f32 v[128:129], v[128:129], v[216:217] op_sel:[0,1] op_sel_hi:[1,1]
	v_pk_mul_f32 v[130:131], v[130:131], v[216:217] op_sel:[0,1] op_sel_hi:[1,1]
	v_pk_fma_f32 v[128:129], v[0:1], v[128:129], v[32:33]
	v_pk_fma_f32 v[130:131], v[2:3], v[130:131], v[34:35]
	v_pk_mul_f32 v[132:133], v[132:133], v[216:217] op_sel:[0,1] op_sel_hi:[1,1]
	v_pk_mul_f32 v[134:135], v[134:135], v[216:217] op_sel:[0,1] op_sel_hi:[1,1]
	v_pk_fma_f32 v[132:133], v[4:5], v[132:133], v[36:37]
	v_pk_fma_f32 v[134:135], v[6:7], v[134:135], v[38:39]
	global_store_dwordx4 v240, v[128:131], s[28:29]
	global_store_dwordx4 v240, v[132:135], s[28:29] offset:16
	v_pk_mul_f32 v[136:137], v[136:137], v[216:217] op_sel:[0,1] op_sel_hi:[1,1]
	v_pk_mul_f32 v[138:139], v[138:139], v[216:217] op_sel:[0,1] op_sel_hi:[1,1]
	v_pk_fma_f32 v[136:137], v[8:9], v[136:137], v[40:41]
	v_pk_fma_f32 v[138:139], v[10:11], v[138:139], v[42:43]
	v_pk_mul_f32 v[140:141], v[140:141], v[216:217] op_sel:[0,1] op_sel_hi:[1,1]
	v_pk_mul_f32 v[142:143], v[142:143], v[216:217] op_sel:[0,1] op_sel_hi:[1,1]
	v_pk_fma_f32 v[140:141], v[12:13], v[140:141], v[44:45]
	v_pk_fma_f32 v[142:143], v[14:15], v[142:143], v[46:47]
	global_store_dwordx4 v240, v[136:139], s[28:29] offset:2048
	global_store_dwordx4 v240, v[140:143], s[28:29] offset:2064
	v_pk_mul_f32 v[144:145], v[144:145], v[216:217] op_sel:[0,1] op_sel_hi:[1,1]
	v_pk_mul_f32 v[146:147], v[146:147], v[216:217] op_sel:[0,1] op_sel_hi:[1,1]
	v_pk_fma_f32 v[144:145], v[16:17], v[144:145], v[48:49]
	v_pk_fma_f32 v[146:147], v[18:19], v[146:147], v[50:51]
	v_pk_mul_f32 v[148:149], v[148:149], v[216:217] op_sel:[0,1] op_sel_hi:[1,1]
	v_pk_mul_f32 v[150:151], v[150:151], v[216:217] op_sel:[0,1] op_sel_hi:[1,1]
	v_pk_fma_f32 v[148:149], v[20:21], v[148:149], v[52:53]
	v_pk_fma_f32 v[150:151], v[22:23], v[150:151], v[54:55]
	global_store_dwordx4 v241, v[144:147], s[28:29]
	global_store_dwordx4 v241, v[148:151], s[28:29] offset:16
	v_pk_mul_f32 v[152:153], v[152:153], v[216:217] op_sel:[0,1] op_sel_hi:[1,1]
	v_pk_mul_f32 v[154:155], v[154:155], v[216:217] op_sel:[0,1] op_sel_hi:[1,1]
	v_pk_fma_f32 v[152:153], v[24:25], v[152:153], v[56:57]
	v_pk_fma_f32 v[154:155], v[26:27], v[154:155], v[58:59]
	v_pk_mul_f32 v[156:157], v[156:157], v[216:217] op_sel:[0,1] op_sel_hi:[1,1]
	v_pk_mul_f32 v[158:159], v[158:159], v[216:217] op_sel:[0,1] op_sel_hi:[1,1]
	v_pk_fma_f32 v[156:157], v[28:29], v[156:157], v[60:61]
	v_pk_fma_f32 v[158:159], v[30:31], v[158:159], v[62:63]
	global_store_dwordx4 v241, v[152:155], s[28:29] offset:2048
	global_store_dwordx4 v241, v[156:159], s[28:29] offset:2064
	s_add_u32 s20, s20, s21
	s_cmp_ge_u32 s20, 0x4000
	s_cbranch_scc1 .Lln2b_done
.Lln2b_loop:
	s_mul_i32 s23, s21, 3
	s_add_u32 s23, s20, s23
	s_min_u32 s23, s23, 0x3fff
	s_lshl_b32 s23, s23, 13
	s_add_u32 s24, s12, s23
	s_addc_u32 s25, s13, 0
	global_load_dwordx4 v[128:131], v240, s[24:25]
	global_load_dwordx4 v[132:135], v240, s[24:25] offset:16
	global_load_dwordx4 v[136:139], v240, s[24:25] offset:2048
	global_load_dwordx4 v[140:143], v240, s[24:25] offset:2064
	global_load_dwordx4 v[144:147], v241, s[24:25]
	global_load_dwordx4 v[148:151], v241, s[24:25] offset:16
	global_load_dwordx4 v[152:155], v241, s[24:25] offset:2048
	global_load_dwordx4 v[156:159], v241, s[24:25] offset:2064
	s_waitcnt vmcnt(48)
; __device__ __forceinline__ void ln_phase(const float* in, float* outf, bf16_t* outb, const float* g, const float* b, int wv0) {
;     ...
;   for (int row = wv; row < NTOK; row += nwv) {
;     f32x4 v[8]; float s = 0.f;
; #pragma unroll
;     for (int i = 0; i < 8; ++i) v[i] = vn[i];
;     if (row + nwv < NTOK) { const f32x4* ir = (const f32x4*)(in + (size_t)(row + nwv) * DM);
; #pragma unroll
;       for (int i = 0; i < 8; ++i) vn[i] = ir[i * 64 + lane]; }
; #pragma unroll
;     for (int i = 0; i < 8; ++i) s += v[i][0] + v[i][1] + v[i][2] + v[i][3];
;     s = wave_sum(s); const float mu = s * (1.0f / 2048.0f);
;     float sq = 0.f;
; #pragma unroll
;     for (int i = 0; i < 8; ++i) { v[i] -= mu; sq += v[i][0] * v[i][0] + v[i][1] * v[i][1] + v[i][2] * v[i][2] + v[i][3] * v[i][3]; }
;     sq = wave_sum(sq); const float rstd = __builtin_amdgcn_rsqf(sq * (1.0f / 2048.0f) + EPS);
; #pragma unroll
;     for (int i = 0; i < 8; ++i) {
;       const f32x4 y = v[i] * rstd * gg[i] + bb[i];
;       ((f32x4*)(outf + (size_t)row * DM))[i * 64 + lane] = y;
;       if (outb) { u32x2 w; w.x = pk2(y[0], y[1]); w.y = pk2(y[2], y[3]); ((u32x2*)(outb + (size_t)row * DM))[i * 64 + lane] = w; } }
	v_pk_add_f32 v[236:237], v[176:177], v[178:179]
	v_pk_add_f32 v[236:237], v[236:237], v[180:181]
	v_pk_add_f32 v[236:237], v[236:237], v[182:183]
	v_pk_add_f32 v[236:237], v[236:237], v[184:185]
	v_pk_add_f32 v[236:237], v[236:237], v[186:187]
	v_pk_add_f32 v[236:237], v[236:237], v[188:189]
	v_pk_add_f32 v[236:237], v[236:237], v[190:191]
	v_pk_add_f32 v[236:237], v[236:237], v[192:193]
	v_pk_add_f32 v[236:237], v[236:237], v[194:195]
	v_pk_add_f32 v[236:237], v[236:237], v[196:197]
	v_pk_add_f32 v[236:237], v[236:237], v[198:199]
	v_pk_add_f32 v[236:237], v[236:237], v[200:201]
	v_pk_add_f32 v[236:237], v[236:237], v[202:203]
	v_pk_add_f32 v[236:237], v[236:237], v[204:205]
	v_pk_add_f32 v[236:237], v[236:237], v[206:207]
	v_add_f32_e32 v234, v236, v237
	s_nop 1
	v_add_f32_dpp v234, v234, v234 quad_perm:[1,0,3,2] row_mask:0xf bank_mask:0xf
	s_nop 1
	v_add_f32_dpp v234, v234, v234 quad_perm:[2,3,0,1] row_mask:0xf bank_mask:0xf
	s_nop 1
	v_add_f32_dpp v234, v234, v234 row_half_mirror row_mask:0xf bank_mask:0xf
	s_nop 1
	v_add_f32_dpp v234, v234, v234 row_mirror row_mask:0xf bank_mask:0xf
	s_nop 0
	v_readlane_b32 s26, v234, 0
	v_readlane_b32 s27, v234, 16
	v_readlane_b32 s28, v234, 32
	v_readlane_b32 s29, v234, 48
	v_mov_b32_e32 v234, s26
	v_add_f32_e32 v234, s27, v234
	v_add_f32_e32 v234, s28, v234
	v_add_f32_e32 v234, s29, v234
	v_mul_f32_e32 v216, 0xba000000, v234
	v_pk_add_f32 v[176:177], v[176:177], v[216:217] op_sel_hi:[1,0]
	v_pk_add_f32 v[178:179], v[178:179], v[216:217] op_sel_hi:[1,0]
	v_pk_add_f32 v[180:181], v[180:181], v[216:217] op_sel_hi:[1,0]
	v_pk_add_f32 v[182:183], v[182:183], v[216:217] op_sel_hi:[1,0]
	v_pk_add_f32 v[184:185], v[184:185], v[216:217] op_sel_hi:[1,0]
	v_pk_add_f32 v[186:187], v[186:187], v[216:217] op_sel_hi:[1,0]
	v_pk_add_f32 v[188:189], v[188:189], v[216:217] op_sel_hi:[1,0]
	v_pk_add_f32 v[190:191], v[190:191], v[216:217] op_sel_hi:[1,0]
	v_pk_add_f32 v[192:193], v[192:193], v[216:217] op_sel_hi:[1,0]
	v_pk_add_f32 v[194:195], v[194:195], v[216:217] op_sel_hi:[1,0]
	v_pk_add_f32 v[196:197], v[196:197], v[216:217] op_sel_hi:[1,0]
	v_pk_add_f32 v[198:199], v[198:199], v[216:217] op_sel_hi:[1,0]
	v_pk_add_f32 v[200:201], v[200:201], v[216:217] op_sel_hi:[1,0]
	v_pk_add_f32 v[202:203], v[202:203], v[216:217] op_sel_hi:[1,0]
	v_pk_add_f32 v[204:205], v[204:205], v[216:217] op_sel_hi:[1,0]
	v_pk_add_f32 v[206:207], v[206:207], v[216:217] op_sel_hi:[1,0]
	v_pk_mul_f32 v[236:237], v[176:177], v[176:177]
	v_pk_fma_f32 v[236:237], v[178:179], v[178:179], v[236:237]
	v_pk_fma_f32 v[236:237], v[180:181], v[180:181], v[236:237]
	v_pk_fma_f32 v[236:237], v[182:183], v[182:183], v[236:237]
	v_pk_fma_f32 v[236:237], v[184:185], v[184:185], v[236:237]
	v_pk_fma_f32 v[236:237], v[186:187], v[186:187], v[236:237]
	v_pk_fma_f32 v[236:237], v[188:189], v[188:189], v[236:237]
	v_pk_fma_f32 v[236:237], v[190:191], v[190:191], v[236:237]
	v_pk_fma_f32 v[236:237], v[192:193], v[192:193], v[236:237]
	v_pk_fma_f32 v[236:237], v[194:195], v[194:195], v[236:237]
	v_pk_fma_f32 v[236:237], v[196:197], v[196:197], v[236:237]
	v_pk_fma_f32 v[236:237], v[198:199], v[198:199], v[236:237]
	v_pk_fma_f32 v[236:237], v[200:201], v[200:201], v[236:237]
	v_pk_fma_f32 v[236:237], v[202:203], v[202:203], v[236:237]
	v_pk_fma_f32 v[236:237], v[204:205], v[204:205], v[236:237]
	v_pk_fma_f32 v[236:237], v[206:207], v[206:207], v[236:237]
	v_add_f32_e32 v235, v236, v237
	s_nop 1
	v_add_f32_dpp v235, v235, v235 quad_perm:[1,0,3,2] row_mask:0xf bank_mask:0xf
	s_nop 1
	v_add_f32_dpp v235, v235, v235 quad_perm:[2,3,0,1] row_mask:0xf bank_mask:0xf
	s_nop 1
	v_add_f32_dpp v235, v235, v235 row_half_mirror row_mask:0xf bank_mask:0xf
	s_nop 1
	v_add_f32_dpp v235, v235, v235 row_mirror row_mask:0xf bank_mask:0xf
	s_nop 0
	v_readlane_b32 s26, v235, 0
	v_readlane_b32 s27, v235, 16
	v_readlane_b32 s28, v235, 32
	v_readlane_b32 s29, v235, 48
	v_mov_b32_e32 v235, s26
	v_add_f32_e32 v235, s27, v235
	v_add_f32_e32 v235, s28, v235
	v_add_f32_e32 v235, s29, v235
	v_fmamk_f32 v235, v235, 0x3a000000, v246
	v_rsq_f32_e32 v217, v235
	s_lshl_b32 s23, s20, 13
	s_add_u32 s28, s18, s23
	s_addc_u32 s29, s19, 0
	v_pk_mul_f32 v[176:177], v[176:177], v[216:217] op_sel:[0,1] op_sel_hi:[1,1]
	v_pk_mul_f32 v[178:179], v[178:179], v[216:217] op_sel:[0,1] op_sel_hi:[1,1]
	v_pk_fma_f32 v[176:177], v[0:1], v[176:177], v[32:33]
	v_pk_fma_f32 v[178:179], v[2:3], v[178:179], v[34:35]
	v_pk_mul_f32 v[180:181], v[180:181], v[216:217] op_sel:[0,1] op_sel_hi:[1,1]
	v_pk_mul_f32 v[182:183], v[182:183], v[216:217] op_sel:[0,1] op_sel_hi:[1,1]
	v_pk_fma_f32 v[180:181], v[4:5], v[180:181], v[36:37]
	v_pk_fma_f32 v[182:183], v[6:7], v[182:183], v[38:39]
	global_store_dwordx4 v240, v[176:179], s[28:29]
	global_store_dwordx4 v240, v[180:183], s[28:29] offset:16
	v_pk_mul_f32 v[184:185], v[184:185], v[216:217] op_sel:[0,1] op_sel_hi:[1,1]
	v_pk_mul_f32 v[186:187], v[186:187], v[216:217] op_sel:[0,1] op_sel_hi:[1,1]
	v_pk_fma_f32 v[184:185], v[8:9], v[184:185], v[40:41]
	v_pk_fma_f32 v[186:187], v[10:11], v[186:187], v[42:43]
	v_pk_mul_f32 v[188:189], v[188:189], v[216:217] op_sel:[0,1] op_sel_hi:[1,1]
	v_pk_mul_f32 v[190:191], v[190:191], v[216:217] op_sel:[0,1] op_sel_hi:[1,1]
	v_pk_fma_f32 v[188:189], v[12:13], v[188:189], v[44:45]
	v_pk_fma_f32 v[190:191], v[14:15], v[190:191], v[46:47]
	global_store_dwordx4 v240, v[184:187], s[28:29] offset:2048
	global_store_dwordx4 v240, v[188:191], s[28:29] offset:2064
	v_pk_mul_f32 v[192:193], v[192:193], v[216:217] op_sel:[0,1] op_sel_hi:[1,1]
	v_pk_mul_f32 v[194:195], v[194:195], v[216:217] op_sel:[0,1] op_sel_hi:[1,1]
	v_pk_fma_f32 v[192:193], v[16:17], v[192:193], v[48:49]
	v_pk_fma_f32 v[194:195], v[18:19], v[194:195], v[50:51]
	v_pk_mul_f32 v[196:197], v[196:197], v[216:217] op_sel:[0,1] op_sel_hi:[1,1]
	v_pk_mul_f32 v[198:199], v[198:199], v[216:217] op_sel:[0,1] op_sel_hi:[1,1]
	v_pk_fma_f32 v[196:197], v[20:21], v[196:197], v[52:53]
	v_pk_fma_f32 v[198:199], v[22:23], v[198:199], v[54:55]
	global_store_dwordx4 v241, v[192:195], s[28:29]
	global_store_dwordx4 v241, v[196:199], s[28:29] offset:16
	v_pk_mul_f32 v[200:201], v[200:201], v[216:217] op_sel:[0,1] op_sel_hi:[1,1]
	v_pk_mul_f32 v[202:203], v[202:203], v[216:217] op_sel:[0,1] op_sel_hi:[1,1]
	v_pk_fma_f32 v[200:201], v[24:25], v[200:201], v[56:57]
	v_pk_fma_f32 v[202:203], v[26:27], v[202:203], v[58:59]
	v_pk_mul_f32 v[204:205], v[204:205], v[216:217] op_sel:[0,1] op_sel_hi:[1,1]
	v_pk_mul_f32 v[206:207], v[206:207], v[216:217] op_sel:[0,1] op_sel_hi:[1,1]
	v_pk_fma_f32 v[204:205], v[28:29], v[204:205], v[60:61]
	v_pk_fma_f32 v[206:207], v[30:31], v[206:207], v[62:63]
	global_store_dwordx4 v241, v[200:203], s[28:29] offset:2048
	global_store_dwordx4 v241, v[204:207], s[28:29] offset:2064
	s_add_u32 s20, s20, s21
	s_cmp_ge_u32 s20, 0x4000
	s_cbranch_scc1 .Lln2b_done
; __device__ __forceinline__ void ln_phase(const float* in, float* outf, bf16_t* outb, const float* g, const float* b, int wv0) {
;     ...
;   for (int row = wv; row < NTOK; row += nwv) {
;     f32x4 v[8]; float s = 0.f;
; #pragma unroll
;     for (int i = 0; i < 8; ++i) v[i] = vn[i];
;     if (row + nwv < NTOK) { const f32x4* ir = (const f32x4*)(in + (size_t)(row + nwv) * DM);
; #pragma unroll
;       for (int i = 0; i < 8; ++i) vn[i] = ir[i * 64 + lane]; }
; #pragma unroll
;     for (int i = 0; i < 8; ++i) s += v[i][0] + v[i][1] + v[i][2] + v[i][3];
;     s = wave_sum(s); const float mu = s * (1.0f / 2048.0f);
;     float sq = 0.f;
; #pragma unroll
;     for (int i = 0; i < 8; ++i) { v[i] -= mu; sq += v[i][0] * v[i][0] + v[i][1] * v[i][1] + v[i][2] * v[i][2] + v[i][3] * v[i][3]; }
;     sq = wave_sum(sq); const float rstd = __builtin_amdgcn_rsqf(sq * (1.0f / 2048.0f) + EPS);
; #pragma unroll
;     for (int i = 0; i < 8; ++i) {
;       const f32x4 y = v[i] * rstd * gg[i] + bb[i];
;       ((f32x4*)(outf + (size_t)row * DM))[i * 64 + lane] = y;
;       if (outb) { u32x2 w; w.x = pk2(y[0], y[1]); w.y = pk2(y[2], y[3]); ((u32x2*)(outb + (size_t)row * DM))[i * 64 + lane] = w; } }
	s_mul_i32 s23, s21, 3
	s_add_u32 s23, s20, s23
	s_min_u32 s23, s23, 0x3fff
	s_lshl_b32 s23, s23, 13
	s_add_u32 s24, s12, s23
	s_addc_u32 s25, s13, 0
	global_load_dwordx4 v[176:179], v240, s[24:25]
	global_load_dwordx4 v[180:183], v240, s[24:25] offset:16
	global_load_dwordx4 v[184:187], v240, s[24:25] offset:2048
	global_load_dwordx4 v[188:191], v240, s[24:25] offset:2064
	global_load_dwordx4 v[192:195], v241, s[24:25]
	global_load_dwordx4 v[196:199], v241, s[24:25] offset:16
	global_load_dwordx4 v[200:203], v241, s[24:25] offset:2048
	global_load_dwordx4 v[204:207], v241, s[24:25] offset:2064
	s_waitcnt vmcnt(48)
	v_pk_add_f32 v[236:237], v[64:65], v[66:67]
	v_pk_add_f32 v[236:237], v[236:237], v[68:69]
	v_pk_add_f32 v[236:237], v[236:237], v[70:71]
	v_pk_add_f32 v[236:237], v[236:237], v[72:73]
	v_pk_add_f32 v[236:237], v[236:237], v[74:75]
	v_pk_add_f32 v[236:237], v[236:237], v[76:77]
	v_pk_add_f32 v[236:237], v[236:237], v[78:79]
	v_pk_add_f32 v[236:237], v[236:237], v[80:81]
	v_pk_add_f32 v[236:237], v[236:237], v[82:83]
	v_pk_add_f32 v[236:237], v[236:237], v[84:85]
	v_pk_add_f32 v[236:237], v[236:237], v[86:87]
	v_pk_add_f32 v[236:237], v[236:237], v[88:89]
	v_pk_add_f32 v[236:237], v[236:237], v[90:91]
	v_pk_add_f32 v[236:237], v[236:237], v[92:93]
	v_pk_add_f32 v[236:237], v[236:237], v[94:95]
	v_add_f32_e32 v234, v236, v237
	s_nop 1
	v_add_f32_dpp v234, v234, v234 quad_perm:[1,0,3,2] row_mask:0xf bank_mask:0xf
	s_nop 1
	v_add_f32_dpp v234, v234, v234 quad_perm:[2,3,0,1] row_mask:0xf bank_mask:0xf
	s_nop 1
	v_add_f32_dpp v234, v234, v234 row_half_mirror row_mask:0xf bank_mask:0xf
	s_nop 1
	v_add_f32_dpp v234, v234, v234 row_mirror row_mask:0xf bank_mask:0xf
	s_nop 0
	v_readlane_b32 s26, v234, 0
	v_readlane_b32 s27, v234, 16
	v_readlane_b32 s28, v234, 32
	v_readlane_b32 s29, v234, 48
	v_mov_b32_e32 v234, s26
	v_add_f32_e32 v234, s27, v234
	v_add_f32_e32 v234, s28, v234
	v_add_f32_e32 v234, s29, v234
	v_mul_f32_e32 v216, 0xba000000, v234
	v_pk_add_f32 v[64:65], v[64:65], v[216:217] op_sel_hi:[1,0]
	v_pk_add_f32 v[66:67], v[66:67], v[216:217] op_sel_hi:[1,0]
	v_pk_add_f32 v[68:69], v[68:69], v[216:217] op_sel_hi:[1,0]
	v_pk_add_f32 v[70:71], v[70:71], v[216:217] op_sel_hi:[1,0]
	v_pk_add_f32 v[72:73], v[72:73], v[216:217] op_sel_hi:[1,0]
	v_pk_add_f32 v[74:75], v[74:75], v[216:217] op_sel_hi:[1,0]
	v_pk_add_f32 v[76:77], v[76:77], v[216:217] op_sel_hi:[1,0]
	v_pk_add_f32 v[78:79], v[78:79], v[216:217] op_sel_hi:[1,0]
	v_pk_add_f32 v[80:81], v[80:81], v[216:217] op_sel_hi:[1,0]
	v_pk_add_f32 v[82:83], v[82:83], v[216:217] op_sel_hi:[1,0]
	v_pk_add_f32 v[84:85], v[84:85], v[216:217] op_sel_hi:[1,0]
	v_pk_add_f32 v[86:87], v[86:87], v[216:217] op_sel_hi:[1,0]
	v_pk_add_f32 v[88:89], v[88:89], v[216:217] op_sel_hi:[1,0]
	v_pk_add_f32 v[90:91], v[90:91], v[216:217] op_sel_hi:[1,0]
	v_pk_add_f32 v[92:93], v[92:93], v[216:217] op_sel_hi:[1,0]
	v_pk_add_f32 v[94:95], v[94:95], v[216:217] op_sel_hi:[1,0]
	v_pk_mul_f32 v[236:237], v[64:65], v[64:65]
	v_pk_fma_f32 v[236:237], v[66:67], v[66:67], v[236:237]
	v_pk_fma_f32 v[236:237], v[68:69], v[68:69], v[236:237]
	v_pk_fma_f32 v[236:237], v[70:71], v[70:71], v[236:237]
	v_pk_fma_f32 v[236:237], v[72:73], v[72:73], v[236:237]
	v_pk_fma_f32 v[236:237], v[74:75], v[74:75], v[236:237]
	v_pk_fma_f32 v[236:237], v[76:77], v[76:77], v[236:237]
	v_pk_fma_f32 v[236:237], v[78:79], v[78:79], v[236:237]
	v_pk_fma_f32 v[236:237], v[80:81], v[80:81], v[236:237]
	v_pk_fma_f32 v[236:237], v[82:83], v[82:83], v[236:237]
	v_pk_fma_f32 v[236:237], v[84:85], v[84:85], v[236:237]
	v_pk_fma_f32 v[236:237], v[86:87], v[86:87], v[236:237]
	v_pk_fma_f32 v[236:237], v[88:89], v[88:89], v[236:237]
	v_pk_fma_f32 v[236:237], v[90:91], v[90:91], v[236:237]
	v_pk_fma_f32 v[236:237], v[92:93], v[92:93], v[236:237]
	v_pk_fma_f32 v[236:237], v[94:95], v[94:95], v[236:237]
	v_add_f32_e32 v235, v236, v237
	s_nop 1
	v_add_f32_dpp v235, v235, v235 quad_perm:[1,0,3,2] row_mask:0xf bank_mask:0xf
	s_nop 1
	v_add_f32_dpp v235, v235, v235 quad_perm:[2,3,0,1] row_mask:0xf bank_mask:0xf
	s_nop 1
	v_add_f32_dpp v235, v235, v235 row_half_mirror row_mask:0xf bank_mask:0xf
	s_nop 1
	v_add_f32_dpp v235, v235, v235 row_mirror row_mask:0xf bank_mask:0xf
	s_nop 0
	v_readlane_b32 s26, v235, 0
	v_readlane_b32 s27, v235, 16
	v_readlane_b32 s28, v235, 32
	v_readlane_b32 s29, v235, 48
	v_mov_b32_e32 v235, s26
	v_add_f32_e32 v235, s27, v235
	v_add_f32_e32 v235, s28, v235
	v_add_f32_e32 v235, s29, v235
	v_fmamk_f32 v235, v235, 0x3a000000, v246
	v_rsq_f32_e32 v217, v235
	s_lshl_b32 s23, s20, 13
	s_add_u32 s28, s18, s23
	s_addc_u32 s29, s19, 0
	v_pk_mul_f32 v[64:65], v[64:65], v[216:217] op_sel:[0,1] op_sel_hi:[1,1]
	v_pk_mul_f32 v[66:67], v[66:67], v[216:217] op_sel:[0,1] op_sel_hi:[1,1]
	v_pk_fma_f32 v[64:65], v[0:1], v[64:65], v[32:33]
	v_pk_fma_f32 v[66:67], v[2:3], v[66:67], v[34:35]
	v_pk_mul_f32 v[68:69], v[68:69], v[216:217] op_sel:[0,1] op_sel_hi:[1,1]
	v_pk_mul_f32 v[70:71], v[70:71], v[216:217] op_sel:[0,1] op_sel_hi:[1,1]
	v_pk_fma_f32 v[68:69], v[4:5], v[68:69], v[36:37]
	v_pk_fma_f32 v[70:71], v[6:7], v[70:71], v[38:39]
	global_store_dwordx4 v240, v[64:67], s[28:29]
	global_store_dwordx4 v240, v[68:71], s[28:29] offset:16
	v_pk_mul_f32 v[72:73], v[72:73], v[216:217] op_sel:[0,1] op_sel_hi:[1,1]
	v_pk_mul_f32 v[74:75], v[74:75], v[216:217] op_sel:[0,1] op_sel_hi:[1,1]
	v_pk_fma_f32 v[72:73], v[8:9], v[72:73], v[40:41]
	v_pk_fma_f32 v[74:75], v[10:11], v[74:75], v[42:43]
	v_pk_mul_f32 v[76:77], v[76:77], v[216:217] op_sel:[0,1] op_sel_hi:[1,1]
	v_pk_mul_f32 v[78:79], v[78:79], v[216:217] op_sel:[0,1] op_sel_hi:[1,1]
; __device__ __forceinline__ void ln_phase(const float* in, float* outf, bf16_t* outb, const float* g, const float* b, int wv0) {
;     ...
;   for (int row = wv; row < NTOK; row += nwv) {
;     f32x4 v[8]; float s = 0.f;
; #pragma unroll
;     for (int i = 0; i < 8; ++i) v[i] = vn[i];
;     if (row + nwv < NTOK) { const f32x4* ir = (const f32x4*)(in + (size_t)(row + nwv) * DM);
; #pragma unroll
;       for (int i = 0; i < 8; ++i) vn[i] = ir[i * 64 + lane]; }
; #pragma unroll
;     for (int i = 0; i < 8; ++i) s += v[i][0] + v[i][1] + v[i][2] + v[i][3];
;     s = wave_sum(s); const float mu = s * (1.0f / 2048.0f);
;     float sq = 0.f;
; #pragma unroll
;     for (int i = 0; i < 8; ++i) { v[i] -= mu; sq += v[i][0] * v[i][0] + v[i][1] * v[i][1] + v[i][2] * v[i][2] + v[i][3] * v[i][3]; }
;     sq = wave_sum(sq); const float rstd = __builtin_amdgcn_rsqf(sq * (1.0f / 2048.0f) + EPS);
; #pragma unroll
;     for (int i = 0; i < 8; ++i) {
;       const f32x4 y = v[i] * rstd * gg[i] + bb[i];
;       ((f32x4*)(outf + (size_t)row * DM))[i * 64 + lane] = y;
;       if (outb) { u32x2 w; w.x = pk2(y[0], y[1]); w.y = pk2(y[2], y[3]); ((u32x2*)(outb + (size_t)row * DM))[i * 64 + lane] = w; } }
	v_pk_fma_f32 v[76:77], v[12:13], v[76:77], v[44:45]
	v_pk_fma_f32 v[78:79], v[14:15], v[78:79], v[46:47]
	global_store_dwordx4 v240, v[72:75], s[28:29] offset:2048
	global_store_dwordx4 v240, v[76:79], s[28:29] offset:2064
	v_pk_mul_f32 v[80:81], v[80:81], v[216:217] op_sel:[0,1] op_sel_hi:[1,1]
	v_pk_mul_f32 v[82:83], v[82:83], v[216:217] op_sel:[0,1] op_sel_hi:[1,1]
	v_pk_fma_f32 v[80:81], v[16:17], v[80:81], v[48:49]
	v_pk_fma_f32 v[82:83], v[18:19], v[82:83], v[50:51]
	v_pk_mul_f32 v[84:85], v[84:85], v[216:217] op_sel:[0,1] op_sel_hi:[1,1]
	v_pk_mul_f32 v[86:87], v[86:87], v[216:217] op_sel:[0,1] op_sel_hi:[1,1]
	v_pk_fma_f32 v[84:85], v[20:21], v[84:85], v[52:53]
	v_pk_fma_f32 v[86:87], v[22:23], v[86:87], v[54:55]
	global_store_dwordx4 v241, v[80:83], s[28:29]
	global_store_dwordx4 v241, v[84:87], s[28:29] offset:16
	v_pk_mul_f32 v[88:89], v[88:89], v[216:217] op_sel:[0,1] op_sel_hi:[1,1]
	v_pk_mul_f32 v[90:91], v[90:91], v[216:217] op_sel:[0,1] op_sel_hi:[1,1]
	v_pk_fma_f32 v[88:89], v[24:25], v[88:89], v[56:57]
	v_pk_fma_f32 v[90:91], v[26:27], v[90:91], v[58:59]
	v_pk_mul_f32 v[92:93], v[92:93], v[216:217] op_sel:[0,1] op_sel_hi:[1,1]
	v_pk_mul_f32 v[94:95], v[94:95], v[216:217] op_sel:[0,1] op_sel_hi:[1,1]
	v_pk_fma_f32 v[92:93], v[28:29], v[92:93], v[60:61]
	v_pk_fma_f32 v[94:95], v[30:31], v[94:95], v[62:63]
	global_store_dwordx4 v241, v[88:91], s[28:29] offset:2048
	global_store_dwordx4 v241, v[92:95], s[28:29] offset:2064
	s_add_u32 s20, s20, s21
	s_cmp_ge_u32 s20, 0x4000
	s_cbranch_scc1 .Lln2b_done
	s_mul_i32 s23, s21, 3
	s_add_u32 s23, s20, s23
	s_min_u32 s23, s23, 0x3fff
	s_lshl_b32 s23, s23, 13
	s_add_u32 s24, s12, s23
	s_addc_u32 s25, s13, 0
	global_load_dwordx4 v[64:67], v240, s[24:25]
	global_load_dwordx4 v[68:71], v240, s[24:25] offset:16
	global_load_dwordx4 v[72:75], v240, s[24:25] offset:2048
	global_load_dwordx4 v[76:79], v240, s[24:25] offset:2064
	global_load_dwordx4 v[80:83], v241, s[24:25]
	global_load_dwordx4 v[84:87], v241, s[24:25] offset:16
	global_load_dwordx4 v[88:91], v241, s[24:25] offset:2048
	global_load_dwordx4 v[92:95], v241, s[24:25] offset:2064
	s_waitcnt vmcnt(48)
	v_pk_add_f32 v[236:237], v[96:97], v[98:99]
	v_pk_add_f32 v[236:237], v[236:237], v[100:101]
	v_pk_add_f32 v[236:237], v[236:237], v[102:103]
	v_pk_add_f32 v[236:237], v[236:237], v[104:105]
	v_pk_add_f32 v[236:237], v[236:237], v[106:107]
	v_pk_add_f32 v[236:237], v[236:237], v[108:109]
	v_pk_add_f32 v[236:237], v[236:237], v[110:111]
	v_pk_add_f32 v[236:237], v[236:237], v[112:113]
	v_pk_add_f32 v[236:237], v[236:237], v[114:115]
	v_pk_add_f32 v[236:237], v[236:237], v[116:117]
	v_pk_add_f32 v[236:237], v[236:237], v[118:119]
	v_pk_add_f32 v[236:237], v[236:237], v[120:121]
	v_pk_add_f32 v[236:237], v[236:237], v[122:123]
	v_pk_add_f32 v[236:237], v[236:237], v[124:125]
	v_pk_add_f32 v[236:237], v[236:237], v[126:127]
	v_add_f32_e32 v234, v236, v237
	s_nop 1
	v_add_f32_dpp v234, v234, v234 quad_perm:[1,0,3,2] row_mask:0xf bank_mask:0xf
	s_nop 1
	v_add_f32_dpp v234, v234, v234 quad_perm:[2,3,0,1] row_mask:0xf bank_mask:0xf
	s_nop 1
	v_add_f32_dpp v234, v234, v234 row_half_mirror row_mask:0xf bank_mask:0xf
	s_nop 1
	v_add_f32_dpp v234, v234, v234 row_mirror row_mask:0xf bank_mask:0xf
	s_nop 0
	v_readlane_b32 s26, v234, 0
	v_readlane_b32 s27, v234, 16
	v_readlane_b32 s28, v234, 32
	v_readlane_b32 s29, v234, 48
	v_mov_b32_e32 v234, s26
	v_add_f32_e32 v234, s27, v234
	v_add_f32_e32 v234, s28, v234
	v_add_f32_e32 v234, s29, v234
	v_mul_f32_e32 v216, 0xba000000, v234
	v_pk_add_f32 v[96:97], v[96:97], v[216:217] op_sel_hi:[1,0]
	v_pk_add_f32 v[98:99], v[98:99], v[216:217] op_sel_hi:[1,0]
	v_pk_add_f32 v[100:101], v[100:101], v[216:217] op_sel_hi:[1,0]
	v_pk_add_f32 v[102:103], v[102:103], v[216:217] op_sel_hi:[1,0]
	v_pk_add_f32 v[104:105], v[104:105], v[216:217] op_sel_hi:[1,0]
	v_pk_add_f32 v[106:107], v[106:107], v[216:217] op_sel_hi:[1,0]
	v_pk_add_f32 v[108:109], v[108:109], v[216:217] op_sel_hi:[1,0]
	v_pk_add_f32 v[110:111], v[110:111], v[216:217] op_sel_hi:[1,0]
	v_pk_add_f32 v[112:113], v[112:113], v[216:217] op_sel_hi:[1,0]
	v_pk_add_f32 v[114:115], v[114:115], v[216:217] op_sel_hi:[1,0]
	v_pk_add_f32 v[116:117], v[116:117], v[216:217] op_sel_hi:[1,0]
	v_pk_add_f32 v[118:119], v[118:119], v[216:217] op_sel_hi:[1,0]
	v_pk_add_f32 v[120:121], v[120:121], v[216:217] op_sel_hi:[1,0]
	v_pk_add_f32 v[122:123], v[122:123], v[216:217] op_sel_hi:[1,0]
	v_pk_add_f32 v[124:125], v[124:125], v[216:217] op_sel_hi:[1,0]
	v_pk_add_f32 v[126:127], v[126:127], v[216:217] op_sel_hi:[1,0]
	v_pk_mul_f32 v[236:237], v[96:97], v[96:97]
	v_pk_fma_f32 v[236:237], v[98:99], v[98:99], v[236:237]
	v_pk_fma_f32 v[236:237], v[100:101], v[100:101], v[236:237]
	v_pk_fma_f32 v[236:237], v[102:103], v[102:103], v[236:237]
	v_pk_fma_f32 v[236:237], v[104:105], v[104:105], v[236:237]
	v_pk_fma_f32 v[236:237], v[106:107], v[106:107], v[236:237]
	v_pk_fma_f32 v[236:237], v[108:109], v[108:109], v[236:237]
	v_pk_fma_f32 v[236:237], v[110:111], v[110:111], v[236:237]
	v_pk_fma_f32 v[236:237], v[112:113], v[112:113], v[236:237]
	v_pk_fma_f32 v[236:237], v[114:115], v[114:115], v[236:237]
	v_pk_fma_f32 v[236:237], v[116:117], v[116:117], v[236:237]
	v_pk_fma_f32 v[236:237], v[118:119], v[118:119], v[236:237]
	v_pk_fma_f32 v[236:237], v[120:121], v[120:121], v[236:237]
	v_pk_fma_f32 v[236:237], v[122:123], v[122:123], v[236:237]
	v_pk_fma_f32 v[236:237], v[124:125], v[124:125], v[236:237]
	v_pk_fma_f32 v[236:237], v[126:127], v[126:127], v[236:237]
	v_add_f32_e32 v235, v236, v237
	s_nop 1
	v_add_f32_dpp v235, v235, v235 quad_perm:[1,0,3,2] row_mask:0xf bank_mask:0xf
; __device__ __forceinline__ void ln_phase(const float* in, float* outf, bf16_t* outb, const float* g, const float* b, int wv0) {
;     ...
;   for (int row = wv; row < NTOK; row += nwv) {
;     f32x4 v[8]; float s = 0.f;
; #pragma unroll
;     for (int i = 0; i < 8; ++i) v[i] = vn[i];
;     if (row + nwv < NTOK) { const f32x4* ir = (const f32x4*)(in + (size_t)(row + nwv) * DM);
; #pragma unroll
;       for (int i = 0; i < 8; ++i) vn[i] = ir[i * 64 + lane]; }
; #pragma unroll
;     for (int i = 0; i < 8; ++i) s += v[i][0] + v[i][1] + v[i][2] + v[i][3];
;     s = wave_sum(s); const float mu = s * (1.0f / 2048.0f);
;     float sq = 0.f;
; #pragma unroll
;     for (int i = 0; i < 8; ++i) { v[i] -= mu; sq += v[i][0] * v[i][0] + v[i][1] * v[i][1] + v[i][2] * v[i][2] + v[i][3] * v[i][3]; }
;     sq = wave_sum(sq); const float rstd = __builtin_amdgcn_rsqf(sq * (1.0f / 2048.0f) + EPS);
; #pragma unroll
;     for (int i = 0; i < 8; ++i) {
;       const f32x4 y = v[i] * rstd * gg[i] + bb[i];
;       ((f32x4*)(outf + (size_t)row * DM))[i * 64 + lane] = y;
;       if (outb) { u32x2 w; w.x = pk2(y[0], y[1]); w.y = pk2(y[2], y[3]); ((u32x2*)(outb + (size_t)row * DM))[i * 64 + lane] = w; } }
	s_nop 1
	v_add_f32_dpp v235, v235, v235 quad_perm:[2,3,0,1] row_mask:0xf bank_mask:0xf
	s_nop 1
	v_add_f32_dpp v235, v235, v235 row_half_mirror row_mask:0xf bank_mask:0xf
	s_nop 1
	v_add_f32_dpp v235, v235, v235 row_mirror row_mask:0xf bank_mask:0xf
	s_nop 0
	v_readlane_b32 s26, v235, 0
	v_readlane_b32 s27, v235, 16
	v_readlane_b32 s28, v235, 32
	v_readlane_b32 s29, v235, 48
	v_mov_b32_e32 v235, s26
	v_add_f32_e32 v235, s27, v235
	v_add_f32_e32 v235, s28, v235
	v_add_f32_e32 v235, s29, v235
	v_fmamk_f32 v235, v235, 0x3a000000, v246
	v_rsq_f32_e32 v217, v235
	s_lshl_b32 s23, s20, 13
	s_add_u32 s28, s18, s23
	s_addc_u32 s29, s19, 0
	v_pk_mul_f32 v[96:97], v[96:97], v[216:217] op_sel:[0,1] op_sel_hi:[1,1]
	v_pk_mul_f32 v[98:99], v[98:99], v[216:217] op_sel:[0,1] op_sel_hi:[1,1]
	v_pk_fma_f32 v[96:97], v[0:1], v[96:97], v[32:33]
	v_pk_fma_f32 v[98:99], v[2:3], v[98:99], v[34:35]
	v_pk_mul_f32 v[100:101], v[100:101], v[216:217] op_sel:[0,1] op_sel_hi:[1,1]
	v_pk_mul_f32 v[102:103], v[102:103], v[216:217] op_sel:[0,1] op_sel_hi:[1,1]
	v_pk_fma_f32 v[100:101], v[4:5], v[100:101], v[36:37]
	v_pk_fma_f32 v[102:103], v[6:7], v[102:103], v[38:39]
	global_store_dwordx4 v240, v[96:99], s[28:29]
	global_store_dwordx4 v240, v[100:103], s[28:29] offset:16
	v_pk_mul_f32 v[104:105], v[104:105], v[216:217] op_sel:[0,1] op_sel_hi:[1,1]
	v_pk_mul_f32 v[106:107], v[106:107], v[216:217] op_sel:[0,1] op_sel_hi:[1,1]
	v_pk_fma_f32 v[104:105], v[8:9], v[104:105], v[40:41]
	v_pk_fma_f32 v[106:107], v[10:11], v[106:107], v[42:43]
	v_pk_mul_f32 v[108:109], v[108:109], v[216:217] op_sel:[0,1] op_sel_hi:[1,1]
	v_pk_mul_f32 v[110:111], v[110:111], v[216:217] op_sel:[0,1] op_sel_hi:[1,1]
	v_pk_fma_f32 v[108:109], v[12:13], v[108:109], v[44:45]
	v_pk_fma_f32 v[110:111], v[14:15], v[110:111], v[46:47]
	global_store_dwordx4 v240, v[104:107], s[28:29] offset:2048
	global_store_dwordx4 v240, v[108:111], s[28:29] offset:2064
	v_pk_mul_f32 v[112:113], v[112:113], v[216:217] op_sel:[0,1] op_sel_hi:[1,1]
	v_pk_mul_f32 v[114:115], v[114:115], v[216:217] op_sel:[0,1] op_sel_hi:[1,1]
	v_pk_fma_f32 v[112:113], v[16:17], v[112:113], v[48:49]
	v_pk_fma_f32 v[114:115], v[18:19], v[114:115], v[50:51]
	v_pk_mul_f32 v[116:117], v[116:117], v[216:217] op_sel:[0,1] op_sel_hi:[1,1]
	v_pk_mul_f32 v[118:119], v[118:119], v[216:217] op_sel:[0,1] op_sel_hi:[1,1]
	v_pk_fma_f32 v[116:117], v[20:21], v[116:117], v[52:53]
	v_pk_fma_f32 v[118:119], v[22:23], v[118:119], v[54:55]
	global_store_dwordx4 v241, v[112:115], s[28:29]
	global_store_dwordx4 v241, v[116:119], s[28:29] offset:16
	v_pk_mul_f32 v[120:121], v[120:121], v[216:217] op_sel:[0,1] op_sel_hi:[1,1]
	v_pk_mul_f32 v[122:123], v[122:123], v[216:217] op_sel:[0,1] op_sel_hi:[1,1]
	v_pk_fma_f32 v[120:121], v[24:25], v[120:121], v[56:57]
	v_pk_fma_f32 v[122:123], v[26:27], v[122:123], v[58:59]
	v_pk_mul_f32 v[124:125], v[124:125], v[216:217] op_sel:[0,1] op_sel_hi:[1,1]
	v_pk_mul_f32 v[126:127], v[126:127], v[216:217] op_sel:[0,1] op_sel_hi:[1,1]
	v_pk_fma_f32 v[124:125], v[28:29], v[124:125], v[60:61]
	v_pk_fma_f32 v[126:127], v[30:31], v[126:127], v[62:63]
	global_store_dwordx4 v241, v[120:123], s[28:29] offset:2048
	global_store_dwordx4 v241, v[124:127], s[28:29] offset:2064
	s_add_u32 s20, s20, s21
	s_cmp_ge_u32 s20, 0x4000
	s_cbranch_scc1 .Lln2b_done
	s_mul_i32 s23, s21, 3
	s_add_u32 s23, s20, s23
	s_min_u32 s23, s23, 0x3fff
	s_lshl_b32 s23, s23, 13
	s_add_u32 s24, s12, s23
	s_addc_u32 s25, s13, 0
	global_load_dwordx4 v[96:99], v240, s[24:25]
	global_load_dwordx4 v[100:103], v240, s[24:25] offset:16
	global_load_dwordx4 v[104:107], v240, s[24:25] offset:2048
	global_load_dwordx4 v[108:111], v240, s[24:25] offset:2064
	global_load_dwordx4 v[112:115], v241, s[24:25]
	global_load_dwordx4 v[116:119], v241, s[24:25] offset:16
	global_load_dwordx4 v[120:123], v241, s[24:25] offset:2048
	global_load_dwordx4 v[124:127], v241, s[24:25] offset:2064
	s_waitcnt vmcnt(48)
; __device__ __forceinline__ void ln_phase(const float* in, float* outf, bf16_t* outb, const float* g, const float* b, int wv0) {
;     ...
;   for (int row = wv; row < NTOK; row += nwv) {
;     f32x4 v[8]; float s = 0.f;
; #pragma unroll
;     for (int i = 0; i < 8; ++i) v[i] = vn[i];
;     if (row + nwv < NTOK) { const f32x4* ir = (const f32x4*)(in + (size_t)(row + nwv) * DM);
; #pragma unroll
;       for (int i = 0; i < 8; ++i) vn[i] = ir[i * 64 + lane]; }
; #pragma unroll
;     for (int i = 0; i < 8; ++i) s += v[i][0] + v[i][1] + v[i][2] + v[i][3];
;     s = wave_sum(s); const float mu = s * (1.0f / 2048.0f);
;     float sq = 0.f;
; #pragma unroll
;     for (int i = 0; i < 8; ++i) { v[i] -= mu; sq += v[i][0] * v[i][0] + v[i][1] * v[i][1] + v[i][2] * v[i][2] + v[i][3] * v[i][3]; }
;     sq = wave_sum(sq); const float rstd = __builtin_amdgcn_rsqf(sq * (1.0f / 2048.0f) + EPS);
; #pragma unroll
;     for (int i = 0; i < 8; ++i) {
;       const f32x4 y = v[i] * rstd * gg[i] + bb[i];
;       ((f32x4*)(outf + (size_t)row * DM))[i * 64 + lane] = y;
;       if (outb) { u32x2 w; w.x = pk2(y[0], y[1]); w.y = pk2(y[2], y[3]); ((u32x2*)(outb + (size_t)row * DM))[i * 64 + lane] = w; } }
;   }
	v_pk_add_f32 v[236:237], v[128:129], v[130:131]
	v_pk_add_f32 v[236:237], v[236:237], v[132:133]
	v_pk_add_f32 v[236:237], v[236:237], v[134:135]
	v_pk_add_f32 v[236:237], v[236:237], v[136:137]
	v_pk_add_f32 v[236:237], v[236:237], v[138:139]
	v_pk_add_f32 v[236:237], v[236:237], v[140:141]
	v_pk_add_f32 v[236:237], v[236:237], v[142:143]
	v_pk_add_f32 v[236:237], v[236:237], v[144:145]
	v_pk_add_f32 v[236:237], v[236:237], v[146:147]
	v_pk_add_f32 v[236:237], v[236:237], v[148:149]
	v_pk_add_f32 v[236:237], v[236:237], v[150:151]
	v_pk_add_f32 v[236:237], v[236:237], v[152:153]
	v_pk_add_f32 v[236:237], v[236:237], v[154:155]
	v_pk_add_f32 v[236:237], v[236:237], v[156:157]
	v_pk_add_f32 v[236:237], v[236:237], v[158:159]
	v_add_f32_e32 v234, v236, v237
	s_nop 1
	v_add_f32_dpp v234, v234, v234 quad_perm:[1,0,3,2] row_mask:0xf bank_mask:0xf
	s_nop 1
	v_add_f32_dpp v234, v234, v234 quad_perm:[2,3,0,1] row_mask:0xf bank_mask:0xf
	s_nop 1
	v_add_f32_dpp v234, v234, v234 row_half_mirror row_mask:0xf bank_mask:0xf
	s_nop 1
	v_add_f32_dpp v234, v234, v234 row_mirror row_mask:0xf bank_mask:0xf
	s_nop 0
	v_readlane_b32 s26, v234, 0
	v_readlane_b32 s27, v234, 16
	v_readlane_b32 s28, v234, 32
	v_readlane_b32 s29, v234, 48
	v_mov_b32_e32 v234, s26
	v_add_f32_e32 v234, s27, v234
	v_add_f32_e32 v234, s28, v234
	v_add_f32_e32 v234, s29, v234
	v_mul_f32_e32 v216, 0xba000000, v234
	v_pk_add_f32 v[128:129], v[128:129], v[216:217] op_sel_hi:[1,0]
	v_pk_add_f32 v[130:131], v[130:131], v[216:217] op_sel_hi:[1,0]
	v_pk_add_f32 v[132:133], v[132:133], v[216:217] op_sel_hi:[1,0]
	v_pk_add_f32 v[134:135], v[134:135], v[216:217] op_sel_hi:[1,0]
	v_pk_add_f32 v[136:137], v[136:137], v[216:217] op_sel_hi:[1,0]
	v_pk_add_f32 v[138:139], v[138:139], v[216:217] op_sel_hi:[1,0]
	v_pk_add_f32 v[140:141], v[140:141], v[216:217] op_sel_hi:[1,0]
	v_pk_add_f32 v[142:143], v[142:143], v[216:217] op_sel_hi:[1,0]
	v_pk_add_f32 v[144:145], v[144:145], v[216:217] op_sel_hi:[1,0]
	v_pk_add_f32 v[146:147], v[146:147], v[216:217] op_sel_hi:[1,0]
	v_pk_add_f32 v[148:149], v[148:149], v[216:217] op_sel_hi:[1,0]
	v_pk_add_f32 v[150:151], v[150:151], v[216:217] op_sel_hi:[1,0]
	v_pk_add_f32 v[152:153], v[152:153], v[216:217] op_sel_hi:[1,0]
	v_pk_add_f32 v[154:155], v[154:155], v[216:217] op_sel_hi:[1,0]
	v_pk_add_f32 v[156:157], v[156:157], v[216:217] op_sel_hi:[1,0]
	v_pk_add_f32 v[158:159], v[158:159], v[216:217] op_sel_hi:[1,0]
	v_pk_mul_f32 v[236:237], v[128:129], v[128:129]
	v_pk_fma_f32 v[236:237], v[130:131], v[130:131], v[236:237]
	v_pk_fma_f32 v[236:237], v[132:133], v[132:133], v[236:237]
	v_pk_fma_f32 v[236:237], v[134:135], v[134:135], v[236:237]
	v_pk_fma_f32 v[236:237], v[136:137], v[136:137], v[236:237]
	v_pk_fma_f32 v[236:237], v[138:139], v[138:139], v[236:237]
	v_pk_fma_f32 v[236:237], v[140:141], v[140:141], v[236:237]
	v_pk_fma_f32 v[236:237], v[142:143], v[142:143], v[236:237]
	v_pk_fma_f32 v[236:237], v[144:145], v[144:145], v[236:237]
	v_pk_fma_f32 v[236:237], v[146:147], v[146:147], v[236:237]
	v_pk_fma_f32 v[236:237], v[148:149], v[148:149], v[236:237]
	v_pk_fma_f32 v[236:237], v[150:151], v[150:151], v[236:237]
	v_pk_fma_f32 v[236:237], v[152:153], v[152:153], v[236:237]
	v_pk_fma_f32 v[236:237], v[154:155], v[154:155], v[236:237]
	v_pk_fma_f32 v[236:237], v[156:157], v[156:157], v[236:237]
	v_pk_fma_f32 v[236:237], v[158:159], v[158:159], v[236:237]
	v_add_f32_e32 v235, v236, v237
	s_nop 1
	v_add_f32_dpp v235, v235, v235 quad_perm:[1,0,3,2] row_mask:0xf bank_mask:0xf
	s_nop 1
	v_add_f32_dpp v235, v235, v235 quad_perm:[2,3,0,1] row_mask:0xf bank_mask:0xf
	s_nop 1
	v_add_f32_dpp v235, v235, v235 row_half_mirror row_mask:0xf bank_mask:0xf
	s_nop 1
	v_add_f32_dpp v235, v235, v235 row_mirror row_mask:0xf bank_mask:0xf
	s_nop 0
	v_readlane_b32 s26, v235, 0
	v_readlane_b32 s27, v235, 16
	v_readlane_b32 s28, v235, 32
	v_readlane_b32 s29, v235, 48
	v_mov_b32_e32 v235, s26
	v_add_f32_e32 v235, s27, v235
	v_add_f32_e32 v235, s28, v235
	v_add_f32_e32 v235, s29, v235
	v_fmamk_f32 v235, v235, 0x3a000000, v246
	v_rsq_f32_e32 v217, v235
	s_lshl_b32 s23, s20, 13
	s_add_u32 s28, s18, s23
	s_addc_u32 s29, s19, 0
	v_pk_mul_f32 v[128:129], v[128:129], v[216:217] op_sel:[0,1] op_sel_hi:[1,1]
	v_pk_mul_f32 v[130:131], v[130:131], v[216:217] op_sel:[0,1] op_sel_hi:[1,1]
	v_pk_fma_f32 v[128:129], v[0:1], v[128:129], v[32:33]
	v_pk_fma_f32 v[130:131], v[2:3], v[130:131], v[34:35]
	v_pk_mul_f32 v[132:133], v[132:133], v[216:217] op_sel:[0,1] op_sel_hi:[1,1]
	v_pk_mul_f32 v[134:135], v[134:135], v[216:217] op_sel:[0,1] op_sel_hi:[1,1]
	v_pk_fma_f32 v[132:133], v[4:5], v[132:133], v[36:37]
	v_pk_fma_f32 v[134:135], v[6:7], v[134:135], v[38:39]
	global_store_dwordx4 v240, v[128:131], s[28:29]
	global_store_dwordx4 v240, v[132:135], s[28:29] offset:16
	v_pk_mul_f32 v[136:137], v[136:137], v[216:217] op_sel:[0,1] op_sel_hi:[1,1]
	v_pk_mul_f32 v[138:139], v[138:139], v[216:217] op_sel:[0,1] op_sel_hi:[1,1]
	v_pk_fma_f32 v[136:137], v[8:9], v[136:137], v[40:41]
	v_pk_fma_f32 v[138:139], v[10:11], v[138:139], v[42:43]
	v_pk_mul_f32 v[140:141], v[140:141], v[216:217] op_sel:[0,1] op_sel_hi:[1,1]
	v_pk_mul_f32 v[142:143], v[142:143], v[216:217] op_sel:[0,1] op_sel_hi:[1,1]
	v_pk_fma_f32 v[140:141], v[12:13], v[140:141], v[44:45]
	v_pk_fma_f32 v[142:143], v[14:15], v[142:143], v[46:47]
	global_store_dwordx4 v240, v[136:139], s[28:29] offset:2048
	global_store_dwordx4 v240, v[140:143], s[28:29] offset:2064
	v_pk_mul_f32 v[144:145], v[144:145], v[216:217] op_sel:[0,1] op_sel_hi:[1,1]
	v_pk_mul_f32 v[146:147], v[146:147], v[216:217] op_sel:[0,1] op_sel_hi:[1,1]
	v_pk_fma_f32 v[144:145], v[16:17], v[144:145], v[48:49]
	v_pk_fma_f32 v[146:147], v[18:19], v[146:147], v[50:51]
	v_pk_mul_f32 v[148:149], v[148:149], v[216:217] op_sel:[0,1] op_sel_hi:[1,1]
	v_pk_mul_f32 v[150:151], v[150:151], v[216:217] op_sel:[0,1] op_sel_hi:[1,1]
	v_pk_fma_f32 v[148:149], v[20:21], v[148:149], v[52:53]
	v_pk_fma_f32 v[150:151], v[22:23], v[150:151], v[54:55]
	global_store_dwordx4 v241, v[144:147], s[28:29]
	global_store_dwordx4 v241, v[148:151], s[28:29] offset:16
	v_pk_mul_f32 v[152:153], v[152:153], v[216:217] op_sel:[0,1] op_sel_hi:[1,1]
	v_pk_mul_f32 v[154:155], v[154:155], v[216:217] op_sel:[0,1] op_sel_hi:[1,1]
	v_pk_fma_f32 v[152:153], v[24:25], v[152:153], v[56:57]
	v_pk_fma_f32 v[154:155], v[26:27], v[154:155], v[58:59]
	v_pk_mul_f32 v[156:157], v[156:157], v[216:217] op_sel:[0,1] op_sel_hi:[1,1]
	v_pk_mul_f32 v[158:159], v[158:159], v[216:217] op_sel:[0,1] op_sel_hi:[1,1]
	v_pk_fma_f32 v[156:157], v[28:29], v[156:157], v[60:61]
	v_pk_fma_f32 v[158:159], v[30:31], v[158:159], v[62:63]
	global_store_dwordx4 v241, v[152:155], s[28:29] offset:2048
	global_store_dwordx4 v241, v[156:159], s[28:29] offset:2064
	s_add_u32 s20, s20, s21
	s_cmp_ge_u32 s20, 0x4000
	s_cbranch_scc1 .Lln2b_done
	s_branch .Lln2b_loop

; #define PH(b) for (int rep_ = 0, nrep_ = (int)(((PH_MASK >> (b)) & 1) + ((REP_MASK >> (b)) & 1)); rep_ < nrep_; ++rep_)
; __global__ void __launch_bounds__(512, 2) mega(Params p_unused) {
;     ...
;     PH(17) ln_phase(xa, (l == 1) ? p->out : xa, (l == 1) ? nullptr : xb, p->ln2_g + l * DM, p->ln2_b + l * DM, wv0);
.Lln2_end:
	v_mov_b32_e32 v97, 0
